# all s_setprio 1/0 flips around GEMM MFMA blocks removed (256 SALU instructions)
# speedup vs baseline: 1.0032x; 1.0032x over previous
.LBB0_443:
	s_andn2_b64 vcc, exec, s[58:59]
	s_waitcnt vmcnt(0)
	s_cbranch_vccnz .Lpz_zero_p1
	s_add_u32 s14, s4, 0x40080
	s_addc_u32 s15, s5, 0
	s_add_u32 s11, s70, 0x100
	s_addc_u32 s13, s71, 0
	s_mov_b32 s4, 0
	ds_read_b128 v[0:3], v190
	ds_read_b128 v[4:7], v190 offset:1024
	ds_read_b128 v[8:11], v190 offset:2048
	ds_read_b128 v[12:15], v190 offset:3072
	ds_read_b128 v[162:165], v191
	ds_read_b128 v[166:169], v191 offset:1024
	ds_read_b128 v[170:173], v191 offset:2048
	ds_read_b128 v[174:177], v191 offset:3072
	s_add_i32 s63, s4, 2
	s_add_u32 s5, s14, 0xfffc0080
	s_addc_u32 s65, s15, -1
	s_cmp_eq_u32 s96, s4
	s_cselect_b32 s4, s68, s11
	s_cselect_b32 s71, s67, s65
	s_cselect_b32 s70, s66, s5
	s_cselect_b32 s5, s69, s13
	v_lshl_add_u64 v[186:187], s[14:15], 0, v[156:157]
	s_add_i32 m0, s90, 0xc000
	ds_read_b128 v[178:181], v192
	ds_read_b128 v[182:185], v192 offset:1024
	ds_read_b128 v[196:199], v192 offset:2048
	ds_read_b128 v[200:203], v192 offset:3072
	ds_read_b128 v[204:207], v192 offset:4096
	ds_read_b128 v[208:211], v192 offset:5120
	ds_read_b128 v[212:215], v192 offset:6144
	ds_read_b128 v[216:219], v192 offset:7168
	global_load_lds_dwordx4 v[186:187], off
	v_lshl_add_u64 v[186:187], s[14:15], 0, v[158:159]
	s_add_i32 m0, s90, 0xe000
	s_nop 0
	global_load_lds_dwordx4 v[186:187], off
	s_waitcnt vmcnt(8)
	s_waitcnt lgkmcnt(0)
	s_barrier
	s_waitcnt lgkmcnt(0)
	v_mfma_f32_16x16x32_bf16 v[16:19], v[0:3], v[178:181], 0
	v_mfma_f32_16x16x32_bf16 v[20:23], v[8:11], v[178:181], 0
	v_mfma_f32_16x16x32_bf16 v[128:131], v[0:3], v[196:199], 0
	v_mfma_f32_16x16x32_bf16 v[132:135], v[8:11], v[196:199], 0
	v_mfma_f32_16x16x32_bf16 v[112:115], v[0:3], v[204:207], 0
	v_mfma_f32_16x16x32_bf16 v[116:119], v[8:11], v[204:207], 0
	v_mfma_f32_16x16x32_bf16 v[96:99], v[0:3], v[212:215], 0
	v_mfma_f32_16x16x32_bf16 v[100:103], v[8:11], v[212:215], 0
	v_mfma_f32_16x16x32_bf16 v[16:19], v[4:7], v[182:185], v[16:19]
	v_mfma_f32_16x16x32_bf16 v[20:23], v[12:15], v[182:185], v[20:23]
	v_mfma_f32_16x16x32_bf16 v[128:131], v[4:7], v[200:203], v[128:131]
	v_mfma_f32_16x16x32_bf16 v[132:135], v[12:15], v[200:203], v[132:135]
	v_mfma_f32_16x16x32_bf16 v[112:115], v[4:7], v[208:211], v[112:115]
	v_mfma_f32_16x16x32_bf16 v[116:119], v[12:15], v[208:211], v[116:119]
	v_mfma_f32_16x16x32_bf16 v[96:99], v[4:7], v[216:219], v[96:99]
	v_mfma_f32_16x16x32_bf16 v[100:103], v[12:15], v[216:219], v[100:103]
	v_mfma_f32_16x16x32_bf16 v[24:27], v[162:165], v[178:181], 0
	v_mfma_f32_16x16x32_bf16 v[28:31], v[170:173], v[178:181], 0
	v_mfma_f32_16x16x32_bf16 v[136:139], v[162:165], v[196:199], 0
	v_mfma_f32_16x16x32_bf16 v[140:143], v[170:173], v[196:199], 0
	v_mfma_f32_16x16x32_bf16 v[120:123], v[162:165], v[204:207], 0
	v_mfma_f32_16x16x32_bf16 v[124:127], v[170:173], v[204:207], 0
	v_mfma_f32_16x16x32_bf16 v[104:107], v[162:165], v[212:215], 0
	v_mfma_f32_16x16x32_bf16 v[108:111], v[170:173], v[212:215], 0
	v_mfma_f32_16x16x32_bf16 v[24:27], v[166:169], v[182:185], v[24:27]
	v_mfma_f32_16x16x32_bf16 v[28:31], v[174:177], v[182:185], v[28:31]
	v_mfma_f32_16x16x32_bf16 v[136:139], v[166:169], v[200:203], v[136:139]
	v_mfma_f32_16x16x32_bf16 v[140:143], v[174:177], v[200:203], v[140:143]
	v_mfma_f32_16x16x32_bf16 v[120:123], v[166:169], v[208:211], v[120:123]
	v_mfma_f32_16x16x32_bf16 v[124:127], v[174:177], v[208:211], v[124:127]
	v_mfma_f32_16x16x32_bf16 v[104:107], v[166:169], v[216:219], v[104:107]
	v_mfma_f32_16x16x32_bf16 v[108:111], v[174:177], v[216:219], v[108:111]
	s_barrier
	s_add_i32 s65, s38, s89
	v_lshl_add_u64 v[186:187], s[4:5], 0, v[144:145]
	s_mov_b32 m0, s65
	ds_read_b128 v[178:181], v192 offset:16384
	ds_read_b128 v[182:185], v192 offset:17408
	ds_read_b128 v[196:199], v192 offset:18432
	ds_read_b128 v[200:203], v192 offset:19456
	ds_read_b128 v[204:207], v192 offset:20480
	ds_read_b128 v[208:211], v192 offset:21504
	ds_read_b128 v[212:215], v192 offset:22528
	ds_read_b128 v[216:219], v192 offset:23552
	global_load_lds_dwordx4 v[186:187], off
	s_add_i32 m0, s65, 0x2000
	s_add_u32 s72, s4, 0x40000
	v_lshl_add_u64 v[220:221], s[4:5], 0, v[146:147]
	s_addc_u32 s73, s5, 0
	s_add_i32 s65, s39, s89
	global_load_lds_dwordx4 v[220:221], off
	v_lshl_add_u64 v[222:223], s[72:73], 0, v[144:145]
	s_mov_b32 m0, s65
	v_lshl_add_u64 v[224:225], s[70:71], 0, v[146:147]
	global_load_lds_dwordx4 v[222:223], off
	v_lshl_add_u64 v[222:223], s[72:73], 0, v[146:147]
	s_add_i32 m0, s65, 0x2000
	s_nop 0
	global_load_lds_dwordx4 v[222:223], off
	v_lshl_add_u64 v[222:223], s[70:71], 0, v[144:145]
	s_mov_b32 m0, s90
	s_nop 0
	global_load_lds_dwordx4 v[222:223], off
	s_mov_b32 m0, s91
	s_nop 0
	global_load_lds_dwordx4 v[224:225], off
	s_waitcnt vmcnt(8)
	s_waitcnt lgkmcnt(0)
	s_barrier
	s_waitcnt lgkmcnt(0)
	v_mfma_f32_16x16x32_bf16 v[80:83], v[0:3], v[178:181], 0
	v_mfma_f32_16x16x32_bf16 v[84:87], v[8:11], v[178:181], 0
	v_mfma_f32_16x16x32_bf16 v[64:67], v[0:3], v[196:199], 0
	v_mfma_f32_16x16x32_bf16 v[68:71], v[8:11], v[196:199], 0
	v_mfma_f32_16x16x32_bf16 v[48:51], v[0:3], v[204:207], 0
	v_mfma_f32_16x16x32_bf16 v[52:55], v[8:11], v[204:207], 0
	v_mfma_f32_16x16x32_bf16 v[0:3], v[0:3], v[212:215], 0
	v_mfma_f32_16x16x32_bf16 v[80:83], v[4:7], v[182:185], v[80:83]
	v_mfma_f32_16x16x32_bf16 v[84:87], v[12:15], v[182:185], v[84:87]
	v_mfma_f32_16x16x32_bf16 v[64:67], v[4:7], v[200:203], v[64:67]
	v_mfma_f32_16x16x32_bf16 v[68:71], v[12:15], v[200:203], v[68:71]
	v_mfma_f32_16x16x32_bf16 v[48:51], v[4:7], v[208:211], v[48:51]
	v_mfma_f32_16x16x32_bf16 v[52:55], v[12:15], v[208:211], v[52:55]
	v_mfma_f32_16x16x32_bf16 v[0:3], v[4:7], v[216:219], v[0:3]
	v_mfma_f32_16x16x32_bf16 v[4:7], v[8:11], v[212:215], 0
	v_mfma_f32_16x16x32_bf16 v[4:7], v[12:15], v[216:219], v[4:7]
	v_mfma_f32_16x16x32_bf16 v[36:39], v[162:165], v[196:199], 0
	v_mfma_f32_16x16x32_bf16 v[72:75], v[166:169], v[200:203], v[36:39]
	v_mfma_f32_16x16x32_bf16 v[36:39], v[170:173], v[196:199], 0
	v_mfma_f32_16x16x32_bf16 v[76:79], v[174:177], v[200:203], v[36:39]
	v_mfma_f32_16x16x32_bf16 v[36:39], v[162:165], v[204:207], 0
	v_mfma_f32_16x16x32_bf16 v[56:59], v[166:169], v[208:211], v[36:39]
	v_mfma_f32_16x16x32_bf16 v[36:39], v[170:173], v[204:207], 0
	v_mfma_f32_16x16x32_bf16 v[60:63], v[174:177], v[208:211], v[36:39]
	v_mfma_f32_16x16x32_bf16 v[36:39], v[162:165], v[212:215], 0
	v_mfma_f32_16x16x32_bf16 v[32:35], v[170:173], v[212:215], 0
	v_mfma_f32_16x16x32_bf16 v[8:11], v[162:165], v[178:181], 0
	v_mfma_f32_16x16x32_bf16 v[12:15], v[170:173], v[178:181], 0
	v_mfma_f32_16x16x32_bf16 v[44:47], v[166:169], v[216:219], v[36:39]
	v_mfma_f32_16x16x32_bf16 v[32:35], v[174:177], v[216:219], v[32:35]
	v_mfma_f32_16x16x32_bf16 v[8:11], v[166:169], v[182:185], v[8:11]
	v_mfma_f32_16x16x32_bf16 v[12:15], v[174:177], v[182:185], v[12:15]
	s_barrier
	s_add_i32 s65, 0, 0x18000
	s_add_i32 s72, 0, 0x1c000
	v_add_u32_e32 v92, s65, v189
	v_add_u32_e32 v150, s72, v189
	ds_read_b128 v[36:39], v92
	ds_read_b128 v[40:43], v92 offset:1024
	ds_read_b128 v[88:91], v92 offset:2048
	ds_read_b128 v[92:95], v92 offset:3072
	ds_read_b128 v[162:165], v150
	ds_read_b128 v[166:169], v150 offset:1024
	ds_read_b128 v[170:173], v150 offset:2048
	ds_read_b128 v[174:177], v150 offset:3072
	s_add_u32 s70, s70, 0x40000
	s_addc_u32 s71, s71, 0
	s_mov_b32 m0, s92
	v_lshl_add_u64 v[226:227], s[70:71], 0, v[144:145]
	ds_read_b128 v[178:181], v192 offset:32768
	ds_read_b128 v[182:185], v192 offset:33792
	ds_read_b128 v[196:199], v192 offset:34816
	ds_read_b128 v[200:203], v192 offset:35840
	ds_read_b128 v[204:207], v192 offset:36864
	ds_read_b128 v[208:211], v192 offset:37888
	ds_read_b128 v[212:215], v192 offset:38912
	ds_read_b128 v[216:219], v192 offset:39936
	global_load_lds_dwordx4 v[226:227], off
	v_lshl_add_u64 v[226:227], s[70:71], 0, v[146:147]
	s_mov_b32 m0, s93
	s_nop 0
	global_load_lds_dwordx4 v[226:227], off
	s_waitcnt vmcnt(8)
	s_waitcnt lgkmcnt(0)
	s_barrier
	s_waitcnt lgkmcnt(0)
	v_mfma_f32_16x16x32_bf16 v[16:19], v[36:39], v[178:181], v[16:19]
	v_mfma_f32_16x16x32_bf16 v[20:23], v[88:91], v[178:181], v[20:23]
	v_mfma_f32_16x16x32_bf16 v[128:131], v[36:39], v[196:199], v[128:131]
	v_mfma_f32_16x16x32_bf16 v[132:135], v[88:91], v[196:199], v[132:135]
	v_mfma_f32_16x16x32_bf16 v[112:115], v[36:39], v[204:207], v[112:115]
	v_mfma_f32_16x16x32_bf16 v[116:119], v[88:91], v[204:207], v[116:119]
	v_mfma_f32_16x16x32_bf16 v[96:99], v[36:39], v[212:215], v[96:99]
	v_mfma_f32_16x16x32_bf16 v[100:103], v[88:91], v[212:215], v[100:103]
	v_mfma_f32_16x16x32_bf16 v[16:19], v[40:43], v[182:185], v[16:19]
	v_mfma_f32_16x16x32_bf16 v[20:23], v[92:95], v[182:185], v[20:23]
	v_mfma_f32_16x16x32_bf16 v[128:131], v[40:43], v[200:203], v[128:131]
	v_mfma_f32_16x16x32_bf16 v[132:135], v[92:95], v[200:203], v[132:135]
	v_mfma_f32_16x16x32_bf16 v[112:115], v[40:43], v[208:211], v[112:115]
	v_mfma_f32_16x16x32_bf16 v[116:119], v[92:95], v[208:211], v[116:119]
	v_mfma_f32_16x16x32_bf16 v[96:99], v[40:43], v[216:219], v[96:99]
	v_mfma_f32_16x16x32_bf16 v[100:103], v[92:95], v[216:219], v[100:103]
	v_mfma_f32_16x16x32_bf16 v[24:27], v[162:165], v[178:181], v[24:27]
	v_mfma_f32_16x16x32_bf16 v[28:31], v[170:173], v[178:181], v[28:31]
	v_mfma_f32_16x16x32_bf16 v[136:139], v[162:165], v[196:199], v[136:139]
	v_mfma_f32_16x16x32_bf16 v[140:143], v[170:173], v[196:199], v[140:143]
	v_mfma_f32_16x16x32_bf16 v[120:123], v[162:165], v[204:207], v[120:123]
	v_mfma_f32_16x16x32_bf16 v[124:127], v[170:173], v[204:207], v[124:127]
	v_mfma_f32_16x16x32_bf16 v[104:107], v[162:165], v[212:215], v[104:107]
	v_mfma_f32_16x16x32_bf16 v[108:111], v[170:173], v[212:215], v[108:111]
	v_mfma_f32_16x16x32_bf16 v[24:27], v[166:169], v[182:185], v[24:27]
	v_mfma_f32_16x16x32_bf16 v[28:31], v[174:177], v[182:185], v[28:31]
	v_mfma_f32_16x16x32_bf16 v[136:139], v[166:169], v[200:203], v[136:139]
	v_mfma_f32_16x16x32_bf16 v[140:143], v[174:177], v[200:203], v[140:143]
	v_mfma_f32_16x16x32_bf16 v[120:123], v[166:169], v[208:211], v[120:123]
	v_mfma_f32_16x16x32_bf16 v[124:127], v[174:177], v[208:211], v[124:127]
	v_mfma_f32_16x16x32_bf16 v[104:107], v[166:169], v[216:219], v[104:107]
	v_mfma_f32_16x16x32_bf16 v[108:111], v[174:177], v[216:219], v[108:111]
	s_barrier
	s_add_i32 s65, s65, s89
	v_lshl_add_u64 v[186:187], v[186:187], 0, s[56:57]
	s_mov_b32 m0, s65
	ds_read_b128 v[178:181], v192 offset:49152
	ds_read_b128 v[182:185], v192 offset:50176
	ds_read_b128 v[196:199], v192 offset:51200
	ds_read_b128 v[200:203], v192 offset:52224
	ds_read_b128 v[204:207], v192 offset:53248
	ds_read_b128 v[208:211], v192 offset:54272
	ds_read_b128 v[212:215], v192 offset:55296
	ds_read_b128 v[216:219], v192 offset:56320
	global_load_lds_dwordx4 v[186:187], off
	s_add_i32 m0, s65, 0x2000
	s_add_u32 s4, s4, 0x40080
	v_lshl_add_u64 v[186:187], v[220:221], 0, s[56:57]
	s_addc_u32 s5, s5, 0
	s_add_i32 s65, s72, s89
	global_load_lds_dwordx4 v[186:187], off
	v_lshl_add_u64 v[186:187], s[4:5], 0, v[144:145]
	s_mov_b32 m0, s65
	s_nop 0
	global_load_lds_dwordx4 v[186:187], off
	v_lshl_add_u64 v[186:187], s[4:5], 0, v[146:147]
	s_add_i32 m0, s65, 0x2000
	s_nop 0
	global_load_lds_dwordx4 v[186:187], off
	v_lshl_add_u64 v[186:187], v[222:223], 0, s[56:57]
	s_mov_b32 m0, s81
	s_nop 0
	global_load_lds_dwordx4 v[186:187], off
	v_lshl_add_u64 v[186:187], v[224:225], 0, s[56:57]
	s_mov_b32 m0, s80
	s_nop 0
	global_load_lds_dwordx4 v[186:187], off
	s_waitcnt vmcnt(8)
	s_waitcnt lgkmcnt(0)
	s_barrier
	s_waitcnt lgkmcnt(0)
	v_mfma_f32_16x16x32_bf16 v[0:3], v[36:39], v[212:215], v[0:3]
	v_mfma_f32_16x16x32_bf16 v[80:83], v[36:39], v[178:181], v[80:83]
	v_mfma_f32_16x16x32_bf16 v[84:87], v[88:91], v[178:181], v[84:87]
	v_mfma_f32_16x16x32_bf16 v[64:67], v[36:39], v[196:199], v[64:67]
	v_mfma_f32_16x16x32_bf16 v[68:71], v[88:91], v[196:199], v[68:71]
	v_mfma_f32_16x16x32_bf16 v[48:51], v[36:39], v[204:207], v[48:51]
	v_mfma_f32_16x16x32_bf16 v[52:55], v[88:91], v[204:207], v[52:55]
	v_mfma_f32_16x16x32_bf16 v[36:39], v[40:43], v[216:219], v[0:3]
	v_mfma_f32_16x16x32_bf16 v[0:3], v[88:91], v[212:215], v[4:7]
	v_mfma_f32_16x16x32_bf16 v[80:83], v[40:43], v[182:185], v[80:83]
	v_mfma_f32_16x16x32_bf16 v[84:87], v[92:95], v[182:185], v[84:87]
	v_mfma_f32_16x16x32_bf16 v[64:67], v[40:43], v[200:203], v[64:67]
	v_mfma_f32_16x16x32_bf16 v[68:71], v[92:95], v[200:203], v[68:71]
	v_mfma_f32_16x16x32_bf16 v[48:51], v[40:43], v[208:211], v[48:51]
	v_mfma_f32_16x16x32_bf16 v[52:55], v[92:95], v[208:211], v[52:55]
	v_mfma_f32_16x16x32_bf16 v[40:43], v[92:95], v[216:219], v[0:3]
	v_mfma_f32_16x16x32_bf16 v[0:3], v[162:165], v[178:181], v[8:11]
	v_mfma_f32_16x16x32_bf16 v[88:91], v[166:169], v[182:185], v[0:3]
	v_mfma_f32_16x16x32_bf16 v[0:3], v[170:173], v[178:181], v[12:15]
	v_mfma_f32_16x16x32_bf16 v[92:95], v[174:177], v[182:185], v[0:3]
	v_mfma_f32_16x16x32_bf16 v[0:3], v[162:165], v[196:199], v[72:75]
	v_mfma_f32_16x16x32_bf16 v[72:75], v[166:169], v[200:203], v[0:3]
	v_mfma_f32_16x16x32_bf16 v[0:3], v[170:173], v[196:199], v[76:79]
	v_mfma_f32_16x16x32_bf16 v[76:79], v[174:177], v[200:203], v[0:3]
	v_mfma_f32_16x16x32_bf16 v[0:3], v[162:165], v[204:207], v[56:59]
	v_mfma_f32_16x16x32_bf16 v[56:59], v[166:169], v[208:211], v[0:3]
	v_mfma_f32_16x16x32_bf16 v[0:3], v[170:173], v[204:207], v[60:63]
	v_mfma_f32_16x16x32_bf16 v[60:63], v[174:177], v[208:211], v[0:3]
	v_mfma_f32_16x16x32_bf16 v[0:3], v[162:165], v[212:215], v[44:47]
	v_mfma_f32_16x16x32_bf16 v[44:47], v[166:169], v[216:219], v[0:3]
	v_mfma_f32_16x16x32_bf16 v[0:3], v[170:173], v[212:215], v[32:35]
	v_mfma_f32_16x16x32_bf16 v[32:35], v[174:177], v[216:219], v[0:3]
	s_barrier
	s_add_u32 s14, s14, 0x100
	s_addc_u32 s15, s15, 0
	s_add_u32 s11, s11, 0x100
	s_addc_u32 s13, s13, 0
	s_cmp_ge_i32 s63, s36
	s_mov_b32 s4, s63
	s_cbranch_scc0 .LBB0_445
	s_branch .LBB0_446

.LBB0_445:
	ds_read_b128 v[0:3], v190
	ds_read_b128 v[4:7], v190 offset:1024
	ds_read_b128 v[8:11], v190 offset:2048
	ds_read_b128 v[12:15], v190 offset:3072
	ds_read_b128 v[162:165], v191
	ds_read_b128 v[166:169], v191 offset:1024
	ds_read_b128 v[170:173], v191 offset:2048
	ds_read_b128 v[174:177], v191 offset:3072
	s_add_i32 s63, s4, 2
	s_add_u32 s5, s14, 0xfffc0080
	s_addc_u32 s65, s15, -1
	s_cmp_eq_u32 s96, s4
	s_cselect_b32 s4, s68, s11
	s_cselect_b32 s71, s67, s65
	s_cselect_b32 s70, s66, s5
	s_cselect_b32 s5, s69, s13
	v_lshl_add_u64 v[186:187], s[14:15], 0, v[156:157]
	s_add_i32 m0, s90, 0xc000
	ds_read_b128 v[178:181], v192
	ds_read_b128 v[182:185], v192 offset:1024
	ds_read_b128 v[196:199], v192 offset:2048
	ds_read_b128 v[200:203], v192 offset:3072
	ds_read_b128 v[204:207], v192 offset:4096
	ds_read_b128 v[208:211], v192 offset:5120
	ds_read_b128 v[212:215], v192 offset:6144
	ds_read_b128 v[216:219], v192 offset:7168
	global_load_lds_dwordx4 v[186:187], off
	v_lshl_add_u64 v[186:187], s[14:15], 0, v[158:159]
	s_add_i32 m0, s90, 0xe000
	s_nop 0
	global_load_lds_dwordx4 v[186:187], off
	s_waitcnt vmcnt(8)
	s_waitcnt lgkmcnt(0)
	s_barrier
	s_waitcnt lgkmcnt(0)
	v_mfma_f32_16x16x32_bf16 v[16:19], v[0:3], v[178:181], v[16:19]
	v_mfma_f32_16x16x32_bf16 v[20:23], v[8:11], v[178:181], v[20:23]
	v_mfma_f32_16x16x32_bf16 v[128:131], v[0:3], v[196:199], v[128:131]
	v_mfma_f32_16x16x32_bf16 v[132:135], v[8:11], v[196:199], v[132:135]
	v_mfma_f32_16x16x32_bf16 v[112:115], v[0:3], v[204:207], v[112:115]
	v_mfma_f32_16x16x32_bf16 v[116:119], v[8:11], v[204:207], v[116:119]
	v_mfma_f32_16x16x32_bf16 v[96:99], v[0:3], v[212:215], v[96:99]
	v_mfma_f32_16x16x32_bf16 v[100:103], v[8:11], v[212:215], v[100:103]
	v_mfma_f32_16x16x32_bf16 v[16:19], v[4:7], v[182:185], v[16:19]
	v_mfma_f32_16x16x32_bf16 v[20:23], v[12:15], v[182:185], v[20:23]
	v_mfma_f32_16x16x32_bf16 v[128:131], v[4:7], v[200:203], v[128:131]
	v_mfma_f32_16x16x32_bf16 v[132:135], v[12:15], v[200:203], v[132:135]
	v_mfma_f32_16x16x32_bf16 v[112:115], v[4:7], v[208:211], v[112:115]
	v_mfma_f32_16x16x32_bf16 v[116:119], v[12:15], v[208:211], v[116:119]
	v_mfma_f32_16x16x32_bf16 v[96:99], v[4:7], v[216:219], v[96:99]
	v_mfma_f32_16x16x32_bf16 v[100:103], v[12:15], v[216:219], v[100:103]
	v_mfma_f32_16x16x32_bf16 v[24:27], v[162:165], v[178:181], v[24:27]
	v_mfma_f32_16x16x32_bf16 v[28:31], v[170:173], v[178:181], v[28:31]
	v_mfma_f32_16x16x32_bf16 v[136:139], v[162:165], v[196:199], v[136:139]
	v_mfma_f32_16x16x32_bf16 v[140:143], v[170:173], v[196:199], v[140:143]
	v_mfma_f32_16x16x32_bf16 v[120:123], v[162:165], v[204:207], v[120:123]
	v_mfma_f32_16x16x32_bf16 v[124:127], v[170:173], v[204:207], v[124:127]
	v_mfma_f32_16x16x32_bf16 v[104:107], v[162:165], v[212:215], v[104:107]
	v_mfma_f32_16x16x32_bf16 v[108:111], v[170:173], v[212:215], v[108:111]
	v_mfma_f32_16x16x32_bf16 v[24:27], v[166:169], v[182:185], v[24:27]
	v_mfma_f32_16x16x32_bf16 v[28:31], v[174:177], v[182:185], v[28:31]
	v_mfma_f32_16x16x32_bf16 v[136:139], v[166:169], v[200:203], v[136:139]
	v_mfma_f32_16x16x32_bf16 v[140:143], v[174:177], v[200:203], v[140:143]
	v_mfma_f32_16x16x32_bf16 v[120:123], v[166:169], v[208:211], v[120:123]
	v_mfma_f32_16x16x32_bf16 v[124:127], v[174:177], v[208:211], v[124:127]
	v_mfma_f32_16x16x32_bf16 v[104:107], v[166:169], v[216:219], v[104:107]
	v_mfma_f32_16x16x32_bf16 v[108:111], v[174:177], v[216:219], v[108:111]
	s_barrier
	s_add_i32 s65, s38, s89
	v_lshl_add_u64 v[186:187], s[4:5], 0, v[144:145]
	s_mov_b32 m0, s65
	ds_read_b128 v[178:181], v192 offset:16384
	ds_read_b128 v[182:185], v192 offset:17408
	ds_read_b128 v[196:199], v192 offset:18432
	ds_read_b128 v[200:203], v192 offset:19456
	ds_read_b128 v[204:207], v192 offset:20480
	ds_read_b128 v[208:211], v192 offset:21504
	ds_read_b128 v[212:215], v192 offset:22528
	ds_read_b128 v[216:219], v192 offset:23552
	global_load_lds_dwordx4 v[186:187], off
	s_add_i32 m0, s65, 0x2000
	s_add_u32 s72, s4, 0x40000
	v_lshl_add_u64 v[220:221], s[4:5], 0, v[146:147]
	s_addc_u32 s73, s5, 0
	s_add_i32 s65, s39, s89
	global_load_lds_dwordx4 v[220:221], off
	v_lshl_add_u64 v[222:223], s[72:73], 0, v[144:145]
	s_mov_b32 m0, s65
	v_lshl_add_u64 v[224:225], s[70:71], 0, v[146:147]
	global_load_lds_dwordx4 v[222:223], off
	v_lshl_add_u64 v[222:223], s[72:73], 0, v[146:147]
	s_add_i32 m0, s65, 0x2000
	s_nop 0
	global_load_lds_dwordx4 v[222:223], off
	v_lshl_add_u64 v[222:223], s[70:71], 0, v[144:145]
	s_mov_b32 m0, s90
	s_nop 0
	global_load_lds_dwordx4 v[222:223], off
	s_mov_b32 m0, s91
	s_nop 0
	global_load_lds_dwordx4 v[224:225], off
	s_waitcnt vmcnt(8)
	s_waitcnt lgkmcnt(0)
	s_barrier
	s_waitcnt lgkmcnt(0)
	v_mfma_f32_16x16x32_bf16 v[80:83], v[0:3], v[178:181], v[80:83]
	v_mfma_f32_16x16x32_bf16 v[84:87], v[8:11], v[178:181], v[84:87]
	v_mfma_f32_16x16x32_bf16 v[64:67], v[0:3], v[196:199], v[64:67]
	v_mfma_f32_16x16x32_bf16 v[68:71], v[8:11], v[196:199], v[68:71]
	v_mfma_f32_16x16x32_bf16 v[48:51], v[0:3], v[204:207], v[48:51]
	v_mfma_f32_16x16x32_bf16 v[52:55], v[8:11], v[204:207], v[52:55]
	v_mfma_f32_16x16x32_bf16 v[0:3], v[0:3], v[212:215], v[36:39]
	v_mfma_f32_16x16x32_bf16 v[80:83], v[4:7], v[182:185], v[80:83]
	v_mfma_f32_16x16x32_bf16 v[84:87], v[12:15], v[182:185], v[84:87]
	v_mfma_f32_16x16x32_bf16 v[64:67], v[4:7], v[200:203], v[64:67]
	v_mfma_f32_16x16x32_bf16 v[68:71], v[12:15], v[200:203], v[68:71]
	v_mfma_f32_16x16x32_bf16 v[48:51], v[4:7], v[208:211], v[48:51]
	v_mfma_f32_16x16x32_bf16 v[52:55], v[12:15], v[208:211], v[52:55]
	v_mfma_f32_16x16x32_bf16 v[0:3], v[4:7], v[216:219], v[0:3]
	v_mfma_f32_16x16x32_bf16 v[4:7], v[8:11], v[212:215], v[40:43]
	v_mfma_f32_16x16x32_bf16 v[4:7], v[12:15], v[216:219], v[4:7]
	v_mfma_f32_16x16x32_bf16 v[36:39], v[162:165], v[196:199], v[72:75]
	v_mfma_f32_16x16x32_bf16 v[72:75], v[166:169], v[200:203], v[36:39]
	v_mfma_f32_16x16x32_bf16 v[36:39], v[170:173], v[196:199], v[76:79]
	v_mfma_f32_16x16x32_bf16 v[76:79], v[174:177], v[200:203], v[36:39]
	v_mfma_f32_16x16x32_bf16 v[36:39], v[162:165], v[204:207], v[56:59]
	v_mfma_f32_16x16x32_bf16 v[56:59], v[166:169], v[208:211], v[36:39]
	v_mfma_f32_16x16x32_bf16 v[36:39], v[170:173], v[204:207], v[60:63]
	v_mfma_f32_16x16x32_bf16 v[60:63], v[174:177], v[208:211], v[36:39]
	v_mfma_f32_16x16x32_bf16 v[36:39], v[162:165], v[212:215], v[44:47]
	v_mfma_f32_16x16x32_bf16 v[32:35], v[170:173], v[212:215], v[32:35]
	v_mfma_f32_16x16x32_bf16 v[8:11], v[162:165], v[178:181], v[88:91]
	v_mfma_f32_16x16x32_bf16 v[12:15], v[170:173], v[178:181], v[92:95]
	v_mfma_f32_16x16x32_bf16 v[44:47], v[166:169], v[216:219], v[36:39]
	v_mfma_f32_16x16x32_bf16 v[32:35], v[174:177], v[216:219], v[32:35]
	v_mfma_f32_16x16x32_bf16 v[8:11], v[166:169], v[182:185], v[8:11]
	v_mfma_f32_16x16x32_bf16 v[12:15], v[174:177], v[182:185], v[12:15]
	s_barrier
	s_add_i32 s65, 0, 0x18000
	s_add_i32 s72, 0, 0x1c000
	v_add_u32_e32 v92, s65, v189
	v_add_u32_e32 v150, s72, v189
	ds_read_b128 v[36:39], v92
	ds_read_b128 v[40:43], v92 offset:1024
	ds_read_b128 v[88:91], v92 offset:2048
	ds_read_b128 v[92:95], v92 offset:3072
	ds_read_b128 v[162:165], v150
	ds_read_b128 v[166:169], v150 offset:1024
	ds_read_b128 v[170:173], v150 offset:2048
	ds_read_b128 v[174:177], v150 offset:3072
	s_add_u32 s70, s70, 0x40000
	s_addc_u32 s71, s71, 0
	s_mov_b32 m0, s92
	v_lshl_add_u64 v[226:227], s[70:71], 0, v[144:145]
	ds_read_b128 v[178:181], v192 offset:32768
	ds_read_b128 v[182:185], v192 offset:33792
	ds_read_b128 v[196:199], v192 offset:34816
	ds_read_b128 v[200:203], v192 offset:35840
	ds_read_b128 v[204:207], v192 offset:36864
	ds_read_b128 v[208:211], v192 offset:37888
	ds_read_b128 v[212:215], v192 offset:38912
	ds_read_b128 v[216:219], v192 offset:39936
	global_load_lds_dwordx4 v[226:227], off
	v_lshl_add_u64 v[226:227], s[70:71], 0, v[146:147]
	s_mov_b32 m0, s93
	s_nop 0
	global_load_lds_dwordx4 v[226:227], off
	s_waitcnt vmcnt(8)
	s_waitcnt lgkmcnt(0)
	s_barrier
	s_waitcnt lgkmcnt(0)
	v_mfma_f32_16x16x32_bf16 v[16:19], v[36:39], v[178:181], v[16:19]
	v_mfma_f32_16x16x32_bf16 v[20:23], v[88:91], v[178:181], v[20:23]
	v_mfma_f32_16x16x32_bf16 v[128:131], v[36:39], v[196:199], v[128:131]
	v_mfma_f32_16x16x32_bf16 v[132:135], v[88:91], v[196:199], v[132:135]
	v_mfma_f32_16x16x32_bf16 v[112:115], v[36:39], v[204:207], v[112:115]
	v_mfma_f32_16x16x32_bf16 v[116:119], v[88:91], v[204:207], v[116:119]
	v_mfma_f32_16x16x32_bf16 v[96:99], v[36:39], v[212:215], v[96:99]
	v_mfma_f32_16x16x32_bf16 v[100:103], v[88:91], v[212:215], v[100:103]
	v_mfma_f32_16x16x32_bf16 v[16:19], v[40:43], v[182:185], v[16:19]
	v_mfma_f32_16x16x32_bf16 v[20:23], v[92:95], v[182:185], v[20:23]
	v_mfma_f32_16x16x32_bf16 v[128:131], v[40:43], v[200:203], v[128:131]
	v_mfma_f32_16x16x32_bf16 v[132:135], v[92:95], v[200:203], v[132:135]
	v_mfma_f32_16x16x32_bf16 v[112:115], v[40:43], v[208:211], v[112:115]
	v_mfma_f32_16x16x32_bf16 v[116:119], v[92:95], v[208:211], v[116:119]
	v_mfma_f32_16x16x32_bf16 v[96:99], v[40:43], v[216:219], v[96:99]
	v_mfma_f32_16x16x32_bf16 v[100:103], v[92:95], v[216:219], v[100:103]
	v_mfma_f32_16x16x32_bf16 v[24:27], v[162:165], v[178:181], v[24:27]
	v_mfma_f32_16x16x32_bf16 v[28:31], v[170:173], v[178:181], v[28:31]
	v_mfma_f32_16x16x32_bf16 v[136:139], v[162:165], v[196:199], v[136:139]
	v_mfma_f32_16x16x32_bf16 v[140:143], v[170:173], v[196:199], v[140:143]
	v_mfma_f32_16x16x32_bf16 v[120:123], v[162:165], v[204:207], v[120:123]
	v_mfma_f32_16x16x32_bf16 v[124:127], v[170:173], v[204:207], v[124:127]
	v_mfma_f32_16x16x32_bf16 v[104:107], v[162:165], v[212:215], v[104:107]
	v_mfma_f32_16x16x32_bf16 v[108:111], v[170:173], v[212:215], v[108:111]
	v_mfma_f32_16x16x32_bf16 v[24:27], v[166:169], v[182:185], v[24:27]
	v_mfma_f32_16x16x32_bf16 v[28:31], v[174:177], v[182:185], v[28:31]
	v_mfma_f32_16x16x32_bf16 v[136:139], v[166:169], v[200:203], v[136:139]
	v_mfma_f32_16x16x32_bf16 v[140:143], v[174:177], v[200:203], v[140:143]
	v_mfma_f32_16x16x32_bf16 v[120:123], v[166:169], v[208:211], v[120:123]
	v_mfma_f32_16x16x32_bf16 v[124:127], v[174:177], v[208:211], v[124:127]
	v_mfma_f32_16x16x32_bf16 v[104:107], v[166:169], v[216:219], v[104:107]
	v_mfma_f32_16x16x32_bf16 v[108:111], v[174:177], v[216:219], v[108:111]
	s_barrier
	s_add_i32 s65, s65, s89
	v_lshl_add_u64 v[186:187], v[186:187], 0, s[56:57]
	s_mov_b32 m0, s65
	ds_read_b128 v[178:181], v192 offset:49152
	ds_read_b128 v[182:185], v192 offset:50176
	ds_read_b128 v[196:199], v192 offset:51200
	ds_read_b128 v[200:203], v192 offset:52224
	ds_read_b128 v[204:207], v192 offset:53248
	ds_read_b128 v[208:211], v192 offset:54272
	ds_read_b128 v[212:215], v192 offset:55296
	ds_read_b128 v[216:219], v192 offset:56320
	global_load_lds_dwordx4 v[186:187], off
	s_add_i32 m0, s65, 0x2000
	s_add_u32 s4, s4, 0x40080
	v_lshl_add_u64 v[186:187], v[220:221], 0, s[56:57]
	s_addc_u32 s5, s5, 0
	s_add_i32 s65, s72, s89
	global_load_lds_dwordx4 v[186:187], off
	v_lshl_add_u64 v[186:187], s[4:5], 0, v[144:145]
	s_mov_b32 m0, s65
	s_nop 0
	global_load_lds_dwordx4 v[186:187], off
	v_lshl_add_u64 v[186:187], s[4:5], 0, v[146:147]
	s_add_i32 m0, s65, 0x2000
	s_nop 0
	global_load_lds_dwordx4 v[186:187], off
	v_lshl_add_u64 v[186:187], v[222:223], 0, s[56:57]
	s_mov_b32 m0, s81
	s_nop 0
	global_load_lds_dwordx4 v[186:187], off
	v_lshl_add_u64 v[186:187], v[224:225], 0, s[56:57]
	s_mov_b32 m0, s80
	s_nop 0
	global_load_lds_dwordx4 v[186:187], off
	s_waitcnt vmcnt(8)
	s_waitcnt lgkmcnt(0)
	s_barrier
	s_waitcnt lgkmcnt(0)
	v_mfma_f32_16x16x32_bf16 v[0:3], v[36:39], v[212:215], v[0:3]
	v_mfma_f32_16x16x32_bf16 v[80:83], v[36:39], v[178:181], v[80:83]
	v_mfma_f32_16x16x32_bf16 v[84:87], v[88:91], v[178:181], v[84:87]
	v_mfma_f32_16x16x32_bf16 v[64:67], v[36:39], v[196:199], v[64:67]
	v_mfma_f32_16x16x32_bf16 v[68:71], v[88:91], v[196:199], v[68:71]
	v_mfma_f32_16x16x32_bf16 v[48:51], v[36:39], v[204:207], v[48:51]
	v_mfma_f32_16x16x32_bf16 v[52:55], v[88:91], v[204:207], v[52:55]
	v_mfma_f32_16x16x32_bf16 v[36:39], v[40:43], v[216:219], v[0:3]
	v_mfma_f32_16x16x32_bf16 v[0:3], v[88:91], v[212:215], v[4:7]
	v_mfma_f32_16x16x32_bf16 v[80:83], v[40:43], v[182:185], v[80:83]
	v_mfma_f32_16x16x32_bf16 v[84:87], v[92:95], v[182:185], v[84:87]
	v_mfma_f32_16x16x32_bf16 v[64:67], v[40:43], v[200:203], v[64:67]
	v_mfma_f32_16x16x32_bf16 v[68:71], v[92:95], v[200:203], v[68:71]
	v_mfma_f32_16x16x32_bf16 v[48:51], v[40:43], v[208:211], v[48:51]
	v_mfma_f32_16x16x32_bf16 v[52:55], v[92:95], v[208:211], v[52:55]
	v_mfma_f32_16x16x32_bf16 v[40:43], v[92:95], v[216:219], v[0:3]
	v_mfma_f32_16x16x32_bf16 v[0:3], v[162:165], v[178:181], v[8:11]
	v_mfma_f32_16x16x32_bf16 v[88:91], v[166:169], v[182:185], v[0:3]
	v_mfma_f32_16x16x32_bf16 v[0:3], v[170:173], v[178:181], v[12:15]
	v_mfma_f32_16x16x32_bf16 v[92:95], v[174:177], v[182:185], v[0:3]
	v_mfma_f32_16x16x32_bf16 v[0:3], v[162:165], v[196:199], v[72:75]
	v_mfma_f32_16x16x32_bf16 v[72:75], v[166:169], v[200:203], v[0:3]
	v_mfma_f32_16x16x32_bf16 v[0:3], v[170:173], v[196:199], v[76:79]
	v_mfma_f32_16x16x32_bf16 v[76:79], v[174:177], v[200:203], v[0:3]
	v_mfma_f32_16x16x32_bf16 v[0:3], v[162:165], v[204:207], v[56:59]
	v_mfma_f32_16x16x32_bf16 v[56:59], v[166:169], v[208:211], v[0:3]
	v_mfma_f32_16x16x32_bf16 v[0:3], v[170:173], v[204:207], v[60:63]
	v_mfma_f32_16x16x32_bf16 v[60:63], v[174:177], v[208:211], v[0:3]
	v_mfma_f32_16x16x32_bf16 v[0:3], v[162:165], v[212:215], v[44:47]
	v_mfma_f32_16x16x32_bf16 v[44:47], v[166:169], v[216:219], v[0:3]
	v_mfma_f32_16x16x32_bf16 v[0:3], v[170:173], v[212:215], v[32:35]
	v_mfma_f32_16x16x32_bf16 v[32:35], v[174:177], v[216:219], v[0:3]
	s_barrier
	s_add_u32 s14, s14, 0x100
	s_addc_u32 s15, s15, 0
	s_add_u32 s11, s11, 0x100
	s_addc_u32 s13, s13, 0
	s_cmp_ge_i32 s63, s36
	s_mov_b32 s4, s63
	s_cbranch_scc0 .LBB0_445

.LBB0_725:
	s_andn2_b64 vcc, exec, s[12:13]
	s_cbranch_vccnz .Lpz_zero_1
	s_add_u32 s30, s4, 0x10080
	s_addc_u32 s31, s5, 0
	s_add_u32 s23, s34, 0x100
	s_addc_u32 s25, s35, 0
	s_mov_b32 s4, 0
	ds_read_b128 v[144:147], v141
	ds_read_b128 v[150:153], v141 offset:1024
	ds_read_b128 v[154:157], v141 offset:2048
	ds_read_b128 v[158:161], v141 offset:3072
	ds_read_b128 v[162:165], v142
	ds_read_b128 v[166:169], v142 offset:1024
	ds_read_b128 v[170:173], v142 offset:2048
	ds_read_b128 v[174:177], v142 offset:3072
	s_add_i32 s54, s4, 2
	s_add_u32 s5, s30, 0xffff0080
	s_addc_u32 s34, s31, -1
	s_cmp_eq_u32 s46, s4
	s_cselect_b32 s4, s28, s23
	s_cselect_b32 s35, s27, s34
	s_cselect_b32 s34, s26, s5
	s_cselect_b32 s5, s29, s25
	v_lshl_add_u64 v[186:187], s[30:31], 0, v[132:133]
	s_add_i32 m0, s17, 0xc000
	ds_read_b128 v[178:181], v143
	ds_read_b128 v[182:185], v143 offset:1024
	ds_read_b128 v[190:193], v143 offset:2048
	ds_read_b128 v[194:197], v143 offset:3072
	ds_read_b128 v[198:201], v143 offset:4096
	ds_read_b128 v[202:205], v143 offset:5120
	ds_read_b128 v[206:209], v143 offset:6144
	ds_read_b128 v[210:213], v143 offset:7168
	global_load_lds_dwordx4 v[186:187], off
	v_lshl_add_u64 v[186:187], s[30:31], 0, v[134:135]
	s_add_i32 m0, s17, 0xe000
	s_nop 0
	global_load_lds_dwordx4 v[186:187], off
	s_waitcnt vmcnt(8)
	s_waitcnt lgkmcnt(0)
	s_barrier
	s_waitcnt lgkmcnt(0)
	v_mfma_f32_16x16x32_bf16 v[120:123], v[144:147], v[178:181], 0
	v_mfma_f32_16x16x32_bf16 v[124:127], v[154:157], v[178:181], 0
	v_mfma_f32_16x16x32_bf16 v[108:111], v[144:147], v[190:193], 0
	v_mfma_f32_16x16x32_bf16 v[104:107], v[154:157], v[190:193], 0
	v_mfma_f32_16x16x32_bf16 v[92:95], v[144:147], v[198:201], 0
	v_mfma_f32_16x16x32_bf16 v[88:91], v[154:157], v[198:201], 0
	v_mfma_f32_16x16x32_bf16 v[76:79], v[144:147], v[206:209], 0
	v_mfma_f32_16x16x32_bf16 v[72:75], v[154:157], v[206:209], 0
	v_mfma_f32_16x16x32_bf16 v[120:123], v[150:153], v[182:185], v[120:123]
	v_mfma_f32_16x16x32_bf16 v[124:127], v[158:161], v[182:185], v[124:127]
	v_mfma_f32_16x16x32_bf16 v[108:111], v[150:153], v[194:197], v[108:111]
	v_mfma_f32_16x16x32_bf16 v[104:107], v[158:161], v[194:197], v[104:107]
	v_mfma_f32_16x16x32_bf16 v[92:95], v[150:153], v[202:205], v[92:95]
	v_mfma_f32_16x16x32_bf16 v[88:91], v[158:161], v[202:205], v[88:91]
	v_mfma_f32_16x16x32_bf16 v[76:79], v[150:153], v[210:213], v[76:79]
	v_mfma_f32_16x16x32_bf16 v[72:75], v[158:161], v[210:213], v[72:75]
	v_mfma_f32_16x16x32_bf16 v[116:119], v[162:165], v[178:181], 0
	v_mfma_f32_16x16x32_bf16 v[112:115], v[170:173], v[178:181], 0
	v_mfma_f32_16x16x32_bf16 v[100:103], v[162:165], v[190:193], 0
	v_mfma_f32_16x16x32_bf16 v[96:99], v[170:173], v[190:193], 0
	v_mfma_f32_16x16x32_bf16 v[84:87], v[162:165], v[198:201], 0
	v_mfma_f32_16x16x32_bf16 v[80:83], v[170:173], v[198:201], 0
	v_mfma_f32_16x16x32_bf16 v[68:71], v[162:165], v[206:209], 0
	v_mfma_f32_16x16x32_bf16 v[64:67], v[170:173], v[206:209], 0
	v_mfma_f32_16x16x32_bf16 v[116:119], v[166:169], v[182:185], v[116:119]
	v_mfma_f32_16x16x32_bf16 v[112:115], v[174:177], v[182:185], v[112:115]
	v_mfma_f32_16x16x32_bf16 v[100:103], v[166:169], v[194:197], v[100:103]
	v_mfma_f32_16x16x32_bf16 v[96:99], v[174:177], v[194:197], v[96:99]
	v_mfma_f32_16x16x32_bf16 v[84:87], v[166:169], v[202:205], v[84:87]
	v_mfma_f32_16x16x32_bf16 v[80:83], v[174:177], v[202:205], v[80:83]
	v_mfma_f32_16x16x32_bf16 v[68:71], v[166:169], v[210:213], v[68:71]
	v_mfma_f32_16x16x32_bf16 v[64:67], v[174:177], v[210:213], v[64:67]
	s_barrier
	s_add_i32 s55, s51, s33
	v_lshl_add_u64 v[186:187], s[4:5], 0, v[128:129]
	s_mov_b32 m0, s55
	ds_read_b128 v[178:181], v143 offset:16384
	ds_read_b128 v[182:185], v143 offset:17408
	ds_read_b128 v[190:193], v143 offset:18432
	ds_read_b128 v[194:197], v143 offset:19456
	ds_read_b128 v[198:201], v143 offset:20480
	ds_read_b128 v[202:205], v143 offset:21504
	ds_read_b128 v[206:209], v143 offset:22528
	ds_read_b128 v[210:213], v143 offset:23552
	global_load_lds_dwordx4 v[186:187], off
	s_add_i32 m0, s55, 0x2000
	s_add_u32 s56, s4, 0x10000
	v_lshl_add_u64 v[214:215], s[4:5], 0, v[130:131]
	s_addc_u32 s57, s5, 0
	s_add_i32 s55, s52, s33
	global_load_lds_dwordx4 v[214:215], off
	v_lshl_add_u64 v[216:217], s[56:57], 0, v[128:129]
	s_mov_b32 m0, s55
	v_lshl_add_u64 v[218:219], s[34:35], 0, v[130:131]
	global_load_lds_dwordx4 v[216:217], off
	v_lshl_add_u64 v[216:217], s[56:57], 0, v[130:131]
	s_add_i32 m0, s55, 0x2000
	s_nop 0
	global_load_lds_dwordx4 v[216:217], off
	v_lshl_add_u64 v[216:217], s[34:35], 0, v[128:129]
	s_mov_b32 m0, s17
	s_nop 0
	global_load_lds_dwordx4 v[216:217], off
	s_mov_b32 m0, s21
	s_nop 0
	global_load_lds_dwordx4 v[218:219], off
	s_waitcnt vmcnt(8)
	s_waitcnt lgkmcnt(0)
	s_barrier
	s_waitcnt lgkmcnt(0)
	v_mfma_f32_16x16x32_bf16 v[60:63], v[144:147], v[178:181], 0
	v_mfma_f32_16x16x32_bf16 v[56:59], v[154:157], v[178:181], 0
	v_mfma_f32_16x16x32_bf16 v[44:47], v[144:147], v[190:193], 0
	v_mfma_f32_16x16x32_bf16 v[40:43], v[154:157], v[190:193], 0
	v_mfma_f32_16x16x32_bf16 v[28:31], v[144:147], v[198:201], 0
	v_mfma_f32_16x16x32_bf16 v[24:27], v[154:157], v[198:201], 0
	v_mfma_f32_16x16x32_bf16 v[12:15], v[144:147], v[206:209], 0
	v_mfma_f32_16x16x32_bf16 v[8:11], v[154:157], v[206:209], 0
	v_mfma_f32_16x16x32_bf16 v[60:63], v[150:153], v[182:185], v[60:63]
	v_mfma_f32_16x16x32_bf16 v[56:59], v[158:161], v[182:185], v[56:59]
	v_mfma_f32_16x16x32_bf16 v[44:47], v[150:153], v[194:197], v[44:47]
	v_mfma_f32_16x16x32_bf16 v[40:43], v[158:161], v[194:197], v[40:43]
	v_mfma_f32_16x16x32_bf16 v[28:31], v[150:153], v[202:205], v[28:31]
	v_mfma_f32_16x16x32_bf16 v[24:27], v[158:161], v[202:205], v[24:27]
	v_mfma_f32_16x16x32_bf16 v[12:15], v[150:153], v[210:213], v[12:15]
	v_mfma_f32_16x16x32_bf16 v[8:11], v[158:161], v[210:213], v[8:11]
	v_mfma_f32_16x16x32_bf16 v[52:55], v[162:165], v[178:181], 0
	v_mfma_f32_16x16x32_bf16 v[48:51], v[170:173], v[178:181], 0
	v_mfma_f32_16x16x32_bf16 v[36:39], v[162:165], v[190:193], 0
	v_mfma_f32_16x16x32_bf16 v[32:35], v[170:173], v[190:193], 0
	v_mfma_f32_16x16x32_bf16 v[20:23], v[162:165], v[198:201], 0
	v_mfma_f32_16x16x32_bf16 v[16:19], v[170:173], v[198:201], 0
	v_mfma_f32_16x16x32_bf16 v[4:7], v[162:165], v[206:209], 0
	v_mfma_f32_16x16x32_bf16 v[0:3], v[170:173], v[206:209], 0
	v_mfma_f32_16x16x32_bf16 v[52:55], v[166:169], v[182:185], v[52:55]
	v_mfma_f32_16x16x32_bf16 v[48:51], v[174:177], v[182:185], v[48:51]
	v_mfma_f32_16x16x32_bf16 v[36:39], v[166:169], v[194:197], v[36:39]
	v_mfma_f32_16x16x32_bf16 v[32:35], v[174:177], v[194:197], v[32:35]
	v_mfma_f32_16x16x32_bf16 v[20:23], v[166:169], v[202:205], v[20:23]
	v_mfma_f32_16x16x32_bf16 v[16:19], v[174:177], v[202:205], v[16:19]
	v_mfma_f32_16x16x32_bf16 v[4:7], v[166:169], v[210:213], v[4:7]
	v_mfma_f32_16x16x32_bf16 v[0:3], v[174:177], v[210:213], v[0:3]
	s_barrier
	s_add_i32 s55, 0, 0x18000
	v_add_u32_e32 v149, s55, v139
	s_add_i32 s56, 0, 0x1c000
	ds_read_b128 v[144:147], v149
	ds_read_b128 v[150:153], v149 offset:1024
	ds_read_b128 v[154:157], v149 offset:2048
	ds_read_b128 v[158:161], v149 offset:3072
	v_add_u32_e32 v149, s56, v139
	ds_read_b128 v[162:165], v149
	ds_read_b128 v[166:169], v149 offset:1024
	ds_read_b128 v[170:173], v149 offset:2048
	ds_read_b128 v[174:177], v149 offset:3072
	s_add_u32 s34, s34, 0x10000
	s_addc_u32 s35, s35, 0
	s_mov_b32 m0, s40
	v_lshl_add_u64 v[220:221], s[34:35], 0, v[128:129]
	ds_read_b128 v[178:181], v143 offset:32768
	ds_read_b128 v[182:185], v143 offset:33792
	ds_read_b128 v[190:193], v143 offset:34816
	ds_read_b128 v[194:197], v143 offset:35840
	ds_read_b128 v[198:201], v143 offset:36864
	ds_read_b128 v[202:205], v143 offset:37888
	ds_read_b128 v[206:209], v143 offset:38912
	ds_read_b128 v[210:213], v143 offset:39936
	global_load_lds_dwordx4 v[220:221], off
	v_lshl_add_u64 v[220:221], s[34:35], 0, v[130:131]
	s_mov_b32 m0, s41
	s_nop 0
	global_load_lds_dwordx4 v[220:221], off
	s_waitcnt vmcnt(8)
	s_waitcnt lgkmcnt(0)
	s_barrier
	s_waitcnt lgkmcnt(0)
	v_mfma_f32_16x16x32_bf16 v[120:123], v[144:147], v[178:181], v[120:123]
	v_mfma_f32_16x16x32_bf16 v[124:127], v[154:157], v[178:181], v[124:127]
	v_mfma_f32_16x16x32_bf16 v[108:111], v[144:147], v[190:193], v[108:111]
	v_mfma_f32_16x16x32_bf16 v[104:107], v[154:157], v[190:193], v[104:107]
	v_mfma_f32_16x16x32_bf16 v[92:95], v[144:147], v[198:201], v[92:95]
	v_mfma_f32_16x16x32_bf16 v[88:91], v[154:157], v[198:201], v[88:91]
	v_mfma_f32_16x16x32_bf16 v[76:79], v[144:147], v[206:209], v[76:79]
	v_mfma_f32_16x16x32_bf16 v[72:75], v[154:157], v[206:209], v[72:75]
	v_mfma_f32_16x16x32_bf16 v[120:123], v[150:153], v[182:185], v[120:123]
	v_mfma_f32_16x16x32_bf16 v[124:127], v[158:161], v[182:185], v[124:127]
	v_mfma_f32_16x16x32_bf16 v[108:111], v[150:153], v[194:197], v[108:111]
	v_mfma_f32_16x16x32_bf16 v[104:107], v[158:161], v[194:197], v[104:107]
	v_mfma_f32_16x16x32_bf16 v[92:95], v[150:153], v[202:205], v[92:95]
	v_mfma_f32_16x16x32_bf16 v[88:91], v[158:161], v[202:205], v[88:91]
	v_mfma_f32_16x16x32_bf16 v[76:79], v[150:153], v[210:213], v[76:79]
	v_mfma_f32_16x16x32_bf16 v[72:75], v[158:161], v[210:213], v[72:75]
	v_mfma_f32_16x16x32_bf16 v[116:119], v[162:165], v[178:181], v[116:119]
	v_mfma_f32_16x16x32_bf16 v[112:115], v[170:173], v[178:181], v[112:115]
	v_mfma_f32_16x16x32_bf16 v[100:103], v[162:165], v[190:193], v[100:103]
	v_mfma_f32_16x16x32_bf16 v[96:99], v[170:173], v[190:193], v[96:99]
	v_mfma_f32_16x16x32_bf16 v[84:87], v[162:165], v[198:201], v[84:87]
	v_mfma_f32_16x16x32_bf16 v[80:83], v[170:173], v[198:201], v[80:83]
	v_mfma_f32_16x16x32_bf16 v[68:71], v[162:165], v[206:209], v[68:71]
	v_mfma_f32_16x16x32_bf16 v[64:67], v[170:173], v[206:209], v[64:67]
	v_mfma_f32_16x16x32_bf16 v[116:119], v[166:169], v[182:185], v[116:119]
	v_mfma_f32_16x16x32_bf16 v[112:115], v[174:177], v[182:185], v[112:115]
	v_mfma_f32_16x16x32_bf16 v[100:103], v[166:169], v[194:197], v[100:103]
	v_mfma_f32_16x16x32_bf16 v[96:99], v[174:177], v[194:197], v[96:99]
	v_mfma_f32_16x16x32_bf16 v[84:87], v[166:169], v[202:205], v[84:87]
	v_mfma_f32_16x16x32_bf16 v[80:83], v[174:177], v[202:205], v[80:83]
	v_mfma_f32_16x16x32_bf16 v[68:71], v[166:169], v[210:213], v[68:71]
	v_mfma_f32_16x16x32_bf16 v[64:67], v[174:177], v[210:213], v[64:67]
	s_barrier
	s_add_i32 s34, s55, s33
	v_lshl_add_u64 v[186:187], v[186:187], 0, s[10:11]
	s_mov_b32 m0, s34
	ds_read_b128 v[178:181], v143 offset:49152
	ds_read_b128 v[182:185], v143 offset:50176
	ds_read_b128 v[190:193], v143 offset:51200
	ds_read_b128 v[194:197], v143 offset:52224
	ds_read_b128 v[198:201], v143 offset:53248
	ds_read_b128 v[202:205], v143 offset:54272
	ds_read_b128 v[206:209], v143 offset:55296
	ds_read_b128 v[210:213], v143 offset:56320
	global_load_lds_dwordx4 v[186:187], off
	s_add_i32 m0, s34, 0x2000
	s_add_u32 s4, s4, 0x10080
	v_lshl_add_u64 v[186:187], v[214:215], 0, s[10:11]
	s_addc_u32 s5, s5, 0
	s_add_i32 s34, s56, s33
	global_load_lds_dwordx4 v[186:187], off
	v_lshl_add_u64 v[186:187], s[4:5], 0, v[128:129]
	s_mov_b32 m0, s34
	s_nop 0
	global_load_lds_dwordx4 v[186:187], off
	v_lshl_add_u64 v[186:187], s[4:5], 0, v[130:131]
	s_add_i32 m0, s34, 0x2000
	s_nop 0
	global_load_lds_dwordx4 v[186:187], off
	v_lshl_add_u64 v[186:187], v[216:217], 0, s[10:11]
	s_mov_b32 m0, s44
	s_nop 0
	global_load_lds_dwordx4 v[186:187], off
	v_lshl_add_u64 v[186:187], v[218:219], 0, s[10:11]
	s_mov_b32 m0, s45
	s_nop 0
	global_load_lds_dwordx4 v[186:187], off
	s_waitcnt vmcnt(8)
	s_waitcnt lgkmcnt(0)
	s_barrier
	s_waitcnt lgkmcnt(0)
	v_mfma_f32_16x16x32_bf16 v[60:63], v[144:147], v[178:181], v[60:63]
	v_mfma_f32_16x16x32_bf16 v[56:59], v[154:157], v[178:181], v[56:59]
	v_mfma_f32_16x16x32_bf16 v[44:47], v[144:147], v[190:193], v[44:47]
	v_mfma_f32_16x16x32_bf16 v[40:43], v[154:157], v[190:193], v[40:43]
	v_mfma_f32_16x16x32_bf16 v[28:31], v[144:147], v[198:201], v[28:31]
	v_mfma_f32_16x16x32_bf16 v[24:27], v[154:157], v[198:201], v[24:27]
	v_mfma_f32_16x16x32_bf16 v[12:15], v[144:147], v[206:209], v[12:15]
	v_mfma_f32_16x16x32_bf16 v[8:11], v[154:157], v[206:209], v[8:11]
	v_mfma_f32_16x16x32_bf16 v[60:63], v[150:153], v[182:185], v[60:63]
	v_mfma_f32_16x16x32_bf16 v[56:59], v[158:161], v[182:185], v[56:59]
	v_mfma_f32_16x16x32_bf16 v[44:47], v[150:153], v[194:197], v[44:47]
	v_mfma_f32_16x16x32_bf16 v[40:43], v[158:161], v[194:197], v[40:43]
	v_mfma_f32_16x16x32_bf16 v[28:31], v[150:153], v[202:205], v[28:31]
	v_mfma_f32_16x16x32_bf16 v[24:27], v[158:161], v[202:205], v[24:27]
	v_mfma_f32_16x16x32_bf16 v[12:15], v[150:153], v[210:213], v[12:15]
	v_mfma_f32_16x16x32_bf16 v[8:11], v[158:161], v[210:213], v[8:11]
	v_mfma_f32_16x16x32_bf16 v[52:55], v[162:165], v[178:181], v[52:55]
	v_mfma_f32_16x16x32_bf16 v[48:51], v[170:173], v[178:181], v[48:51]
	v_mfma_f32_16x16x32_bf16 v[36:39], v[162:165], v[190:193], v[36:39]
	v_mfma_f32_16x16x32_bf16 v[32:35], v[170:173], v[190:193], v[32:35]
	v_mfma_f32_16x16x32_bf16 v[20:23], v[162:165], v[198:201], v[20:23]
	v_mfma_f32_16x16x32_bf16 v[16:19], v[170:173], v[198:201], v[16:19]
	v_mfma_f32_16x16x32_bf16 v[4:7], v[162:165], v[206:209], v[4:7]
	v_mfma_f32_16x16x32_bf16 v[0:3], v[170:173], v[206:209], v[0:3]
	v_mfma_f32_16x16x32_bf16 v[52:55], v[166:169], v[182:185], v[52:55]
	v_mfma_f32_16x16x32_bf16 v[48:51], v[174:177], v[182:185], v[48:51]
	v_mfma_f32_16x16x32_bf16 v[36:39], v[166:169], v[194:197], v[36:39]
	v_mfma_f32_16x16x32_bf16 v[32:35], v[174:177], v[194:197], v[32:35]
	v_mfma_f32_16x16x32_bf16 v[20:23], v[166:169], v[202:205], v[20:23]
	v_mfma_f32_16x16x32_bf16 v[16:19], v[174:177], v[202:205], v[16:19]
	v_mfma_f32_16x16x32_bf16 v[4:7], v[166:169], v[210:213], v[4:7]
	v_mfma_f32_16x16x32_bf16 v[0:3], v[174:177], v[210:213], v[0:3]
	s_barrier
	s_add_u32 s30, s30, 0x100
	s_addc_u32 s31, s31, 0
	s_add_u32 s23, s23, 0x100
	s_addc_u32 s25, s25, 0
	s_cmp_ge_i32 s54, s42
	s_mov_b32 s4, s54
	s_cbranch_scc0 .LBB0_727
	s_branch .LBB0_728

.LBB0_727:
	ds_read_b128 v[144:147], v141
	ds_read_b128 v[150:153], v141 offset:1024
	ds_read_b128 v[154:157], v141 offset:2048
	ds_read_b128 v[158:161], v141 offset:3072
	ds_read_b128 v[162:165], v142
	ds_read_b128 v[166:169], v142 offset:1024
	ds_read_b128 v[170:173], v142 offset:2048
	ds_read_b128 v[174:177], v142 offset:3072
	s_add_i32 s54, s4, 2
	s_add_u32 s5, s30, 0xffff0080
	s_addc_u32 s34, s31, -1
	s_cmp_eq_u32 s46, s4
	s_cselect_b32 s4, s28, s23
	s_cselect_b32 s35, s27, s34
	s_cselect_b32 s34, s26, s5
	s_cselect_b32 s5, s29, s25
	v_lshl_add_u64 v[186:187], s[30:31], 0, v[132:133]
	s_add_i32 m0, s17, 0xc000
	ds_read_b128 v[178:181], v143
	ds_read_b128 v[182:185], v143 offset:1024
	ds_read_b128 v[190:193], v143 offset:2048
	ds_read_b128 v[194:197], v143 offset:3072
	ds_read_b128 v[198:201], v143 offset:4096
	ds_read_b128 v[202:205], v143 offset:5120
	ds_read_b128 v[206:209], v143 offset:6144
	ds_read_b128 v[210:213], v143 offset:7168
	global_load_lds_dwordx4 v[186:187], off
	v_lshl_add_u64 v[186:187], s[30:31], 0, v[134:135]
	s_add_i32 m0, s17, 0xe000
	s_nop 0
	global_load_lds_dwordx4 v[186:187], off
	s_waitcnt vmcnt(8)
	s_waitcnt lgkmcnt(0)
	s_barrier
	s_waitcnt lgkmcnt(0)
	v_mfma_f32_16x16x32_bf16 v[120:123], v[144:147], v[178:181], v[120:123]
	v_mfma_f32_16x16x32_bf16 v[124:127], v[154:157], v[178:181], v[124:127]
	v_mfma_f32_16x16x32_bf16 v[108:111], v[144:147], v[190:193], v[108:111]
	v_mfma_f32_16x16x32_bf16 v[104:107], v[154:157], v[190:193], v[104:107]
	v_mfma_f32_16x16x32_bf16 v[92:95], v[144:147], v[198:201], v[92:95]
	v_mfma_f32_16x16x32_bf16 v[88:91], v[154:157], v[198:201], v[88:91]
	v_mfma_f32_16x16x32_bf16 v[76:79], v[144:147], v[206:209], v[76:79]
	v_mfma_f32_16x16x32_bf16 v[72:75], v[154:157], v[206:209], v[72:75]
	v_mfma_f32_16x16x32_bf16 v[120:123], v[150:153], v[182:185], v[120:123]
	v_mfma_f32_16x16x32_bf16 v[124:127], v[158:161], v[182:185], v[124:127]
	v_mfma_f32_16x16x32_bf16 v[108:111], v[150:153], v[194:197], v[108:111]
	v_mfma_f32_16x16x32_bf16 v[104:107], v[158:161], v[194:197], v[104:107]
	v_mfma_f32_16x16x32_bf16 v[92:95], v[150:153], v[202:205], v[92:95]
	v_mfma_f32_16x16x32_bf16 v[88:91], v[158:161], v[202:205], v[88:91]
	v_mfma_f32_16x16x32_bf16 v[76:79], v[150:153], v[210:213], v[76:79]
	v_mfma_f32_16x16x32_bf16 v[72:75], v[158:161], v[210:213], v[72:75]
	v_mfma_f32_16x16x32_bf16 v[116:119], v[162:165], v[178:181], v[116:119]
	v_mfma_f32_16x16x32_bf16 v[112:115], v[170:173], v[178:181], v[112:115]
	v_mfma_f32_16x16x32_bf16 v[100:103], v[162:165], v[190:193], v[100:103]
	v_mfma_f32_16x16x32_bf16 v[96:99], v[170:173], v[190:193], v[96:99]
	v_mfma_f32_16x16x32_bf16 v[84:87], v[162:165], v[198:201], v[84:87]
	v_mfma_f32_16x16x32_bf16 v[80:83], v[170:173], v[198:201], v[80:83]
	v_mfma_f32_16x16x32_bf16 v[68:71], v[162:165], v[206:209], v[68:71]
	v_mfma_f32_16x16x32_bf16 v[64:67], v[170:173], v[206:209], v[64:67]
	v_mfma_f32_16x16x32_bf16 v[116:119], v[166:169], v[182:185], v[116:119]
	v_mfma_f32_16x16x32_bf16 v[112:115], v[174:177], v[182:185], v[112:115]
	v_mfma_f32_16x16x32_bf16 v[100:103], v[166:169], v[194:197], v[100:103]
	v_mfma_f32_16x16x32_bf16 v[96:99], v[174:177], v[194:197], v[96:99]
	v_mfma_f32_16x16x32_bf16 v[84:87], v[166:169], v[202:205], v[84:87]
	v_mfma_f32_16x16x32_bf16 v[80:83], v[174:177], v[202:205], v[80:83]
	v_mfma_f32_16x16x32_bf16 v[68:71], v[166:169], v[210:213], v[68:71]
	v_mfma_f32_16x16x32_bf16 v[64:67], v[174:177], v[210:213], v[64:67]
	s_barrier
	s_add_i32 s55, s51, s33
	v_lshl_add_u64 v[186:187], s[4:5], 0, v[128:129]
	s_mov_b32 m0, s55
	ds_read_b128 v[178:181], v143 offset:16384
	ds_read_b128 v[182:185], v143 offset:17408
	ds_read_b128 v[190:193], v143 offset:18432
	ds_read_b128 v[194:197], v143 offset:19456
	ds_read_b128 v[198:201], v143 offset:20480
	ds_read_b128 v[202:205], v143 offset:21504
	ds_read_b128 v[206:209], v143 offset:22528
	ds_read_b128 v[210:213], v143 offset:23552
	global_load_lds_dwordx4 v[186:187], off
	s_add_i32 m0, s55, 0x2000
	s_add_u32 s56, s4, 0x10000
	v_lshl_add_u64 v[214:215], s[4:5], 0, v[130:131]
	s_addc_u32 s57, s5, 0
	s_add_i32 s55, s52, s33
	global_load_lds_dwordx4 v[214:215], off
	v_lshl_add_u64 v[216:217], s[56:57], 0, v[128:129]
	s_mov_b32 m0, s55
	v_lshl_add_u64 v[218:219], s[34:35], 0, v[130:131]
	global_load_lds_dwordx4 v[216:217], off
	v_lshl_add_u64 v[216:217], s[56:57], 0, v[130:131]
	s_add_i32 m0, s55, 0x2000
	s_nop 0
	global_load_lds_dwordx4 v[216:217], off
	v_lshl_add_u64 v[216:217], s[34:35], 0, v[128:129]
	s_mov_b32 m0, s17
	s_nop 0
	global_load_lds_dwordx4 v[216:217], off
	s_mov_b32 m0, s21
	s_nop 0
	global_load_lds_dwordx4 v[218:219], off
	s_waitcnt vmcnt(8)
	s_waitcnt lgkmcnt(0)
	s_barrier
	s_waitcnt lgkmcnt(0)
	v_mfma_f32_16x16x32_bf16 v[60:63], v[144:147], v[178:181], v[60:63]
	v_mfma_f32_16x16x32_bf16 v[56:59], v[154:157], v[178:181], v[56:59]
	v_mfma_f32_16x16x32_bf16 v[44:47], v[144:147], v[190:193], v[44:47]
	v_mfma_f32_16x16x32_bf16 v[40:43], v[154:157], v[190:193], v[40:43]
	v_mfma_f32_16x16x32_bf16 v[28:31], v[144:147], v[198:201], v[28:31]
	v_mfma_f32_16x16x32_bf16 v[24:27], v[154:157], v[198:201], v[24:27]
	v_mfma_f32_16x16x32_bf16 v[12:15], v[144:147], v[206:209], v[12:15]
	v_mfma_f32_16x16x32_bf16 v[8:11], v[154:157], v[206:209], v[8:11]
	v_mfma_f32_16x16x32_bf16 v[60:63], v[150:153], v[182:185], v[60:63]
	v_mfma_f32_16x16x32_bf16 v[56:59], v[158:161], v[182:185], v[56:59]
	v_mfma_f32_16x16x32_bf16 v[44:47], v[150:153], v[194:197], v[44:47]
	v_mfma_f32_16x16x32_bf16 v[40:43], v[158:161], v[194:197], v[40:43]
	v_mfma_f32_16x16x32_bf16 v[28:31], v[150:153], v[202:205], v[28:31]
	v_mfma_f32_16x16x32_bf16 v[24:27], v[158:161], v[202:205], v[24:27]
	v_mfma_f32_16x16x32_bf16 v[12:15], v[150:153], v[210:213], v[12:15]
	v_mfma_f32_16x16x32_bf16 v[8:11], v[158:161], v[210:213], v[8:11]
	v_mfma_f32_16x16x32_bf16 v[52:55], v[162:165], v[178:181], v[52:55]
	v_mfma_f32_16x16x32_bf16 v[48:51], v[170:173], v[178:181], v[48:51]
	v_mfma_f32_16x16x32_bf16 v[36:39], v[162:165], v[190:193], v[36:39]
	v_mfma_f32_16x16x32_bf16 v[32:35], v[170:173], v[190:193], v[32:35]
	v_mfma_f32_16x16x32_bf16 v[20:23], v[162:165], v[198:201], v[20:23]
	v_mfma_f32_16x16x32_bf16 v[16:19], v[170:173], v[198:201], v[16:19]
	v_mfma_f32_16x16x32_bf16 v[4:7], v[162:165], v[206:209], v[4:7]
	v_mfma_f32_16x16x32_bf16 v[0:3], v[170:173], v[206:209], v[0:3]
	v_mfma_f32_16x16x32_bf16 v[52:55], v[166:169], v[182:185], v[52:55]
	v_mfma_f32_16x16x32_bf16 v[48:51], v[174:177], v[182:185], v[48:51]
	v_mfma_f32_16x16x32_bf16 v[36:39], v[166:169], v[194:197], v[36:39]
	v_mfma_f32_16x16x32_bf16 v[32:35], v[174:177], v[194:197], v[32:35]
	v_mfma_f32_16x16x32_bf16 v[20:23], v[166:169], v[202:205], v[20:23]
	v_mfma_f32_16x16x32_bf16 v[16:19], v[174:177], v[202:205], v[16:19]
	v_mfma_f32_16x16x32_bf16 v[4:7], v[166:169], v[210:213], v[4:7]
	v_mfma_f32_16x16x32_bf16 v[0:3], v[174:177], v[210:213], v[0:3]
	s_barrier
	s_add_i32 s55, 0, 0x18000
	v_add_u32_e32 v149, s55, v139
	s_add_i32 s56, 0, 0x1c000
	ds_read_b128 v[144:147], v149
	ds_read_b128 v[150:153], v149 offset:1024
	ds_read_b128 v[154:157], v149 offset:2048
	ds_read_b128 v[158:161], v149 offset:3072
	v_add_u32_e32 v149, s56, v139
	ds_read_b128 v[162:165], v149
	ds_read_b128 v[166:169], v149 offset:1024
	ds_read_b128 v[170:173], v149 offset:2048
	ds_read_b128 v[174:177], v149 offset:3072
	s_add_u32 s34, s34, 0x10000
	s_addc_u32 s35, s35, 0
	s_mov_b32 m0, s40
	v_lshl_add_u64 v[220:221], s[34:35], 0, v[128:129]
	ds_read_b128 v[178:181], v143 offset:32768
	ds_read_b128 v[182:185], v143 offset:33792
	ds_read_b128 v[190:193], v143 offset:34816
	ds_read_b128 v[194:197], v143 offset:35840
	ds_read_b128 v[198:201], v143 offset:36864
	ds_read_b128 v[202:205], v143 offset:37888
	ds_read_b128 v[206:209], v143 offset:38912
	ds_read_b128 v[210:213], v143 offset:39936
	global_load_lds_dwordx4 v[220:221], off
	v_lshl_add_u64 v[220:221], s[34:35], 0, v[130:131]
	s_mov_b32 m0, s41
	s_nop 0
	global_load_lds_dwordx4 v[220:221], off
	s_waitcnt vmcnt(8)
	s_waitcnt lgkmcnt(0)
	s_barrier
	s_waitcnt lgkmcnt(0)
	v_mfma_f32_16x16x32_bf16 v[120:123], v[144:147], v[178:181], v[120:123]
	v_mfma_f32_16x16x32_bf16 v[124:127], v[154:157], v[178:181], v[124:127]
	v_mfma_f32_16x16x32_bf16 v[108:111], v[144:147], v[190:193], v[108:111]
	v_mfma_f32_16x16x32_bf16 v[104:107], v[154:157], v[190:193], v[104:107]
	v_mfma_f32_16x16x32_bf16 v[92:95], v[144:147], v[198:201], v[92:95]
	v_mfma_f32_16x16x32_bf16 v[88:91], v[154:157], v[198:201], v[88:91]
	v_mfma_f32_16x16x32_bf16 v[76:79], v[144:147], v[206:209], v[76:79]
	v_mfma_f32_16x16x32_bf16 v[72:75], v[154:157], v[206:209], v[72:75]
	v_mfma_f32_16x16x32_bf16 v[120:123], v[150:153], v[182:185], v[120:123]
	v_mfma_f32_16x16x32_bf16 v[124:127], v[158:161], v[182:185], v[124:127]
	v_mfma_f32_16x16x32_bf16 v[108:111], v[150:153], v[194:197], v[108:111]
	v_mfma_f32_16x16x32_bf16 v[104:107], v[158:161], v[194:197], v[104:107]
	v_mfma_f32_16x16x32_bf16 v[92:95], v[150:153], v[202:205], v[92:95]
	v_mfma_f32_16x16x32_bf16 v[88:91], v[158:161], v[202:205], v[88:91]
	v_mfma_f32_16x16x32_bf16 v[76:79], v[150:153], v[210:213], v[76:79]
	v_mfma_f32_16x16x32_bf16 v[72:75], v[158:161], v[210:213], v[72:75]
	v_mfma_f32_16x16x32_bf16 v[116:119], v[162:165], v[178:181], v[116:119]
	v_mfma_f32_16x16x32_bf16 v[112:115], v[170:173], v[178:181], v[112:115]
	v_mfma_f32_16x16x32_bf16 v[100:103], v[162:165], v[190:193], v[100:103]
	v_mfma_f32_16x16x32_bf16 v[96:99], v[170:173], v[190:193], v[96:99]
	v_mfma_f32_16x16x32_bf16 v[84:87], v[162:165], v[198:201], v[84:87]
	v_mfma_f32_16x16x32_bf16 v[80:83], v[170:173], v[198:201], v[80:83]
	v_mfma_f32_16x16x32_bf16 v[68:71], v[162:165], v[206:209], v[68:71]
	v_mfma_f32_16x16x32_bf16 v[64:67], v[170:173], v[206:209], v[64:67]
	v_mfma_f32_16x16x32_bf16 v[116:119], v[166:169], v[182:185], v[116:119]
	v_mfma_f32_16x16x32_bf16 v[112:115], v[174:177], v[182:185], v[112:115]
	v_mfma_f32_16x16x32_bf16 v[100:103], v[166:169], v[194:197], v[100:103]
	v_mfma_f32_16x16x32_bf16 v[96:99], v[174:177], v[194:197], v[96:99]
	v_mfma_f32_16x16x32_bf16 v[84:87], v[166:169], v[202:205], v[84:87]
	v_mfma_f32_16x16x32_bf16 v[80:83], v[174:177], v[202:205], v[80:83]
	v_mfma_f32_16x16x32_bf16 v[68:71], v[166:169], v[210:213], v[68:71]
	v_mfma_f32_16x16x32_bf16 v[64:67], v[174:177], v[210:213], v[64:67]
	s_barrier
	s_add_i32 s34, s55, s33
	v_lshl_add_u64 v[186:187], v[186:187], 0, s[10:11]
	s_mov_b32 m0, s34
	ds_read_b128 v[178:181], v143 offset:49152
	ds_read_b128 v[182:185], v143 offset:50176
	ds_read_b128 v[190:193], v143 offset:51200
	ds_read_b128 v[194:197], v143 offset:52224
	ds_read_b128 v[198:201], v143 offset:53248
	ds_read_b128 v[202:205], v143 offset:54272
	ds_read_b128 v[206:209], v143 offset:55296
	ds_read_b128 v[210:213], v143 offset:56320
	global_load_lds_dwordx4 v[186:187], off
	s_add_i32 m0, s34, 0x2000
	s_add_u32 s4, s4, 0x10080
	v_lshl_add_u64 v[186:187], v[214:215], 0, s[10:11]
	s_addc_u32 s5, s5, 0
	s_add_i32 s34, s56, s33
	global_load_lds_dwordx4 v[186:187], off
	v_lshl_add_u64 v[186:187], s[4:5], 0, v[128:129]
	s_mov_b32 m0, s34
	s_nop 0
	global_load_lds_dwordx4 v[186:187], off
	v_lshl_add_u64 v[186:187], s[4:5], 0, v[130:131]
	s_add_i32 m0, s34, 0x2000
	s_nop 0
	global_load_lds_dwordx4 v[186:187], off
	v_lshl_add_u64 v[186:187], v[216:217], 0, s[10:11]
	s_mov_b32 m0, s44
	s_nop 0
	global_load_lds_dwordx4 v[186:187], off
	v_lshl_add_u64 v[186:187], v[218:219], 0, s[10:11]
	s_mov_b32 m0, s45
	s_nop 0
	global_load_lds_dwordx4 v[186:187], off
	s_waitcnt vmcnt(8)
	s_waitcnt lgkmcnt(0)
	s_barrier
	s_waitcnt lgkmcnt(0)
	v_mfma_f32_16x16x32_bf16 v[60:63], v[144:147], v[178:181], v[60:63]
	v_mfma_f32_16x16x32_bf16 v[56:59], v[154:157], v[178:181], v[56:59]
	v_mfma_f32_16x16x32_bf16 v[44:47], v[144:147], v[190:193], v[44:47]
	v_mfma_f32_16x16x32_bf16 v[40:43], v[154:157], v[190:193], v[40:43]
	v_mfma_f32_16x16x32_bf16 v[28:31], v[144:147], v[198:201], v[28:31]
	v_mfma_f32_16x16x32_bf16 v[24:27], v[154:157], v[198:201], v[24:27]
	v_mfma_f32_16x16x32_bf16 v[12:15], v[144:147], v[206:209], v[12:15]
	v_mfma_f32_16x16x32_bf16 v[8:11], v[154:157], v[206:209], v[8:11]
	v_mfma_f32_16x16x32_bf16 v[60:63], v[150:153], v[182:185], v[60:63]
	v_mfma_f32_16x16x32_bf16 v[56:59], v[158:161], v[182:185], v[56:59]
	v_mfma_f32_16x16x32_bf16 v[44:47], v[150:153], v[194:197], v[44:47]
	v_mfma_f32_16x16x32_bf16 v[40:43], v[158:161], v[194:197], v[40:43]
	v_mfma_f32_16x16x32_bf16 v[28:31], v[150:153], v[202:205], v[28:31]
	v_mfma_f32_16x16x32_bf16 v[24:27], v[158:161], v[202:205], v[24:27]
	v_mfma_f32_16x16x32_bf16 v[12:15], v[150:153], v[210:213], v[12:15]
	v_mfma_f32_16x16x32_bf16 v[8:11], v[158:161], v[210:213], v[8:11]
	v_mfma_f32_16x16x32_bf16 v[52:55], v[162:165], v[178:181], v[52:55]
	v_mfma_f32_16x16x32_bf16 v[48:51], v[170:173], v[178:181], v[48:51]
	v_mfma_f32_16x16x32_bf16 v[36:39], v[162:165], v[190:193], v[36:39]
	v_mfma_f32_16x16x32_bf16 v[32:35], v[170:173], v[190:193], v[32:35]
	v_mfma_f32_16x16x32_bf16 v[20:23], v[162:165], v[198:201], v[20:23]
	v_mfma_f32_16x16x32_bf16 v[16:19], v[170:173], v[198:201], v[16:19]
	v_mfma_f32_16x16x32_bf16 v[4:7], v[162:165], v[206:209], v[4:7]
	v_mfma_f32_16x16x32_bf16 v[0:3], v[170:173], v[206:209], v[0:3]
	v_mfma_f32_16x16x32_bf16 v[52:55], v[166:169], v[182:185], v[52:55]
	v_mfma_f32_16x16x32_bf16 v[48:51], v[174:177], v[182:185], v[48:51]
	v_mfma_f32_16x16x32_bf16 v[36:39], v[166:169], v[194:197], v[36:39]
	v_mfma_f32_16x16x32_bf16 v[32:35], v[174:177], v[194:197], v[32:35]
	v_mfma_f32_16x16x32_bf16 v[20:23], v[166:169], v[202:205], v[20:23]
	v_mfma_f32_16x16x32_bf16 v[16:19], v[174:177], v[202:205], v[16:19]
	v_mfma_f32_16x16x32_bf16 v[4:7], v[166:169], v[210:213], v[4:7]
	v_mfma_f32_16x16x32_bf16 v[0:3], v[174:177], v[210:213], v[0:3]
	s_barrier
	s_add_u32 s30, s30, 0x100
	s_addc_u32 s31, s31, 0
	s_add_u32 s23, s23, 0x100
	s_addc_u32 s25, s25, 0
	s_cmp_ge_i32 s54, s42
	s_mov_b32 s4, s54
	s_cbranch_scc0 .LBB0_727

.LBB0_794:
	ds_read_b128 v[166:169], v136
	ds_read_b128 v[170:173], v136 offset:1024
	ds_read_b128 v[174:177], v136 offset:2048
	ds_read_b128 v[178:181], v136 offset:3072
	ds_read_b128 v[182:185], v137
	ds_read_b128 v[190:193], v137 offset:1024
	ds_read_b128 v[194:197], v137 offset:2048
	ds_read_b128 v[198:201], v137 offset:3072
	s_add_i32 s42, s16, 2
	s_add_u32 s14, s4, 0x100
	s_addc_u32 s15, s5, 0
	s_cmp_lg_u32 s30, s16
	s_cselect_b32 s16, s14, 0
	s_cselect_b32 s17, s15, 0
	s_add_u32 s20, s6, s16
	s_addc_u32 s21, s7, s17
	s_add_u32 s16, s10, s16
	s_addc_u32 s17, s11, s17
	s_mov_b32 m0, s31
	v_lshl_add_u64 v[156:157], v[128:129], 0, s[4:5]
	ds_read_b128 v[202:205], v138
	ds_read_b128 v[206:209], v138 offset:1024
	ds_read_b128 v[210:213], v138 offset:2048
	ds_read_b128 v[214:217], v138 offset:3072
	ds_read_b128 v[218:221], v138 offset:4096
	ds_read_b128 v[222:225], v138 offset:5120
	ds_read_b128 v[226:229], v138 offset:6144
	ds_read_b128 v[230:233], v138 offset:7168
	global_load_lds_dwordx4 v[156:157], off
	v_lshl_add_u64 v[156:157], v[130:131], 0, s[4:5]
	s_mov_b32 m0, s33
	s_nop 0
	global_load_lds_dwordx4 v[156:157], off
	s_waitcnt vmcnt(8)
	s_waitcnt lgkmcnt(0)
	s_barrier
	s_waitcnt lgkmcnt(0)
	v_mfma_f32_16x16x32_bf16 v[140:143], v[166:169], v[202:205], v[140:143]
	v_mfma_f32_16x16x32_bf16 v[132:135], v[174:177], v[202:205], v[132:135]
	v_mfma_f32_16x16x32_bf16 v[108:111], v[166:169], v[210:213], v[108:111]
	v_mfma_f32_16x16x32_bf16 v[104:107], v[174:177], v[210:213], v[104:107]
	v_mfma_f32_16x16x32_bf16 v[92:95], v[166:169], v[218:221], v[92:95]
	v_mfma_f32_16x16x32_bf16 v[88:91], v[174:177], v[218:221], v[88:91]
	v_mfma_f32_16x16x32_bf16 v[76:79], v[166:169], v[226:229], v[76:79]
	v_mfma_f32_16x16x32_bf16 v[72:75], v[174:177], v[226:229], v[72:75]
	v_mfma_f32_16x16x32_bf16 v[140:143], v[170:173], v[206:209], v[140:143]
	v_mfma_f32_16x16x32_bf16 v[132:135], v[178:181], v[206:209], v[132:135]
	v_mfma_f32_16x16x32_bf16 v[108:111], v[170:173], v[214:217], v[108:111]
	v_mfma_f32_16x16x32_bf16 v[104:107], v[178:181], v[214:217], v[104:107]
	v_mfma_f32_16x16x32_bf16 v[92:95], v[170:173], v[222:225], v[92:95]
	v_mfma_f32_16x16x32_bf16 v[88:91], v[178:181], v[222:225], v[88:91]
	v_mfma_f32_16x16x32_bf16 v[76:79], v[170:173], v[230:233], v[76:79]
	v_mfma_f32_16x16x32_bf16 v[72:75], v[178:181], v[230:233], v[72:75]
	v_mfma_f32_16x16x32_bf16 v[124:127], v[182:185], v[202:205], v[124:127]
	v_mfma_f32_16x16x32_bf16 v[112:115], v[194:197], v[202:205], v[112:115]
	v_mfma_f32_16x16x32_bf16 v[100:103], v[182:185], v[210:213], v[100:103]
	v_mfma_f32_16x16x32_bf16 v[96:99], v[194:197], v[210:213], v[96:99]
	v_mfma_f32_16x16x32_bf16 v[84:87], v[182:185], v[218:221], v[84:87]
	v_mfma_f32_16x16x32_bf16 v[80:83], v[194:197], v[218:221], v[80:83]
	v_mfma_f32_16x16x32_bf16 v[68:71], v[182:185], v[226:229], v[68:71]
	v_mfma_f32_16x16x32_bf16 v[64:67], v[194:197], v[226:229], v[64:67]
	v_mfma_f32_16x16x32_bf16 v[124:127], v[190:193], v[206:209], v[124:127]
	v_mfma_f32_16x16x32_bf16 v[112:115], v[198:201], v[206:209], v[112:115]
	v_mfma_f32_16x16x32_bf16 v[100:103], v[190:193], v[214:217], v[100:103]
	v_mfma_f32_16x16x32_bf16 v[96:99], v[198:201], v[214:217], v[96:99]
	v_mfma_f32_16x16x32_bf16 v[84:87], v[190:193], v[222:225], v[84:87]
	v_mfma_f32_16x16x32_bf16 v[80:83], v[198:201], v[222:225], v[80:83]
	v_mfma_f32_16x16x32_bf16 v[68:71], v[190:193], v[230:233], v[68:71]
	v_mfma_f32_16x16x32_bf16 v[64:67], v[198:201], v[230:233], v[64:67]
	s_barrier
	s_mov_b32 m0, s34
	v_lshl_add_u64 v[156:157], s[16:17], 0, v[116:117]
	s_add_u32 s4, s16, 0x80000
	ds_read_b128 v[202:205], v138 offset:16384
	ds_read_b128 v[206:209], v138 offset:17408
	ds_read_b128 v[210:213], v138 offset:18432
	ds_read_b128 v[214:217], v138 offset:19456
	ds_read_b128 v[218:221], v138 offset:20480
	ds_read_b128 v[222:225], v138 offset:21504
	ds_read_b128 v[226:229], v138 offset:22528
	ds_read_b128 v[230:233], v138 offset:23552
	global_load_lds_dwordx4 v[156:157], off
	v_lshl_add_u64 v[186:187], s[16:17], 0, v[118:119]
	s_mov_b32 m0, s35
	s_addc_u32 s5, s17, 0
	global_load_lds_dwordx4 v[186:187], off
	v_lshl_add_u64 v[234:235], s[4:5], 0, v[116:117]
	s_mov_b32 m0, s36
	v_lshl_add_u64 v[236:237], s[20:21], 0, v[120:121]
	global_load_lds_dwordx4 v[234:235], off
	v_lshl_add_u64 v[234:235], s[4:5], 0, v[118:119]
	s_mov_b32 m0, s37
	s_nop 0
	global_load_lds_dwordx4 v[234:235], off
	v_lshl_add_u64 v[234:235], s[20:21], 0, v[122:123]
	s_mov_b32 m0, s3
	s_nop 0
	global_load_lds_dwordx4 v[234:235], off
	s_mov_b32 m0, s24
	s_nop 0
	global_load_lds_dwordx4 v[236:237], off
	s_waitcnt vmcnt(8)
	s_waitcnt lgkmcnt(0)
	s_barrier
	s_waitcnt lgkmcnt(0)
	v_mfma_f32_16x16x32_bf16 v[60:63], v[166:169], v[202:205], v[60:63]
	v_mfma_f32_16x16x32_bf16 v[56:59], v[174:177], v[202:205], v[56:59]
	v_mfma_f32_16x16x32_bf16 v[44:47], v[166:169], v[210:213], v[44:47]
	v_mfma_f32_16x16x32_bf16 v[40:43], v[174:177], v[210:213], v[40:43]
	v_mfma_f32_16x16x32_bf16 v[28:31], v[166:169], v[218:221], v[28:31]
	v_mfma_f32_16x16x32_bf16 v[24:27], v[174:177], v[218:221], v[24:27]
	v_mfma_f32_16x16x32_bf16 v[12:15], v[166:169], v[226:229], v[12:15]
	v_mfma_f32_16x16x32_bf16 v[8:11], v[174:177], v[226:229], v[8:11]
	v_mfma_f32_16x16x32_bf16 v[60:63], v[170:173], v[206:209], v[60:63]
	v_mfma_f32_16x16x32_bf16 v[56:59], v[178:181], v[206:209], v[56:59]
	v_mfma_f32_16x16x32_bf16 v[44:47], v[170:173], v[214:217], v[44:47]
	v_mfma_f32_16x16x32_bf16 v[40:43], v[178:181], v[214:217], v[40:43]
	v_mfma_f32_16x16x32_bf16 v[28:31], v[170:173], v[222:225], v[28:31]
	v_mfma_f32_16x16x32_bf16 v[24:27], v[178:181], v[222:225], v[24:27]
	v_mfma_f32_16x16x32_bf16 v[12:15], v[170:173], v[230:233], v[12:15]
	v_mfma_f32_16x16x32_bf16 v[8:11], v[178:181], v[230:233], v[8:11]
	v_mfma_f32_16x16x32_bf16 v[52:55], v[182:185], v[202:205], v[52:55]
	v_mfma_f32_16x16x32_bf16 v[48:51], v[194:197], v[202:205], v[48:51]
	v_mfma_f32_16x16x32_bf16 v[36:39], v[182:185], v[210:213], v[36:39]
	v_mfma_f32_16x16x32_bf16 v[32:35], v[194:197], v[210:213], v[32:35]
	v_mfma_f32_16x16x32_bf16 v[20:23], v[182:185], v[218:221], v[20:23]
	v_mfma_f32_16x16x32_bf16 v[16:19], v[194:197], v[218:221], v[16:19]
	v_mfma_f32_16x16x32_bf16 v[4:7], v[182:185], v[226:229], v[4:7]
	v_mfma_f32_16x16x32_bf16 v[0:3], v[194:197], v[226:229], v[0:3]
	v_mfma_f32_16x16x32_bf16 v[52:55], v[190:193], v[206:209], v[52:55]
	v_mfma_f32_16x16x32_bf16 v[48:51], v[198:201], v[206:209], v[48:51]
	v_mfma_f32_16x16x32_bf16 v[36:39], v[190:193], v[214:217], v[36:39]
	v_mfma_f32_16x16x32_bf16 v[32:35], v[198:201], v[214:217], v[32:35]
	v_mfma_f32_16x16x32_bf16 v[20:23], v[190:193], v[222:225], v[20:23]
	v_mfma_f32_16x16x32_bf16 v[16:19], v[198:201], v[222:225], v[16:19]
	v_mfma_f32_16x16x32_bf16 v[4:7], v[190:193], v[230:233], v[4:7]
	v_mfma_f32_16x16x32_bf16 v[0:3], v[198:201], v[230:233], v[0:3]
	s_barrier
	ds_read_b128 v[166:169], v139
	ds_read_b128 v[170:173], v139 offset:1024
	ds_read_b128 v[174:177], v139 offset:2048
	ds_read_b128 v[178:181], v139 offset:3072
	ds_read_b128 v[182:185], v155
	ds_read_b128 v[190:193], v155 offset:1024
	ds_read_b128 v[194:197], v155 offset:2048
	ds_read_b128 v[198:201], v155 offset:3072
	s_add_u32 s4, s20, 0x40000
	s_addc_u32 s5, s21, 0
	s_mov_b32 m0, s25
	v_lshl_add_u64 v[238:239], s[4:5], 0, v[122:123]
	ds_read_b128 v[202:205], v138 offset:32768
	ds_read_b128 v[206:209], v138 offset:33792
	ds_read_b128 v[210:213], v138 offset:34816
	ds_read_b128 v[214:217], v138 offset:35840
	ds_read_b128 v[218:221], v138 offset:36864
	ds_read_b128 v[222:225], v138 offset:37888
	ds_read_b128 v[226:229], v138 offset:38912
	ds_read_b128 v[230:233], v138 offset:39936
	global_load_lds_dwordx4 v[238:239], off
	v_lshl_add_u64 v[238:239], s[4:5], 0, v[120:121]
	s_mov_b32 m0, s26
	s_nop 0
	global_load_lds_dwordx4 v[238:239], off
	s_waitcnt vmcnt(8)
	s_waitcnt lgkmcnt(0)
	s_barrier
	s_waitcnt lgkmcnt(0)
	v_mfma_f32_16x16x32_bf16 v[140:143], v[166:169], v[202:205], v[140:143]
	v_mfma_f32_16x16x32_bf16 v[132:135], v[174:177], v[202:205], v[132:135]
	v_mfma_f32_16x16x32_bf16 v[108:111], v[166:169], v[210:213], v[108:111]
	v_mfma_f32_16x16x32_bf16 v[104:107], v[174:177], v[210:213], v[104:107]
	v_mfma_f32_16x16x32_bf16 v[92:95], v[166:169], v[218:221], v[92:95]
	v_mfma_f32_16x16x32_bf16 v[88:91], v[174:177], v[218:221], v[88:91]
	v_mfma_f32_16x16x32_bf16 v[76:79], v[166:169], v[226:229], v[76:79]
	v_mfma_f32_16x16x32_bf16 v[72:75], v[174:177], v[226:229], v[72:75]
	v_mfma_f32_16x16x32_bf16 v[140:143], v[170:173], v[206:209], v[140:143]
	v_mfma_f32_16x16x32_bf16 v[132:135], v[178:181], v[206:209], v[132:135]
	v_mfma_f32_16x16x32_bf16 v[108:111], v[170:173], v[214:217], v[108:111]
	v_mfma_f32_16x16x32_bf16 v[104:107], v[178:181], v[214:217], v[104:107]
	v_mfma_f32_16x16x32_bf16 v[92:95], v[170:173], v[222:225], v[92:95]
	v_mfma_f32_16x16x32_bf16 v[88:91], v[178:181], v[222:225], v[88:91]
	v_mfma_f32_16x16x32_bf16 v[76:79], v[170:173], v[230:233], v[76:79]
	v_mfma_f32_16x16x32_bf16 v[72:75], v[178:181], v[230:233], v[72:75]
	v_mfma_f32_16x16x32_bf16 v[124:127], v[182:185], v[202:205], v[124:127]
	v_mfma_f32_16x16x32_bf16 v[112:115], v[194:197], v[202:205], v[112:115]
	v_mfma_f32_16x16x32_bf16 v[100:103], v[182:185], v[210:213], v[100:103]
	v_mfma_f32_16x16x32_bf16 v[96:99], v[194:197], v[210:213], v[96:99]
	v_mfma_f32_16x16x32_bf16 v[84:87], v[182:185], v[218:221], v[84:87]
	v_mfma_f32_16x16x32_bf16 v[80:83], v[194:197], v[218:221], v[80:83]
	v_mfma_f32_16x16x32_bf16 v[68:71], v[182:185], v[226:229], v[68:71]
	v_mfma_f32_16x16x32_bf16 v[64:67], v[194:197], v[226:229], v[64:67]
	v_mfma_f32_16x16x32_bf16 v[124:127], v[190:193], v[206:209], v[124:127]
	v_mfma_f32_16x16x32_bf16 v[112:115], v[198:201], v[206:209], v[112:115]
	v_mfma_f32_16x16x32_bf16 v[100:103], v[190:193], v[214:217], v[100:103]
	v_mfma_f32_16x16x32_bf16 v[96:99], v[198:201], v[214:217], v[96:99]
	v_mfma_f32_16x16x32_bf16 v[84:87], v[190:193], v[222:225], v[84:87]
	v_mfma_f32_16x16x32_bf16 v[80:83], v[198:201], v[222:225], v[80:83]
	v_mfma_f32_16x16x32_bf16 v[68:71], v[190:193], v[230:233], v[68:71]
	v_mfma_f32_16x16x32_bf16 v[64:67], v[198:201], v[230:233], v[64:67]
	s_barrier
	s_mov_b32 m0, s38
	v_lshl_add_u64 v[156:157], v[156:157], 0, s[12:13]
	s_add_u32 s4, s16, 0x80080
	ds_read_b128 v[202:205], v138 offset:49152
	ds_read_b128 v[206:209], v138 offset:50176
	ds_read_b128 v[210:213], v138 offset:51200
	ds_read_b128 v[214:217], v138 offset:52224
	ds_read_b128 v[218:221], v138 offset:53248
	ds_read_b128 v[222:225], v138 offset:54272
	ds_read_b128 v[226:229], v138 offset:55296
	ds_read_b128 v[230:233], v138 offset:56320
	global_load_lds_dwordx4 v[156:157], off
	v_lshl_add_u64 v[156:157], v[186:187], 0, s[12:13]
	s_mov_b32 m0, s39
	s_addc_u32 s5, s17, 0
	global_load_lds_dwordx4 v[156:157], off
	v_lshl_add_u64 v[156:157], s[4:5], 0, v[116:117]
	s_mov_b32 m0, s40
	s_nop 0
	global_load_lds_dwordx4 v[156:157], off
	v_lshl_add_u64 v[156:157], s[4:5], 0, v[118:119]
	s_mov_b32 m0, s41
	s_nop 0
	global_load_lds_dwordx4 v[156:157], off
	v_lshl_add_u64 v[156:157], v[234:235], 0, s[12:13]
	s_mov_b32 m0, s27
	s_nop 0
	global_load_lds_dwordx4 v[156:157], off
	v_lshl_add_u64 v[156:157], v[236:237], 0, s[12:13]
	s_mov_b32 m0, s28
	s_nop 0
	global_load_lds_dwordx4 v[156:157], off
	s_waitcnt vmcnt(8)
	s_waitcnt lgkmcnt(0)
	s_barrier
	s_waitcnt lgkmcnt(0)
	v_mfma_f32_16x16x32_bf16 v[60:63], v[166:169], v[202:205], v[60:63]
	v_mfma_f32_16x16x32_bf16 v[56:59], v[174:177], v[202:205], v[56:59]
	v_mfma_f32_16x16x32_bf16 v[44:47], v[166:169], v[210:213], v[44:47]
	v_mfma_f32_16x16x32_bf16 v[40:43], v[174:177], v[210:213], v[40:43]
	v_mfma_f32_16x16x32_bf16 v[28:31], v[166:169], v[218:221], v[28:31]
	v_mfma_f32_16x16x32_bf16 v[24:27], v[174:177], v[218:221], v[24:27]
	v_mfma_f32_16x16x32_bf16 v[12:15], v[166:169], v[226:229], v[12:15]
	v_mfma_f32_16x16x32_bf16 v[8:11], v[174:177], v[226:229], v[8:11]
	v_mfma_f32_16x16x32_bf16 v[60:63], v[170:173], v[206:209], v[60:63]
	v_mfma_f32_16x16x32_bf16 v[56:59], v[178:181], v[206:209], v[56:59]
	v_mfma_f32_16x16x32_bf16 v[44:47], v[170:173], v[214:217], v[44:47]
	v_mfma_f32_16x16x32_bf16 v[40:43], v[178:181], v[214:217], v[40:43]
	v_mfma_f32_16x16x32_bf16 v[28:31], v[170:173], v[222:225], v[28:31]
	v_mfma_f32_16x16x32_bf16 v[24:27], v[178:181], v[222:225], v[24:27]
	v_mfma_f32_16x16x32_bf16 v[12:15], v[170:173], v[230:233], v[12:15]
	v_mfma_f32_16x16x32_bf16 v[8:11], v[178:181], v[230:233], v[8:11]
	v_mfma_f32_16x16x32_bf16 v[52:55], v[182:185], v[202:205], v[52:55]
	v_mfma_f32_16x16x32_bf16 v[48:51], v[194:197], v[202:205], v[48:51]
	v_mfma_f32_16x16x32_bf16 v[36:39], v[182:185], v[210:213], v[36:39]
	v_mfma_f32_16x16x32_bf16 v[32:35], v[194:197], v[210:213], v[32:35]
	v_mfma_f32_16x16x32_bf16 v[20:23], v[182:185], v[218:221], v[20:23]
	v_mfma_f32_16x16x32_bf16 v[16:19], v[194:197], v[218:221], v[16:19]
	v_mfma_f32_16x16x32_bf16 v[4:7], v[182:185], v[226:229], v[4:7]
	v_mfma_f32_16x16x32_bf16 v[0:3], v[194:197], v[226:229], v[0:3]
	v_mfma_f32_16x16x32_bf16 v[52:55], v[190:193], v[206:209], v[52:55]
	v_mfma_f32_16x16x32_bf16 v[48:51], v[198:201], v[206:209], v[48:51]
	v_mfma_f32_16x16x32_bf16 v[36:39], v[190:193], v[214:217], v[36:39]
	v_mfma_f32_16x16x32_bf16 v[32:35], v[198:201], v[214:217], v[32:35]
	v_mfma_f32_16x16x32_bf16 v[20:23], v[190:193], v[222:225], v[20:23]
	v_mfma_f32_16x16x32_bf16 v[16:19], v[198:201], v[222:225], v[16:19]
	v_mfma_f32_16x16x32_bf16 v[4:7], v[190:193], v[230:233], v[4:7]
	v_mfma_f32_16x16x32_bf16 v[0:3], v[198:201], v[230:233], v[0:3]
	s_barrier
	s_cmp_ge_i32 s42, s29
	s_mov_b64 s[4:5], s[14:15]
	s_mov_b32 s16, s42
	s_cbranch_scc0 .LBB0_794
	v_mov_b32_e32 v117, v143

.LBB0_802:
	ds_read_b128 v[74:77], v68
	ds_read_b128 v[156:159], v68 offset:1024
	ds_read_b128 v[164:167], v68 offset:2048
	ds_read_b128 v[168:171], v68 offset:3072
	ds_read_b128 v[172:175], v69
	ds_read_b128 v[176:179], v69 offset:1024
	ds_read_b128 v[180:183], v69 offset:2048
	ds_read_b128 v[184:187], v69 offset:3072
	s_add_i32 s39, s4, 2
	s_add_u32 s5, s12, 0xffff0080
	s_addc_u32 s14, s13, -1
	s_cmp_lg_u32 s27, s4
	s_cselect_b32 s4, s5, 0
	s_cselect_b32 s40, s14, 0
	s_add_u32 s14, s6, s4
	s_addc_u32 s15, s7, s40
	s_add_u32 s4, s8, s4
	s_addc_u32 s5, s9, s40
	s_mov_b32 m0, s28
	v_lshl_add_u64 v[78:79], v[64:65], 0, s[12:13]
	ds_read_b128 v[190:193], v70
	ds_read_b128 v[194:197], v70 offset:1024
	ds_read_b128 v[198:201], v70 offset:2048
	ds_read_b128 v[202:205], v70 offset:3072
	ds_read_b128 v[206:209], v70 offset:4096
	ds_read_b128 v[210:213], v70 offset:5120
	ds_read_b128 v[214:217], v70 offset:6144
	ds_read_b128 v[218:221], v70 offset:7168
	global_load_lds_dwordx4 v[78:79], off
	v_lshl_add_u64 v[78:79], v[66:67], 0, s[12:13]
	s_mov_b32 m0, s29
	s_nop 0
	global_load_lds_dwordx4 v[78:79], off
	s_waitcnt vmcnt(8)
	s_waitcnt lgkmcnt(0)
	s_barrier
	s_waitcnt lgkmcnt(0)
	v_mfma_f32_16x16x32_bf16 v[140:143], v[74:77], v[190:193], v[140:143]
	v_mfma_f32_16x16x32_bf16 v[128:131], v[164:167], v[190:193], v[128:131]
	v_mfma_f32_16x16x32_bf16 v[124:127], v[74:77], v[198:201], v[124:127]
	v_mfma_f32_16x16x32_bf16 v[112:115], v[164:167], v[198:201], v[112:115]
	v_mfma_f32_16x16x32_bf16 v[108:111], v[74:77], v[206:209], v[108:111]
	v_mfma_f32_16x16x32_bf16 v[96:99], v[164:167], v[206:209], v[96:99]
	v_mfma_f32_16x16x32_bf16 v[92:95], v[74:77], v[214:217], v[92:95]
	v_mfma_f32_16x16x32_bf16 v[78:81], v[164:167], v[214:217], v[80:83]
	v_mfma_f32_16x16x32_bf16 v[140:143], v[156:159], v[194:197], v[140:143]
	v_mfma_f32_16x16x32_bf16 v[128:131], v[168:171], v[194:197], v[128:131]
	v_mfma_f32_16x16x32_bf16 v[124:127], v[156:159], v[202:205], v[124:127]
	v_mfma_f32_16x16x32_bf16 v[112:115], v[168:171], v[202:205], v[112:115]
	v_mfma_f32_16x16x32_bf16 v[108:111], v[156:159], v[210:213], v[108:111]
	v_mfma_f32_16x16x32_bf16 v[96:99], v[168:171], v[210:213], v[96:99]
	v_mfma_f32_16x16x32_bf16 v[92:95], v[156:159], v[218:221], v[92:95]
	v_mfma_f32_16x16x32_bf16 v[78:81], v[168:171], v[218:221], v[78:81]
	v_mfma_f32_16x16x32_bf16 v[136:139], v[172:175], v[190:193], v[136:139]
	v_mfma_f32_16x16x32_bf16 v[132:135], v[180:183], v[190:193], v[132:135]
	v_mfma_f32_16x16x32_bf16 v[120:123], v[172:175], v[198:201], v[120:123]
	v_mfma_f32_16x16x32_bf16 v[116:119], v[180:183], v[198:201], v[116:119]
	v_mfma_f32_16x16x32_bf16 v[104:107], v[172:175], v[206:209], v[104:107]
	v_mfma_f32_16x16x32_bf16 v[100:103], v[180:183], v[206:209], v[100:103]
	v_mfma_f32_16x16x32_bf16 v[88:91], v[172:175], v[214:217], v[88:91]
	v_mfma_f32_16x16x32_bf16 v[82:85], v[180:183], v[214:217], v[84:87]
	v_mfma_f32_16x16x32_bf16 v[136:139], v[176:179], v[194:197], v[136:139]
	v_mfma_f32_16x16x32_bf16 v[132:135], v[184:187], v[194:197], v[132:135]
	v_mfma_f32_16x16x32_bf16 v[120:123], v[176:179], v[202:205], v[120:123]
	v_mfma_f32_16x16x32_bf16 v[116:119], v[184:187], v[202:205], v[116:119]
	v_mfma_f32_16x16x32_bf16 v[104:107], v[176:179], v[210:213], v[104:107]
	v_mfma_f32_16x16x32_bf16 v[100:103], v[184:187], v[210:213], v[100:103]
	v_mfma_f32_16x16x32_bf16 v[88:91], v[176:179], v[218:221], v[88:91]
	v_mfma_f32_16x16x32_bf16 v[84:87], v[184:187], v[218:221], v[82:85]
	s_barrier
	s_mov_b32 m0, s30
	v_lshl_add_u64 v[160:161], s[4:5], 0, v[154:155]
	s_add_u32 s40, s4, 0x10000
	ds_read_b128 v[190:193], v70 offset:16384
	ds_read_b128 v[194:197], v70 offset:17408
	ds_read_b128 v[198:201], v70 offset:18432
	ds_read_b128 v[202:205], v70 offset:19456
	ds_read_b128 v[206:209], v70 offset:20480
	ds_read_b128 v[210:213], v70 offset:21504
	ds_read_b128 v[214:217], v70 offset:22528
	ds_read_b128 v[218:221], v70 offset:23552
	global_load_lds_dwordx4 v[160:161], off
	v_lshl_add_u64 v[222:223], s[4:5], 0, v[144:145]
	s_mov_b32 m0, s31
	s_addc_u32 s41, s5, 0
	global_load_lds_dwordx4 v[222:223], off
	v_lshl_add_u64 v[82:83], s[40:41], 0, v[154:155]
	s_mov_b32 m0, s33
	v_lshl_add_u64 v[224:225], s[14:15], 0, v[154:155]
	global_load_lds_dwordx4 v[82:83], off
	v_lshl_add_u64 v[82:83], s[40:41], 0, v[144:145]
	s_mov_b32 m0, s34
	v_lshl_add_u64 v[226:227], s[14:15], 0, v[144:145]
	global_load_lds_dwordx4 v[82:83], off
	s_mov_b32 m0, s21
	s_nop 0
	global_load_lds_dwordx4 v[224:225], off
	s_mov_b32 m0, s22
	s_nop 0
	global_load_lds_dwordx4 v[226:227], off
	s_waitcnt vmcnt(8)
	s_waitcnt lgkmcnt(0)
	s_barrier
	s_waitcnt lgkmcnt(0)
	v_mfma_f32_16x16x32_bf16 v[60:63], v[74:77], v[190:193], v[60:63]
	v_mfma_f32_16x16x32_bf16 v[48:51], v[164:167], v[190:193], v[48:51]
	v_mfma_f32_16x16x32_bf16 v[44:47], v[74:77], v[198:201], v[44:47]
	v_mfma_f32_16x16x32_bf16 v[32:35], v[164:167], v[198:201], v[32:35]
	v_mfma_f32_16x16x32_bf16 v[28:31], v[74:77], v[206:209], v[28:31]
	v_mfma_f32_16x16x32_bf16 v[16:19], v[164:167], v[206:209], v[16:19]
	v_mfma_f32_16x16x32_bf16 v[12:15], v[74:77], v[214:217], v[12:15]
	v_mfma_f32_16x16x32_bf16 v[4:7], v[164:167], v[214:217], v[4:7]
	v_mfma_f32_16x16x32_bf16 v[60:63], v[156:159], v[194:197], v[60:63]
	v_mfma_f32_16x16x32_bf16 v[48:51], v[168:171], v[194:197], v[48:51]
	v_mfma_f32_16x16x32_bf16 v[44:47], v[156:159], v[202:205], v[44:47]
	v_mfma_f32_16x16x32_bf16 v[32:35], v[168:171], v[202:205], v[32:35]
	v_mfma_f32_16x16x32_bf16 v[28:31], v[156:159], v[210:213], v[28:31]
	v_mfma_f32_16x16x32_bf16 v[16:19], v[168:171], v[210:213], v[16:19]
	v_mfma_f32_16x16x32_bf16 v[12:15], v[156:159], v[218:221], v[12:15]
	v_mfma_f32_16x16x32_bf16 v[4:7], v[168:171], v[218:221], v[4:7]
	v_mfma_f32_16x16x32_bf16 v[56:59], v[172:175], v[190:193], v[56:59]
	v_mfma_f32_16x16x32_bf16 v[52:55], v[180:183], v[190:193], v[52:55]
	v_mfma_f32_16x16x32_bf16 v[40:43], v[172:175], v[198:201], v[40:43]
	v_mfma_f32_16x16x32_bf16 v[36:39], v[180:183], v[198:201], v[36:39]
	v_mfma_f32_16x16x32_bf16 v[24:27], v[172:175], v[206:209], v[24:27]
	v_mfma_f32_16x16x32_bf16 v[20:23], v[180:183], v[206:209], v[20:23]
	v_mfma_f32_16x16x32_bf16 v[8:11], v[172:175], v[214:217], v[8:11]
	v_mfma_f32_16x16x32_bf16 v[0:3], v[180:183], v[214:217], v[0:3]
	v_mfma_f32_16x16x32_bf16 v[56:59], v[176:179], v[194:197], v[56:59]
	v_mfma_f32_16x16x32_bf16 v[52:55], v[184:187], v[194:197], v[52:55]
	v_mfma_f32_16x16x32_bf16 v[40:43], v[176:179], v[202:205], v[40:43]
	v_mfma_f32_16x16x32_bf16 v[36:39], v[184:187], v[202:205], v[36:39]
	v_mfma_f32_16x16x32_bf16 v[24:27], v[176:179], v[210:213], v[24:27]
	v_mfma_f32_16x16x32_bf16 v[20:23], v[184:187], v[210:213], v[20:23]
	v_mfma_f32_16x16x32_bf16 v[8:11], v[176:179], v[218:221], v[8:11]
	v_mfma_f32_16x16x32_bf16 v[0:3], v[184:187], v[218:221], v[0:3]
	s_barrier
	ds_read_b128 v[74:77], v71
	ds_read_b128 v[156:159], v71 offset:1024
	ds_read_b128 v[164:167], v71 offset:2048
	ds_read_b128 v[168:171], v71 offset:3072
	ds_read_b128 v[172:175], v72
	ds_read_b128 v[176:179], v72 offset:1024
	ds_read_b128 v[180:183], v72 offset:2048
	ds_read_b128 v[184:187], v72 offset:3072
	s_add_u32 s14, s14, 0x10000
	s_addc_u32 s15, s15, 0
	s_mov_b32 m0, s23
	v_lshl_add_u64 v[82:83], s[14:15], 0, v[154:155]
	ds_read_b128 v[190:193], v70 offset:32768
	ds_read_b128 v[194:197], v70 offset:33792
	ds_read_b128 v[198:201], v70 offset:34816
	ds_read_b128 v[202:205], v70 offset:35840
	ds_read_b128 v[206:209], v70 offset:36864
	ds_read_b128 v[210:213], v70 offset:37888
	ds_read_b128 v[214:217], v70 offset:38912
	ds_read_b128 v[218:221], v70 offset:39936
	global_load_lds_dwordx4 v[82:83], off
	v_lshl_add_u64 v[82:83], s[14:15], 0, v[144:145]
	s_mov_b32 m0, s24
	s_nop 0
	global_load_lds_dwordx4 v[82:83], off
	s_waitcnt vmcnt(8)
	s_waitcnt lgkmcnt(0)
	s_barrier
	s_waitcnt lgkmcnt(0)
	v_mfma_f32_16x16x32_bf16 v[140:143], v[74:77], v[190:193], v[140:143]
	v_mfma_f32_16x16x32_bf16 v[128:131], v[164:167], v[190:193], v[128:131]
	v_mfma_f32_16x16x32_bf16 v[124:127], v[74:77], v[198:201], v[124:127]
	v_mfma_f32_16x16x32_bf16 v[112:115], v[164:167], v[198:201], v[112:115]
	v_mfma_f32_16x16x32_bf16 v[108:111], v[74:77], v[206:209], v[108:111]
	v_mfma_f32_16x16x32_bf16 v[96:99], v[164:167], v[206:209], v[96:99]
	v_mfma_f32_16x16x32_bf16 v[92:95], v[74:77], v[214:217], v[92:95]
	v_mfma_f32_16x16x32_bf16 v[78:81], v[164:167], v[214:217], v[78:81]
	v_mfma_f32_16x16x32_bf16 v[140:143], v[156:159], v[194:197], v[140:143]
	v_mfma_f32_16x16x32_bf16 v[128:131], v[168:171], v[194:197], v[128:131]
	v_mfma_f32_16x16x32_bf16 v[124:127], v[156:159], v[202:205], v[124:127]
	v_mfma_f32_16x16x32_bf16 v[112:115], v[168:171], v[202:205], v[112:115]
	v_mfma_f32_16x16x32_bf16 v[108:111], v[156:159], v[210:213], v[108:111]
	v_mfma_f32_16x16x32_bf16 v[96:99], v[168:171], v[210:213], v[96:99]
	v_mfma_f32_16x16x32_bf16 v[92:95], v[156:159], v[218:221], v[92:95]
	v_mfma_f32_16x16x32_bf16 v[80:83], v[168:171], v[218:221], v[78:81]
	v_mfma_f32_16x16x32_bf16 v[136:139], v[172:175], v[190:193], v[136:139]
	v_mfma_f32_16x16x32_bf16 v[132:135], v[180:183], v[190:193], v[132:135]
	v_mfma_f32_16x16x32_bf16 v[120:123], v[172:175], v[198:201], v[120:123]
	v_mfma_f32_16x16x32_bf16 v[116:119], v[180:183], v[198:201], v[116:119]
	v_mfma_f32_16x16x32_bf16 v[104:107], v[172:175], v[206:209], v[104:107]
	v_mfma_f32_16x16x32_bf16 v[100:103], v[180:183], v[206:209], v[100:103]
	v_mfma_f32_16x16x32_bf16 v[88:91], v[172:175], v[214:217], v[88:91]
	v_mfma_f32_16x16x32_bf16 v[84:87], v[180:183], v[214:217], v[84:87]
	v_mfma_f32_16x16x32_bf16 v[136:139], v[176:179], v[194:197], v[136:139]
	v_mfma_f32_16x16x32_bf16 v[132:135], v[184:187], v[194:197], v[132:135]
	v_mfma_f32_16x16x32_bf16 v[120:123], v[176:179], v[202:205], v[120:123]
	v_mfma_f32_16x16x32_bf16 v[116:119], v[184:187], v[202:205], v[116:119]
	v_mfma_f32_16x16x32_bf16 v[104:107], v[176:179], v[210:213], v[104:107]
	v_mfma_f32_16x16x32_bf16 v[100:103], v[184:187], v[210:213], v[100:103]
	v_mfma_f32_16x16x32_bf16 v[88:91], v[176:179], v[218:221], v[88:91]
	v_mfma_f32_16x16x32_bf16 v[84:87], v[184:187], v[218:221], v[84:87]
	s_barrier
	s_mov_b32 m0, s35
	v_lshl_add_u64 v[78:79], v[160:161], 0, s[10:11]
	s_add_u32 s4, s4, 0x10080
	ds_read_b128 v[190:193], v70 offset:49152
	ds_read_b128 v[194:197], v70 offset:50176
	ds_read_b128 v[198:201], v70 offset:51200
	ds_read_b128 v[202:205], v70 offset:52224
	ds_read_b128 v[206:209], v70 offset:53248
	ds_read_b128 v[210:213], v70 offset:54272
	ds_read_b128 v[214:217], v70 offset:55296
	ds_read_b128 v[218:221], v70 offset:56320
	global_load_lds_dwordx4 v[78:79], off
	v_lshl_add_u64 v[78:79], v[222:223], 0, s[10:11]
	s_mov_b32 m0, s36
	s_addc_u32 s5, s5, 0
	global_load_lds_dwordx4 v[78:79], off
	v_lshl_add_u64 v[78:79], s[4:5], 0, v[154:155]
	s_mov_b32 m0, s37
	s_nop 0
	global_load_lds_dwordx4 v[78:79], off
	v_lshl_add_u64 v[78:79], s[4:5], 0, v[144:145]
	s_mov_b32 m0, s38
	s_nop 0
	global_load_lds_dwordx4 v[78:79], off
	v_lshl_add_u64 v[78:79], v[224:225], 0, s[10:11]
	s_mov_b32 m0, s25
	s_nop 0
	global_load_lds_dwordx4 v[78:79], off
	v_lshl_add_u64 v[78:79], v[226:227], 0, s[10:11]
	s_mov_b32 m0, s26
	s_nop 0
	global_load_lds_dwordx4 v[78:79], off
	s_waitcnt vmcnt(8)
	s_waitcnt lgkmcnt(0)
	s_barrier
	s_waitcnt lgkmcnt(0)
	v_mfma_f32_16x16x32_bf16 v[60:63], v[74:77], v[190:193], v[60:63]
	v_mfma_f32_16x16x32_bf16 v[48:51], v[164:167], v[190:193], v[48:51]
	v_mfma_f32_16x16x32_bf16 v[44:47], v[74:77], v[198:201], v[44:47]
	v_mfma_f32_16x16x32_bf16 v[32:35], v[164:167], v[198:201], v[32:35]
	v_mfma_f32_16x16x32_bf16 v[28:31], v[74:77], v[206:209], v[28:31]
	v_mfma_f32_16x16x32_bf16 v[16:19], v[164:167], v[206:209], v[16:19]
	v_mfma_f32_16x16x32_bf16 v[12:15], v[74:77], v[214:217], v[12:15]
	v_mfma_f32_16x16x32_bf16 v[4:7], v[164:167], v[214:217], v[4:7]
	v_mfma_f32_16x16x32_bf16 v[60:63], v[156:159], v[194:197], v[60:63]
	v_mfma_f32_16x16x32_bf16 v[48:51], v[168:171], v[194:197], v[48:51]
	v_mfma_f32_16x16x32_bf16 v[44:47], v[156:159], v[202:205], v[44:47]
	v_mfma_f32_16x16x32_bf16 v[32:35], v[168:171], v[202:205], v[32:35]
	v_mfma_f32_16x16x32_bf16 v[28:31], v[156:159], v[210:213], v[28:31]
	v_mfma_f32_16x16x32_bf16 v[16:19], v[168:171], v[210:213], v[16:19]
	v_mfma_f32_16x16x32_bf16 v[12:15], v[156:159], v[218:221], v[12:15]
	v_mfma_f32_16x16x32_bf16 v[4:7], v[168:171], v[218:221], v[4:7]
	v_mfma_f32_16x16x32_bf16 v[56:59], v[172:175], v[190:193], v[56:59]
	v_mfma_f32_16x16x32_bf16 v[52:55], v[180:183], v[190:193], v[52:55]
	v_mfma_f32_16x16x32_bf16 v[40:43], v[172:175], v[198:201], v[40:43]
	v_mfma_f32_16x16x32_bf16 v[36:39], v[180:183], v[198:201], v[36:39]
	v_mfma_f32_16x16x32_bf16 v[24:27], v[172:175], v[206:209], v[24:27]
	v_mfma_f32_16x16x32_bf16 v[20:23], v[180:183], v[206:209], v[20:23]
	v_mfma_f32_16x16x32_bf16 v[8:11], v[172:175], v[214:217], v[8:11]
	v_mfma_f32_16x16x32_bf16 v[0:3], v[180:183], v[214:217], v[0:3]
	v_mfma_f32_16x16x32_bf16 v[56:59], v[176:179], v[194:197], v[56:59]
	v_mfma_f32_16x16x32_bf16 v[52:55], v[184:187], v[194:197], v[52:55]
	v_mfma_f32_16x16x32_bf16 v[40:43], v[176:179], v[202:205], v[40:43]
	v_mfma_f32_16x16x32_bf16 v[36:39], v[184:187], v[202:205], v[36:39]
	v_mfma_f32_16x16x32_bf16 v[24:27], v[176:179], v[210:213], v[24:27]
	v_mfma_f32_16x16x32_bf16 v[20:23], v[184:187], v[210:213], v[20:23]
	v_mfma_f32_16x16x32_bf16 v[8:11], v[176:179], v[218:221], v[8:11]
	v_mfma_f32_16x16x32_bf16 v[0:3], v[184:187], v[218:221], v[0:3]
	s_barrier
	s_add_u32 s12, s12, 0x100
	s_addc_u32 s13, s13, 0
	s_cmp_ge_i32 s39, s3
	s_mov_b32 s4, s39
	s_cbranch_scc0 .LBB0_802
	v_mov_b32_e32 v155, v143
	s_cmpk_lt_u32 s16, 0x100
	s_cbranch_scc1 .LBB0_806

.LBB0_1264:
	s_andn2_b64 vcc, exec, s[14:15]
	s_cbranch_vccnz .Lpz_zero_2
	s_add_u32 s30, s30, 0x20080
	s_addc_u32 s31, s31, 0
	s_add_u32 s21, s4, 0x100
	s_addc_u32 s23, s5, 0
	s_mov_b32 s4, 0
	ds_read_b128 v[138:141], v152
	ds_read_b128 v[142:145], v152 offset:1024
	ds_read_b128 v[156:159], v152 offset:2048
	ds_read_b128 v[160:163], v152 offset:3072
	ds_read_b128 v[164:167], v153
	ds_read_b128 v[168:171], v153 offset:1024
	ds_read_b128 v[172:175], v153 offset:2048
	ds_read_b128 v[176:179], v153 offset:3072
	s_add_i32 s58, s4, 2
	s_add_u32 s5, s30, 0xfffe0080
	s_addc_u32 s34, s31, -1
	s_cmp_eq_u32 s48, s4
	s_cselect_b32 s4, s26, s21
	s_cselect_b32 s35, s25, s34
	s_cselect_b32 s34, s24, s5
	s_cselect_b32 s5, s27, s23
	v_lshl_add_u64 v[214:215], s[30:31], 0, v[132:133]
	s_add_i32 m0, s37, 0xc000
	ds_read_b128 v[180:183], v154
	ds_read_b128 v[184:187], v154 offset:1024
	ds_read_b128 v[190:193], v154 offset:2048
	ds_read_b128 v[194:197], v154 offset:3072
	ds_read_b128 v[198:201], v154 offset:4096
	ds_read_b128 v[202:205], v154 offset:5120
	ds_read_b128 v[206:209], v154 offset:6144
	ds_read_b128 v[210:213], v154 offset:7168
	global_load_lds_dwordx4 v[214:215], off
	v_lshl_add_u64 v[214:215], s[30:31], 0, v[134:135]
	s_add_i32 m0, s37, 0xe000
	s_nop 0
	global_load_lds_dwordx4 v[214:215], off
	s_waitcnt vmcnt(8)
	s_waitcnt lgkmcnt(0)
	s_barrier
	s_waitcnt lgkmcnt(0)
	v_mfma_f32_16x16x32_bf16 v[120:123], v[138:141], v[180:183], 0
	v_mfma_f32_16x16x32_bf16 v[124:127], v[156:159], v[180:183], 0
	v_mfma_f32_16x16x32_bf16 v[108:111], v[138:141], v[190:193], 0
	v_mfma_f32_16x16x32_bf16 v[104:107], v[156:159], v[190:193], 0
	v_mfma_f32_16x16x32_bf16 v[92:95], v[138:141], v[198:201], 0
	v_mfma_f32_16x16x32_bf16 v[88:91], v[156:159], v[198:201], 0
	v_mfma_f32_16x16x32_bf16 v[76:79], v[138:141], v[206:209], 0
	v_mfma_f32_16x16x32_bf16 v[72:75], v[156:159], v[206:209], 0
	v_mfma_f32_16x16x32_bf16 v[120:123], v[142:145], v[184:187], v[120:123]
	v_mfma_f32_16x16x32_bf16 v[124:127], v[160:163], v[184:187], v[124:127]
	v_mfma_f32_16x16x32_bf16 v[108:111], v[142:145], v[194:197], v[108:111]
	v_mfma_f32_16x16x32_bf16 v[104:107], v[160:163], v[194:197], v[104:107]
	v_mfma_f32_16x16x32_bf16 v[92:95], v[142:145], v[202:205], v[92:95]
	v_mfma_f32_16x16x32_bf16 v[88:91], v[160:163], v[202:205], v[88:91]
	v_mfma_f32_16x16x32_bf16 v[76:79], v[142:145], v[210:213], v[76:79]
	v_mfma_f32_16x16x32_bf16 v[72:75], v[160:163], v[210:213], v[72:75]
	v_mfma_f32_16x16x32_bf16 v[116:119], v[164:167], v[180:183], 0
	v_mfma_f32_16x16x32_bf16 v[112:115], v[172:175], v[180:183], 0
	v_mfma_f32_16x16x32_bf16 v[100:103], v[164:167], v[190:193], 0
	v_mfma_f32_16x16x32_bf16 v[96:99], v[172:175], v[190:193], 0
	v_mfma_f32_16x16x32_bf16 v[84:87], v[164:167], v[198:201], 0
	v_mfma_f32_16x16x32_bf16 v[80:83], v[172:175], v[198:201], 0
	v_mfma_f32_16x16x32_bf16 v[68:71], v[164:167], v[206:209], 0
	v_mfma_f32_16x16x32_bf16 v[64:67], v[172:175], v[206:209], 0
	v_mfma_f32_16x16x32_bf16 v[116:119], v[168:171], v[184:187], v[116:119]
	v_mfma_f32_16x16x32_bf16 v[112:115], v[176:179], v[184:187], v[112:115]
	v_mfma_f32_16x16x32_bf16 v[100:103], v[168:171], v[194:197], v[100:103]
	v_mfma_f32_16x16x32_bf16 v[96:99], v[176:179], v[194:197], v[96:99]
	v_mfma_f32_16x16x32_bf16 v[84:87], v[168:171], v[202:205], v[84:87]
	v_mfma_f32_16x16x32_bf16 v[80:83], v[176:179], v[202:205], v[80:83]
	v_mfma_f32_16x16x32_bf16 v[68:71], v[168:171], v[210:213], v[68:71]
	v_mfma_f32_16x16x32_bf16 v[64:67], v[176:179], v[210:213], v[64:67]
	s_barrier
	s_add_i32 s59, s52, s29
	v_lshl_add_u64 v[214:215], s[4:5], 0, v[128:129]
	s_mov_b32 m0, s59
	ds_read_b128 v[180:183], v154 offset:16384
	ds_read_b128 v[184:187], v154 offset:17408
	ds_read_b128 v[190:193], v154 offset:18432
	ds_read_b128 v[194:197], v154 offset:19456
	ds_read_b128 v[198:201], v154 offset:20480
	ds_read_b128 v[202:205], v154 offset:21504
	ds_read_b128 v[206:209], v154 offset:22528
	ds_read_b128 v[210:213], v154 offset:23552
	global_load_lds_dwordx4 v[214:215], off
	s_add_i32 m0, s59, 0x2000
	s_add_u32 s60, s4, 0x20000
	v_lshl_add_u64 v[216:217], s[4:5], 0, v[130:131]
	s_addc_u32 s61, s5, 0
	s_add_i32 s59, s53, s29
	global_load_lds_dwordx4 v[216:217], off
	v_lshl_add_u64 v[218:219], s[60:61], 0, v[128:129]
	s_mov_b32 m0, s59
	v_lshl_add_u64 v[220:221], s[34:35], 0, v[130:131]
	global_load_lds_dwordx4 v[218:219], off
	v_lshl_add_u64 v[218:219], s[60:61], 0, v[130:131]
	s_add_i32 m0, s59, 0x2000
	s_nop 0
	global_load_lds_dwordx4 v[218:219], off
	v_lshl_add_u64 v[218:219], s[34:35], 0, v[128:129]
	s_mov_b32 m0, s37
	s_nop 0
	global_load_lds_dwordx4 v[218:219], off
	s_mov_b32 m0, s38
	s_nop 0
	global_load_lds_dwordx4 v[220:221], off
	s_waitcnt vmcnt(8)
	s_waitcnt lgkmcnt(0)
	s_barrier
	s_waitcnt lgkmcnt(0)
	v_mfma_f32_16x16x32_bf16 v[60:63], v[138:141], v[180:183], 0
	v_mfma_f32_16x16x32_bf16 v[56:59], v[156:159], v[180:183], 0
	v_mfma_f32_16x16x32_bf16 v[44:47], v[138:141], v[190:193], 0
	v_mfma_f32_16x16x32_bf16 v[40:43], v[156:159], v[190:193], 0
	v_mfma_f32_16x16x32_bf16 v[28:31], v[138:141], v[198:201], 0
	v_mfma_f32_16x16x32_bf16 v[24:27], v[156:159], v[198:201], 0
	v_mfma_f32_16x16x32_bf16 v[12:15], v[138:141], v[206:209], 0
	v_mfma_f32_16x16x32_bf16 v[8:11], v[156:159], v[206:209], 0
	v_mfma_f32_16x16x32_bf16 v[60:63], v[142:145], v[184:187], v[60:63]
	v_mfma_f32_16x16x32_bf16 v[56:59], v[160:163], v[184:187], v[56:59]
	v_mfma_f32_16x16x32_bf16 v[44:47], v[142:145], v[194:197], v[44:47]
	v_mfma_f32_16x16x32_bf16 v[40:43], v[160:163], v[194:197], v[40:43]
	v_mfma_f32_16x16x32_bf16 v[28:31], v[142:145], v[202:205], v[28:31]
	v_mfma_f32_16x16x32_bf16 v[24:27], v[160:163], v[202:205], v[24:27]
	v_mfma_f32_16x16x32_bf16 v[12:15], v[142:145], v[210:213], v[12:15]
	v_mfma_f32_16x16x32_bf16 v[8:11], v[160:163], v[210:213], v[8:11]
	v_mfma_f32_16x16x32_bf16 v[52:55], v[164:167], v[180:183], 0
	v_mfma_f32_16x16x32_bf16 v[48:51], v[172:175], v[180:183], 0
	v_mfma_f32_16x16x32_bf16 v[36:39], v[164:167], v[190:193], 0
	v_mfma_f32_16x16x32_bf16 v[32:35], v[172:175], v[190:193], 0
	v_mfma_f32_16x16x32_bf16 v[20:23], v[164:167], v[198:201], 0
	v_mfma_f32_16x16x32_bf16 v[16:19], v[172:175], v[198:201], 0
	v_mfma_f32_16x16x32_bf16 v[4:7], v[164:167], v[206:209], 0
	v_mfma_f32_16x16x32_bf16 v[0:3], v[172:175], v[206:209], 0
	v_mfma_f32_16x16x32_bf16 v[52:55], v[168:171], v[184:187], v[52:55]
	v_mfma_f32_16x16x32_bf16 v[48:51], v[176:179], v[184:187], v[48:51]
	v_mfma_f32_16x16x32_bf16 v[36:39], v[168:171], v[194:197], v[36:39]
	v_mfma_f32_16x16x32_bf16 v[32:35], v[176:179], v[194:197], v[32:35]
	v_mfma_f32_16x16x32_bf16 v[20:23], v[168:171], v[202:205], v[20:23]
	v_mfma_f32_16x16x32_bf16 v[16:19], v[176:179], v[202:205], v[16:19]
	v_mfma_f32_16x16x32_bf16 v[4:7], v[168:171], v[210:213], v[4:7]
	v_mfma_f32_16x16x32_bf16 v[0:3], v[176:179], v[210:213], v[0:3]
	s_barrier
	s_add_i32 s59, 0, 0x18000
	v_add_u32_e32 v155, s59, v147
	s_add_i32 s60, 0, 0x1c000
	ds_read_b128 v[138:141], v155
	ds_read_b128 v[142:145], v155 offset:1024
	ds_read_b128 v[156:159], v155 offset:2048
	ds_read_b128 v[160:163], v155 offset:3072
	v_add_u32_e32 v155, s60, v147
	ds_read_b128 v[164:167], v155
	ds_read_b128 v[168:171], v155 offset:1024
	ds_read_b128 v[172:175], v155 offset:2048
	ds_read_b128 v[176:179], v155 offset:3072
	s_add_u32 s34, s34, 0x20000
	s_addc_u32 s35, s35, 0
	s_mov_b32 m0, s39
	v_lshl_add_u64 v[222:223], s[34:35], 0, v[128:129]
	ds_read_b128 v[180:183], v154 offset:32768
	ds_read_b128 v[184:187], v154 offset:33792
	ds_read_b128 v[190:193], v154 offset:34816
	ds_read_b128 v[194:197], v154 offset:35840
	ds_read_b128 v[198:201], v154 offset:36864
	ds_read_b128 v[202:205], v154 offset:37888
	ds_read_b128 v[206:209], v154 offset:38912
	ds_read_b128 v[210:213], v154 offset:39936
	global_load_lds_dwordx4 v[222:223], off
	v_lshl_add_u64 v[222:223], s[34:35], 0, v[130:131]
	s_mov_b32 m0, s40
	s_nop 0
	global_load_lds_dwordx4 v[222:223], off
	s_waitcnt vmcnt(8)
	s_waitcnt lgkmcnt(0)
	s_barrier
	s_waitcnt lgkmcnt(0)
	v_mfma_f32_16x16x32_bf16 v[120:123], v[138:141], v[180:183], v[120:123]
	v_mfma_f32_16x16x32_bf16 v[124:127], v[156:159], v[180:183], v[124:127]
	v_mfma_f32_16x16x32_bf16 v[108:111], v[138:141], v[190:193], v[108:111]
	v_mfma_f32_16x16x32_bf16 v[104:107], v[156:159], v[190:193], v[104:107]
	v_mfma_f32_16x16x32_bf16 v[92:95], v[138:141], v[198:201], v[92:95]
	v_mfma_f32_16x16x32_bf16 v[88:91], v[156:159], v[198:201], v[88:91]
	v_mfma_f32_16x16x32_bf16 v[76:79], v[138:141], v[206:209], v[76:79]
	v_mfma_f32_16x16x32_bf16 v[72:75], v[156:159], v[206:209], v[72:75]
	v_mfma_f32_16x16x32_bf16 v[120:123], v[142:145], v[184:187], v[120:123]
	v_mfma_f32_16x16x32_bf16 v[124:127], v[160:163], v[184:187], v[124:127]
	v_mfma_f32_16x16x32_bf16 v[108:111], v[142:145], v[194:197], v[108:111]
	v_mfma_f32_16x16x32_bf16 v[104:107], v[160:163], v[194:197], v[104:107]
	v_mfma_f32_16x16x32_bf16 v[92:95], v[142:145], v[202:205], v[92:95]
	v_mfma_f32_16x16x32_bf16 v[88:91], v[160:163], v[202:205], v[88:91]
	v_mfma_f32_16x16x32_bf16 v[76:79], v[142:145], v[210:213], v[76:79]
	v_mfma_f32_16x16x32_bf16 v[72:75], v[160:163], v[210:213], v[72:75]
	v_mfma_f32_16x16x32_bf16 v[116:119], v[164:167], v[180:183], v[116:119]
	v_mfma_f32_16x16x32_bf16 v[112:115], v[172:175], v[180:183], v[112:115]
	v_mfma_f32_16x16x32_bf16 v[100:103], v[164:167], v[190:193], v[100:103]
	v_mfma_f32_16x16x32_bf16 v[96:99], v[172:175], v[190:193], v[96:99]
	v_mfma_f32_16x16x32_bf16 v[84:87], v[164:167], v[198:201], v[84:87]
	v_mfma_f32_16x16x32_bf16 v[80:83], v[172:175], v[198:201], v[80:83]
	v_mfma_f32_16x16x32_bf16 v[68:71], v[164:167], v[206:209], v[68:71]
	v_mfma_f32_16x16x32_bf16 v[64:67], v[172:175], v[206:209], v[64:67]
	v_mfma_f32_16x16x32_bf16 v[116:119], v[168:171], v[184:187], v[116:119]
	v_mfma_f32_16x16x32_bf16 v[112:115], v[176:179], v[184:187], v[112:115]
	v_mfma_f32_16x16x32_bf16 v[100:103], v[168:171], v[194:197], v[100:103]
	v_mfma_f32_16x16x32_bf16 v[96:99], v[176:179], v[194:197], v[96:99]
	v_mfma_f32_16x16x32_bf16 v[84:87], v[168:171], v[202:205], v[84:87]
	v_mfma_f32_16x16x32_bf16 v[80:83], v[176:179], v[202:205], v[80:83]
	v_mfma_f32_16x16x32_bf16 v[68:71], v[168:171], v[210:213], v[68:71]
	v_mfma_f32_16x16x32_bf16 v[64:67], v[176:179], v[210:213], v[64:67]
	s_barrier
	s_add_i32 s34, s59, s29
	v_lshl_add_u64 v[214:215], v[214:215], 0, s[12:13]
	s_mov_b32 m0, s34
	ds_read_b128 v[180:183], v154 offset:49152
	ds_read_b128 v[184:187], v154 offset:50176
	ds_read_b128 v[190:193], v154 offset:51200
	ds_read_b128 v[194:197], v154 offset:52224
	ds_read_b128 v[198:201], v154 offset:53248
	ds_read_b128 v[202:205], v154 offset:54272
	ds_read_b128 v[206:209], v154 offset:55296
	ds_read_b128 v[210:213], v154 offset:56320
	global_load_lds_dwordx4 v[214:215], off
	s_add_i32 m0, s34, 0x2000
	s_add_u32 s4, s4, 0x20080
	v_lshl_add_u64 v[214:215], v[216:217], 0, s[12:13]
	s_addc_u32 s5, s5, 0
	s_add_i32 s34, s60, s29
	global_load_lds_dwordx4 v[214:215], off
	v_lshl_add_u64 v[214:215], s[4:5], 0, v[128:129]
	s_mov_b32 m0, s34
	s_nop 0
	global_load_lds_dwordx4 v[214:215], off
	v_lshl_add_u64 v[214:215], s[4:5], 0, v[130:131]
	s_add_i32 m0, s34, 0x2000
	s_nop 0
	global_load_lds_dwordx4 v[214:215], off
	v_lshl_add_u64 v[214:215], v[218:219], 0, s[12:13]
	s_mov_b32 m0, s46
	s_nop 0
	global_load_lds_dwordx4 v[214:215], off
	v_lshl_add_u64 v[214:215], v[220:221], 0, s[12:13]
	s_mov_b32 m0, s47
	s_nop 0
	global_load_lds_dwordx4 v[214:215], off
	s_waitcnt vmcnt(8)
	s_waitcnt lgkmcnt(0)
	s_barrier
	s_waitcnt lgkmcnt(0)
	v_mfma_f32_16x16x32_bf16 v[60:63], v[138:141], v[180:183], v[60:63]
	v_mfma_f32_16x16x32_bf16 v[56:59], v[156:159], v[180:183], v[56:59]
	v_mfma_f32_16x16x32_bf16 v[44:47], v[138:141], v[190:193], v[44:47]
	v_mfma_f32_16x16x32_bf16 v[40:43], v[156:159], v[190:193], v[40:43]
	v_mfma_f32_16x16x32_bf16 v[28:31], v[138:141], v[198:201], v[28:31]
	v_mfma_f32_16x16x32_bf16 v[24:27], v[156:159], v[198:201], v[24:27]
	v_mfma_f32_16x16x32_bf16 v[12:15], v[138:141], v[206:209], v[12:15]
	v_mfma_f32_16x16x32_bf16 v[8:11], v[156:159], v[206:209], v[8:11]
	v_mfma_f32_16x16x32_bf16 v[60:63], v[142:145], v[184:187], v[60:63]
	v_mfma_f32_16x16x32_bf16 v[56:59], v[160:163], v[184:187], v[56:59]
	v_mfma_f32_16x16x32_bf16 v[44:47], v[142:145], v[194:197], v[44:47]
	v_mfma_f32_16x16x32_bf16 v[40:43], v[160:163], v[194:197], v[40:43]
	v_mfma_f32_16x16x32_bf16 v[28:31], v[142:145], v[202:205], v[28:31]
	v_mfma_f32_16x16x32_bf16 v[24:27], v[160:163], v[202:205], v[24:27]
	v_mfma_f32_16x16x32_bf16 v[12:15], v[142:145], v[210:213], v[12:15]
	v_mfma_f32_16x16x32_bf16 v[8:11], v[160:163], v[210:213], v[8:11]
	v_mfma_f32_16x16x32_bf16 v[52:55], v[164:167], v[180:183], v[52:55]
	v_mfma_f32_16x16x32_bf16 v[48:51], v[172:175], v[180:183], v[48:51]
	v_mfma_f32_16x16x32_bf16 v[36:39], v[164:167], v[190:193], v[36:39]
	v_mfma_f32_16x16x32_bf16 v[32:35], v[172:175], v[190:193], v[32:35]
	v_mfma_f32_16x16x32_bf16 v[20:23], v[164:167], v[198:201], v[20:23]
	v_mfma_f32_16x16x32_bf16 v[16:19], v[172:175], v[198:201], v[16:19]
	v_mfma_f32_16x16x32_bf16 v[4:7], v[164:167], v[206:209], v[4:7]
	v_mfma_f32_16x16x32_bf16 v[0:3], v[172:175], v[206:209], v[0:3]
	v_mfma_f32_16x16x32_bf16 v[52:55], v[168:171], v[184:187], v[52:55]
	v_mfma_f32_16x16x32_bf16 v[48:51], v[176:179], v[184:187], v[48:51]
	v_mfma_f32_16x16x32_bf16 v[36:39], v[168:171], v[194:197], v[36:39]
	v_mfma_f32_16x16x32_bf16 v[32:35], v[176:179], v[194:197], v[32:35]
	v_mfma_f32_16x16x32_bf16 v[20:23], v[168:171], v[202:205], v[20:23]
	v_mfma_f32_16x16x32_bf16 v[16:19], v[176:179], v[202:205], v[16:19]
	v_mfma_f32_16x16x32_bf16 v[4:7], v[168:171], v[210:213], v[4:7]
	v_mfma_f32_16x16x32_bf16 v[0:3], v[176:179], v[210:213], v[0:3]
	s_barrier
	s_add_u32 s30, s30, 0x100
	s_addc_u32 s31, s31, 0
	s_add_u32 s21, s21, 0x100
	s_addc_u32 s23, s23, 0
	s_cmp_ge_i32 s58, s41
	s_mov_b32 s4, s58
	s_cbranch_scc0 .LBB0_1266
	s_branch .LBB0_1267

.LBB0_1266:
	ds_read_b128 v[138:141], v152
	ds_read_b128 v[142:145], v152 offset:1024
	ds_read_b128 v[156:159], v152 offset:2048
	ds_read_b128 v[160:163], v152 offset:3072
	ds_read_b128 v[164:167], v153
	ds_read_b128 v[168:171], v153 offset:1024
	ds_read_b128 v[172:175], v153 offset:2048
	ds_read_b128 v[176:179], v153 offset:3072
	s_add_i32 s58, s4, 2
	s_add_u32 s5, s30, 0xfffe0080
	s_addc_u32 s34, s31, -1
	s_cmp_eq_u32 s48, s4
	s_cselect_b32 s4, s26, s21
	s_cselect_b32 s35, s25, s34
	s_cselect_b32 s34, s24, s5
	s_cselect_b32 s5, s27, s23
	v_lshl_add_u64 v[214:215], s[30:31], 0, v[132:133]
	s_add_i32 m0, s37, 0xc000
	ds_read_b128 v[180:183], v154
	ds_read_b128 v[184:187], v154 offset:1024
	ds_read_b128 v[190:193], v154 offset:2048
	ds_read_b128 v[194:197], v154 offset:3072
	ds_read_b128 v[198:201], v154 offset:4096
	ds_read_b128 v[202:205], v154 offset:5120
	ds_read_b128 v[206:209], v154 offset:6144
	ds_read_b128 v[210:213], v154 offset:7168
	global_load_lds_dwordx4 v[214:215], off
	v_lshl_add_u64 v[214:215], s[30:31], 0, v[134:135]
	s_add_i32 m0, s37, 0xe000
	s_nop 0
	global_load_lds_dwordx4 v[214:215], off
	s_waitcnt vmcnt(8)
	s_waitcnt lgkmcnt(0)
	s_barrier
	s_waitcnt lgkmcnt(0)
	v_mfma_f32_16x16x32_bf16 v[120:123], v[138:141], v[180:183], v[120:123]
	v_mfma_f32_16x16x32_bf16 v[124:127], v[156:159], v[180:183], v[124:127]
	v_mfma_f32_16x16x32_bf16 v[108:111], v[138:141], v[190:193], v[108:111]
	v_mfma_f32_16x16x32_bf16 v[104:107], v[156:159], v[190:193], v[104:107]
	v_mfma_f32_16x16x32_bf16 v[92:95], v[138:141], v[198:201], v[92:95]
	v_mfma_f32_16x16x32_bf16 v[88:91], v[156:159], v[198:201], v[88:91]
	v_mfma_f32_16x16x32_bf16 v[76:79], v[138:141], v[206:209], v[76:79]
	v_mfma_f32_16x16x32_bf16 v[72:75], v[156:159], v[206:209], v[72:75]
	v_mfma_f32_16x16x32_bf16 v[120:123], v[142:145], v[184:187], v[120:123]
	v_mfma_f32_16x16x32_bf16 v[124:127], v[160:163], v[184:187], v[124:127]
	v_mfma_f32_16x16x32_bf16 v[108:111], v[142:145], v[194:197], v[108:111]
	v_mfma_f32_16x16x32_bf16 v[104:107], v[160:163], v[194:197], v[104:107]
	v_mfma_f32_16x16x32_bf16 v[92:95], v[142:145], v[202:205], v[92:95]
	v_mfma_f32_16x16x32_bf16 v[88:91], v[160:163], v[202:205], v[88:91]
	v_mfma_f32_16x16x32_bf16 v[76:79], v[142:145], v[210:213], v[76:79]
	v_mfma_f32_16x16x32_bf16 v[72:75], v[160:163], v[210:213], v[72:75]
	v_mfma_f32_16x16x32_bf16 v[116:119], v[164:167], v[180:183], v[116:119]
	v_mfma_f32_16x16x32_bf16 v[112:115], v[172:175], v[180:183], v[112:115]
	v_mfma_f32_16x16x32_bf16 v[100:103], v[164:167], v[190:193], v[100:103]
	v_mfma_f32_16x16x32_bf16 v[96:99], v[172:175], v[190:193], v[96:99]
	v_mfma_f32_16x16x32_bf16 v[84:87], v[164:167], v[198:201], v[84:87]
	v_mfma_f32_16x16x32_bf16 v[80:83], v[172:175], v[198:201], v[80:83]
	v_mfma_f32_16x16x32_bf16 v[68:71], v[164:167], v[206:209], v[68:71]
	v_mfma_f32_16x16x32_bf16 v[64:67], v[172:175], v[206:209], v[64:67]
	v_mfma_f32_16x16x32_bf16 v[116:119], v[168:171], v[184:187], v[116:119]
	v_mfma_f32_16x16x32_bf16 v[112:115], v[176:179], v[184:187], v[112:115]
	v_mfma_f32_16x16x32_bf16 v[100:103], v[168:171], v[194:197], v[100:103]
	v_mfma_f32_16x16x32_bf16 v[96:99], v[176:179], v[194:197], v[96:99]
	v_mfma_f32_16x16x32_bf16 v[84:87], v[168:171], v[202:205], v[84:87]
	v_mfma_f32_16x16x32_bf16 v[80:83], v[176:179], v[202:205], v[80:83]
	v_mfma_f32_16x16x32_bf16 v[68:71], v[168:171], v[210:213], v[68:71]
	v_mfma_f32_16x16x32_bf16 v[64:67], v[176:179], v[210:213], v[64:67]
	s_barrier
	s_add_i32 s59, s52, s29
	v_lshl_add_u64 v[214:215], s[4:5], 0, v[128:129]
	s_mov_b32 m0, s59
	ds_read_b128 v[180:183], v154 offset:16384
	ds_read_b128 v[184:187], v154 offset:17408
	ds_read_b128 v[190:193], v154 offset:18432
	ds_read_b128 v[194:197], v154 offset:19456
	ds_read_b128 v[198:201], v154 offset:20480
	ds_read_b128 v[202:205], v154 offset:21504
	ds_read_b128 v[206:209], v154 offset:22528
	ds_read_b128 v[210:213], v154 offset:23552
	global_load_lds_dwordx4 v[214:215], off
	s_add_i32 m0, s59, 0x2000
	s_add_u32 s60, s4, 0x20000
	v_lshl_add_u64 v[216:217], s[4:5], 0, v[130:131]
	s_addc_u32 s61, s5, 0
	s_add_i32 s59, s53, s29
	global_load_lds_dwordx4 v[216:217], off
	v_lshl_add_u64 v[218:219], s[60:61], 0, v[128:129]
	s_mov_b32 m0, s59
	v_lshl_add_u64 v[220:221], s[34:35], 0, v[130:131]
	global_load_lds_dwordx4 v[218:219], off
	v_lshl_add_u64 v[218:219], s[60:61], 0, v[130:131]
	s_add_i32 m0, s59, 0x2000
	s_nop 0
	global_load_lds_dwordx4 v[218:219], off
	v_lshl_add_u64 v[218:219], s[34:35], 0, v[128:129]
	s_mov_b32 m0, s37
	s_nop 0
	global_load_lds_dwordx4 v[218:219], off
	s_mov_b32 m0, s38
	s_nop 0
	global_load_lds_dwordx4 v[220:221], off
	s_waitcnt vmcnt(8)
	s_waitcnt lgkmcnt(0)
	s_barrier
	s_waitcnt lgkmcnt(0)
	v_mfma_f32_16x16x32_bf16 v[60:63], v[138:141], v[180:183], v[60:63]
	v_mfma_f32_16x16x32_bf16 v[56:59], v[156:159], v[180:183], v[56:59]
	v_mfma_f32_16x16x32_bf16 v[44:47], v[138:141], v[190:193], v[44:47]
	v_mfma_f32_16x16x32_bf16 v[40:43], v[156:159], v[190:193], v[40:43]
	v_mfma_f32_16x16x32_bf16 v[28:31], v[138:141], v[198:201], v[28:31]
	v_mfma_f32_16x16x32_bf16 v[24:27], v[156:159], v[198:201], v[24:27]
	v_mfma_f32_16x16x32_bf16 v[12:15], v[138:141], v[206:209], v[12:15]
	v_mfma_f32_16x16x32_bf16 v[8:11], v[156:159], v[206:209], v[8:11]
	v_mfma_f32_16x16x32_bf16 v[60:63], v[142:145], v[184:187], v[60:63]
	v_mfma_f32_16x16x32_bf16 v[56:59], v[160:163], v[184:187], v[56:59]
	v_mfma_f32_16x16x32_bf16 v[44:47], v[142:145], v[194:197], v[44:47]
	v_mfma_f32_16x16x32_bf16 v[40:43], v[160:163], v[194:197], v[40:43]
	v_mfma_f32_16x16x32_bf16 v[28:31], v[142:145], v[202:205], v[28:31]
	v_mfma_f32_16x16x32_bf16 v[24:27], v[160:163], v[202:205], v[24:27]
	v_mfma_f32_16x16x32_bf16 v[12:15], v[142:145], v[210:213], v[12:15]
	v_mfma_f32_16x16x32_bf16 v[8:11], v[160:163], v[210:213], v[8:11]
	v_mfma_f32_16x16x32_bf16 v[52:55], v[164:167], v[180:183], v[52:55]
	v_mfma_f32_16x16x32_bf16 v[48:51], v[172:175], v[180:183], v[48:51]
	v_mfma_f32_16x16x32_bf16 v[36:39], v[164:167], v[190:193], v[36:39]
	v_mfma_f32_16x16x32_bf16 v[32:35], v[172:175], v[190:193], v[32:35]
	v_mfma_f32_16x16x32_bf16 v[20:23], v[164:167], v[198:201], v[20:23]
	v_mfma_f32_16x16x32_bf16 v[16:19], v[172:175], v[198:201], v[16:19]
	v_mfma_f32_16x16x32_bf16 v[4:7], v[164:167], v[206:209], v[4:7]
	v_mfma_f32_16x16x32_bf16 v[0:3], v[172:175], v[206:209], v[0:3]
	v_mfma_f32_16x16x32_bf16 v[52:55], v[168:171], v[184:187], v[52:55]
	v_mfma_f32_16x16x32_bf16 v[48:51], v[176:179], v[184:187], v[48:51]
	v_mfma_f32_16x16x32_bf16 v[36:39], v[168:171], v[194:197], v[36:39]
	v_mfma_f32_16x16x32_bf16 v[32:35], v[176:179], v[194:197], v[32:35]
	v_mfma_f32_16x16x32_bf16 v[20:23], v[168:171], v[202:205], v[20:23]
	v_mfma_f32_16x16x32_bf16 v[16:19], v[176:179], v[202:205], v[16:19]
	v_mfma_f32_16x16x32_bf16 v[4:7], v[168:171], v[210:213], v[4:7]
	v_mfma_f32_16x16x32_bf16 v[0:3], v[176:179], v[210:213], v[0:3]
	s_barrier
	s_add_i32 s59, 0, 0x18000
	v_add_u32_e32 v155, s59, v147
	s_add_i32 s60, 0, 0x1c000
	ds_read_b128 v[138:141], v155
	ds_read_b128 v[142:145], v155 offset:1024
	ds_read_b128 v[156:159], v155 offset:2048
	ds_read_b128 v[160:163], v155 offset:3072
	v_add_u32_e32 v155, s60, v147
	ds_read_b128 v[164:167], v155
	ds_read_b128 v[168:171], v155 offset:1024
	ds_read_b128 v[172:175], v155 offset:2048
	ds_read_b128 v[176:179], v155 offset:3072
	s_add_u32 s34, s34, 0x20000
	s_addc_u32 s35, s35, 0
	s_mov_b32 m0, s39
	v_lshl_add_u64 v[222:223], s[34:35], 0, v[128:129]
	ds_read_b128 v[180:183], v154 offset:32768
	ds_read_b128 v[184:187], v154 offset:33792
	ds_read_b128 v[190:193], v154 offset:34816
	ds_read_b128 v[194:197], v154 offset:35840
	ds_read_b128 v[198:201], v154 offset:36864
	ds_read_b128 v[202:205], v154 offset:37888
	ds_read_b128 v[206:209], v154 offset:38912
	ds_read_b128 v[210:213], v154 offset:39936
	global_load_lds_dwordx4 v[222:223], off
	v_lshl_add_u64 v[222:223], s[34:35], 0, v[130:131]
	s_mov_b32 m0, s40
	s_nop 0
	global_load_lds_dwordx4 v[222:223], off
	s_waitcnt vmcnt(8)
	s_waitcnt lgkmcnt(0)
	s_barrier
	s_waitcnt lgkmcnt(0)
	v_mfma_f32_16x16x32_bf16 v[120:123], v[138:141], v[180:183], v[120:123]
	v_mfma_f32_16x16x32_bf16 v[124:127], v[156:159], v[180:183], v[124:127]
	v_mfma_f32_16x16x32_bf16 v[108:111], v[138:141], v[190:193], v[108:111]
	v_mfma_f32_16x16x32_bf16 v[104:107], v[156:159], v[190:193], v[104:107]
	v_mfma_f32_16x16x32_bf16 v[92:95], v[138:141], v[198:201], v[92:95]
	v_mfma_f32_16x16x32_bf16 v[88:91], v[156:159], v[198:201], v[88:91]
	v_mfma_f32_16x16x32_bf16 v[76:79], v[138:141], v[206:209], v[76:79]
	v_mfma_f32_16x16x32_bf16 v[72:75], v[156:159], v[206:209], v[72:75]
	v_mfma_f32_16x16x32_bf16 v[120:123], v[142:145], v[184:187], v[120:123]
	v_mfma_f32_16x16x32_bf16 v[124:127], v[160:163], v[184:187], v[124:127]
	v_mfma_f32_16x16x32_bf16 v[108:111], v[142:145], v[194:197], v[108:111]
	v_mfma_f32_16x16x32_bf16 v[104:107], v[160:163], v[194:197], v[104:107]
	v_mfma_f32_16x16x32_bf16 v[92:95], v[142:145], v[202:205], v[92:95]
	v_mfma_f32_16x16x32_bf16 v[88:91], v[160:163], v[202:205], v[88:91]
	v_mfma_f32_16x16x32_bf16 v[76:79], v[142:145], v[210:213], v[76:79]
	v_mfma_f32_16x16x32_bf16 v[72:75], v[160:163], v[210:213], v[72:75]
	v_mfma_f32_16x16x32_bf16 v[116:119], v[164:167], v[180:183], v[116:119]
	v_mfma_f32_16x16x32_bf16 v[112:115], v[172:175], v[180:183], v[112:115]
	v_mfma_f32_16x16x32_bf16 v[100:103], v[164:167], v[190:193], v[100:103]
	v_mfma_f32_16x16x32_bf16 v[96:99], v[172:175], v[190:193], v[96:99]
	v_mfma_f32_16x16x32_bf16 v[84:87], v[164:167], v[198:201], v[84:87]
	v_mfma_f32_16x16x32_bf16 v[80:83], v[172:175], v[198:201], v[80:83]
	v_mfma_f32_16x16x32_bf16 v[68:71], v[164:167], v[206:209], v[68:71]
	v_mfma_f32_16x16x32_bf16 v[64:67], v[172:175], v[206:209], v[64:67]
	v_mfma_f32_16x16x32_bf16 v[116:119], v[168:171], v[184:187], v[116:119]
	v_mfma_f32_16x16x32_bf16 v[112:115], v[176:179], v[184:187], v[112:115]
	v_mfma_f32_16x16x32_bf16 v[100:103], v[168:171], v[194:197], v[100:103]
	v_mfma_f32_16x16x32_bf16 v[96:99], v[176:179], v[194:197], v[96:99]
	v_mfma_f32_16x16x32_bf16 v[84:87], v[168:171], v[202:205], v[84:87]
	v_mfma_f32_16x16x32_bf16 v[80:83], v[176:179], v[202:205], v[80:83]
	v_mfma_f32_16x16x32_bf16 v[68:71], v[168:171], v[210:213], v[68:71]
	v_mfma_f32_16x16x32_bf16 v[64:67], v[176:179], v[210:213], v[64:67]
	s_barrier
	s_add_i32 s34, s59, s29
	v_lshl_add_u64 v[214:215], v[214:215], 0, s[12:13]
	s_mov_b32 m0, s34
	ds_read_b128 v[180:183], v154 offset:49152
	ds_read_b128 v[184:187], v154 offset:50176
	ds_read_b128 v[190:193], v154 offset:51200
	ds_read_b128 v[194:197], v154 offset:52224
	ds_read_b128 v[198:201], v154 offset:53248
	ds_read_b128 v[202:205], v154 offset:54272
	ds_read_b128 v[206:209], v154 offset:55296
	ds_read_b128 v[210:213], v154 offset:56320
	global_load_lds_dwordx4 v[214:215], off
	s_add_i32 m0, s34, 0x2000
	s_add_u32 s4, s4, 0x20080
	v_lshl_add_u64 v[214:215], v[216:217], 0, s[12:13]
	s_addc_u32 s5, s5, 0
	s_add_i32 s34, s60, s29
	global_load_lds_dwordx4 v[214:215], off
	v_lshl_add_u64 v[214:215], s[4:5], 0, v[128:129]
	s_mov_b32 m0, s34
	s_nop 0
	global_load_lds_dwordx4 v[214:215], off
	v_lshl_add_u64 v[214:215], s[4:5], 0, v[130:131]
	s_add_i32 m0, s34, 0x2000
	s_nop 0
	global_load_lds_dwordx4 v[214:215], off
	v_lshl_add_u64 v[214:215], v[218:219], 0, s[12:13]
	s_mov_b32 m0, s46
	s_nop 0
	global_load_lds_dwordx4 v[214:215], off
	v_lshl_add_u64 v[214:215], v[220:221], 0, s[12:13]
	s_mov_b32 m0, s47
	s_nop 0
	global_load_lds_dwordx4 v[214:215], off
	s_waitcnt vmcnt(8)
	s_waitcnt lgkmcnt(0)
	s_barrier
	s_waitcnt lgkmcnt(0)
	v_mfma_f32_16x16x32_bf16 v[60:63], v[138:141], v[180:183], v[60:63]
	v_mfma_f32_16x16x32_bf16 v[56:59], v[156:159], v[180:183], v[56:59]
	v_mfma_f32_16x16x32_bf16 v[44:47], v[138:141], v[190:193], v[44:47]
	v_mfma_f32_16x16x32_bf16 v[40:43], v[156:159], v[190:193], v[40:43]
	v_mfma_f32_16x16x32_bf16 v[28:31], v[138:141], v[198:201], v[28:31]
	v_mfma_f32_16x16x32_bf16 v[24:27], v[156:159], v[198:201], v[24:27]
	v_mfma_f32_16x16x32_bf16 v[12:15], v[138:141], v[206:209], v[12:15]
	v_mfma_f32_16x16x32_bf16 v[8:11], v[156:159], v[206:209], v[8:11]
	v_mfma_f32_16x16x32_bf16 v[60:63], v[142:145], v[184:187], v[60:63]
	v_mfma_f32_16x16x32_bf16 v[56:59], v[160:163], v[184:187], v[56:59]
	v_mfma_f32_16x16x32_bf16 v[44:47], v[142:145], v[194:197], v[44:47]
	v_mfma_f32_16x16x32_bf16 v[40:43], v[160:163], v[194:197], v[40:43]
	v_mfma_f32_16x16x32_bf16 v[28:31], v[142:145], v[202:205], v[28:31]
	v_mfma_f32_16x16x32_bf16 v[24:27], v[160:163], v[202:205], v[24:27]
	v_mfma_f32_16x16x32_bf16 v[12:15], v[142:145], v[210:213], v[12:15]
	v_mfma_f32_16x16x32_bf16 v[8:11], v[160:163], v[210:213], v[8:11]
	v_mfma_f32_16x16x32_bf16 v[52:55], v[164:167], v[180:183], v[52:55]
	v_mfma_f32_16x16x32_bf16 v[48:51], v[172:175], v[180:183], v[48:51]
	v_mfma_f32_16x16x32_bf16 v[36:39], v[164:167], v[190:193], v[36:39]
	v_mfma_f32_16x16x32_bf16 v[32:35], v[172:175], v[190:193], v[32:35]
	v_mfma_f32_16x16x32_bf16 v[20:23], v[164:167], v[198:201], v[20:23]
	v_mfma_f32_16x16x32_bf16 v[16:19], v[172:175], v[198:201], v[16:19]
	v_mfma_f32_16x16x32_bf16 v[4:7], v[164:167], v[206:209], v[4:7]
	v_mfma_f32_16x16x32_bf16 v[0:3], v[172:175], v[206:209], v[0:3]
	v_mfma_f32_16x16x32_bf16 v[52:55], v[168:171], v[184:187], v[52:55]
	v_mfma_f32_16x16x32_bf16 v[48:51], v[176:179], v[184:187], v[48:51]
	v_mfma_f32_16x16x32_bf16 v[36:39], v[168:171], v[194:197], v[36:39]
	v_mfma_f32_16x16x32_bf16 v[32:35], v[176:179], v[194:197], v[32:35]
	v_mfma_f32_16x16x32_bf16 v[20:23], v[168:171], v[202:205], v[20:23]
	v_mfma_f32_16x16x32_bf16 v[16:19], v[176:179], v[202:205], v[16:19]
	v_mfma_f32_16x16x32_bf16 v[4:7], v[168:171], v[210:213], v[4:7]
	v_mfma_f32_16x16x32_bf16 v[0:3], v[176:179], v[210:213], v[0:3]
	s_barrier
	s_add_u32 s30, s30, 0x100
	s_addc_u32 s31, s31, 0
	s_add_u32 s21, s21, 0x100
	s_addc_u32 s23, s23, 0
	s_cmp_ge_i32 s58, s41
	s_mov_b32 s4, s58
	s_cbranch_scc0 .LBB0_1266

.LBB0_1368:
	s_andn2_b64 vcc, exec, s[18:19]
	s_waitcnt lgkmcnt(0)
	s_waitcnt vmcnt(0)
	s_cbranch_vccnz .Lpz_zero_3
	s_add_u32 s34, s4, 0x40080
	s_addc_u32 s35, s5, 0
	s_add_u32 s23, s36, 0x100
	s_addc_u32 s25, s37, 0
	s_mov_b32 s4, 0
	ds_read_b128 v[138:141], v145
	ds_read_b128 v[150:153], v145 offset:1024
	ds_read_b128 v[154:157], v145 offset:2048
	ds_read_b128 v[158:161], v145 offset:3072
	ds_read_b128 v[162:165], v146
	ds_read_b128 v[166:169], v146 offset:1024
	ds_read_b128 v[170:173], v146 offset:2048
	ds_read_b128 v[174:177], v146 offset:3072
	s_add_i32 s31, s4, 2
	s_add_u32 s5, s34, 0xfffc0080
	s_addc_u32 s36, s35, -1
	s_cmp_eq_u32 s50, s4
	s_cselect_b32 s4, s28, s23
	s_cselect_b32 s37, s27, s36
	s_cselect_b32 s36, s26, s5
	s_cselect_b32 s5, s29, s25
	v_lshl_add_u64 v[186:187], s[34:35], 0, v[132:133]
	s_add_i32 m0, s42, 0xc000
	ds_read_b128 v[178:181], v147
	ds_read_b128 v[182:185], v147 offset:1024
	ds_read_b128 v[190:193], v147 offset:2048
	ds_read_b128 v[194:197], v147 offset:3072
	ds_read_b128 v[198:201], v147 offset:4096
	ds_read_b128 v[202:205], v147 offset:5120
	ds_read_b128 v[206:209], v147 offset:6144
	ds_read_b128 v[210:213], v147 offset:7168
	global_load_lds_dwordx4 v[186:187], off
	v_lshl_add_u64 v[186:187], s[34:35], 0, v[134:135]
	s_add_i32 m0, s42, 0xe000
	s_nop 0
	global_load_lds_dwordx4 v[186:187], off
	s_waitcnt vmcnt(8)
	s_waitcnt lgkmcnt(0)
	s_barrier
	s_waitcnt lgkmcnt(0)
	v_mfma_f32_16x16x32_bf16 v[120:123], v[138:141], v[178:181], 0
	v_mfma_f32_16x16x32_bf16 v[124:127], v[154:157], v[178:181], 0
	v_mfma_f32_16x16x32_bf16 v[108:111], v[138:141], v[190:193], 0
	v_mfma_f32_16x16x32_bf16 v[104:107], v[154:157], v[190:193], 0
	v_mfma_f32_16x16x32_bf16 v[92:95], v[138:141], v[198:201], 0
	v_mfma_f32_16x16x32_bf16 v[88:91], v[154:157], v[198:201], 0
	v_mfma_f32_16x16x32_bf16 v[76:79], v[138:141], v[206:209], 0
	v_mfma_f32_16x16x32_bf16 v[72:75], v[154:157], v[206:209], 0
	v_mfma_f32_16x16x32_bf16 v[120:123], v[150:153], v[182:185], v[120:123]
	v_mfma_f32_16x16x32_bf16 v[124:127], v[158:161], v[182:185], v[124:127]
	v_mfma_f32_16x16x32_bf16 v[108:111], v[150:153], v[194:197], v[108:111]
	v_mfma_f32_16x16x32_bf16 v[104:107], v[158:161], v[194:197], v[104:107]
	v_mfma_f32_16x16x32_bf16 v[92:95], v[150:153], v[202:205], v[92:95]
	v_mfma_f32_16x16x32_bf16 v[88:91], v[158:161], v[202:205], v[88:91]
	v_mfma_f32_16x16x32_bf16 v[76:79], v[150:153], v[210:213], v[76:79]
	v_mfma_f32_16x16x32_bf16 v[72:75], v[158:161], v[210:213], v[72:75]
	v_mfma_f32_16x16x32_bf16 v[116:119], v[162:165], v[178:181], 0
	v_mfma_f32_16x16x32_bf16 v[112:115], v[170:173], v[178:181], 0
	v_mfma_f32_16x16x32_bf16 v[100:103], v[162:165], v[190:193], 0
	v_mfma_f32_16x16x32_bf16 v[96:99], v[170:173], v[190:193], 0
	v_mfma_f32_16x16x32_bf16 v[84:87], v[162:165], v[198:201], 0
	v_mfma_f32_16x16x32_bf16 v[80:83], v[170:173], v[198:201], 0
	v_mfma_f32_16x16x32_bf16 v[68:71], v[162:165], v[206:209], 0
	v_mfma_f32_16x16x32_bf16 v[64:67], v[170:173], v[206:209], 0
	v_mfma_f32_16x16x32_bf16 v[116:119], v[166:169], v[182:185], v[116:119]
	v_mfma_f32_16x16x32_bf16 v[112:115], v[174:177], v[182:185], v[112:115]
	v_mfma_f32_16x16x32_bf16 v[100:103], v[166:169], v[194:197], v[100:103]
	v_mfma_f32_16x16x32_bf16 v[96:99], v[174:177], v[194:197], v[96:99]
	v_mfma_f32_16x16x32_bf16 v[84:87], v[166:169], v[202:205], v[84:87]
	v_mfma_f32_16x16x32_bf16 v[80:83], v[174:177], v[202:205], v[80:83]
	v_mfma_f32_16x16x32_bf16 v[68:71], v[166:169], v[210:213], v[68:71]
	v_mfma_f32_16x16x32_bf16 v[64:67], v[174:177], v[210:213], v[64:67]
	s_barrier
	s_add_i32 s59, s55, s41
	v_lshl_add_u64 v[186:187], s[4:5], 0, v[128:129]
	s_mov_b32 m0, s59
	ds_read_b128 v[178:181], v147 offset:16384
	ds_read_b128 v[182:185], v147 offset:17408
	ds_read_b128 v[190:193], v147 offset:18432
	ds_read_b128 v[194:197], v147 offset:19456
	ds_read_b128 v[198:201], v147 offset:20480
	ds_read_b128 v[202:205], v147 offset:21504
	ds_read_b128 v[206:209], v147 offset:22528
	ds_read_b128 v[210:213], v147 offset:23552
	global_load_lds_dwordx4 v[186:187], off
	s_add_i32 m0, s59, 0x2000
	s_add_u32 s60, s4, 0x40000
	v_lshl_add_u64 v[214:215], s[4:5], 0, v[130:131]
	s_addc_u32 s61, s5, 0
	s_add_i32 s59, s56, s41
	global_load_lds_dwordx4 v[214:215], off
	v_lshl_add_u64 v[216:217], s[60:61], 0, v[128:129]
	s_mov_b32 m0, s59
	v_lshl_add_u64 v[218:219], s[36:37], 0, v[130:131]
	global_load_lds_dwordx4 v[216:217], off
	v_lshl_add_u64 v[216:217], s[60:61], 0, v[130:131]
	s_add_i32 m0, s59, 0x2000
	s_nop 0
	global_load_lds_dwordx4 v[216:217], off
	v_lshl_add_u64 v[216:217], s[36:37], 0, v[128:129]
	s_mov_b32 m0, s42
	s_nop 0
	global_load_lds_dwordx4 v[216:217], off
	s_mov_b32 m0, s43
	s_nop 0
	global_load_lds_dwordx4 v[218:219], off
	s_waitcnt vmcnt(8)
	s_waitcnt lgkmcnt(0)
	s_barrier
	s_waitcnt lgkmcnt(0)
	v_mfma_f32_16x16x32_bf16 v[60:63], v[138:141], v[178:181], 0
	v_mfma_f32_16x16x32_bf16 v[56:59], v[154:157], v[178:181], 0
	v_mfma_f32_16x16x32_bf16 v[44:47], v[138:141], v[190:193], 0
	v_mfma_f32_16x16x32_bf16 v[40:43], v[154:157], v[190:193], 0
	v_mfma_f32_16x16x32_bf16 v[28:31], v[138:141], v[198:201], 0
	v_mfma_f32_16x16x32_bf16 v[24:27], v[154:157], v[198:201], 0
	v_mfma_f32_16x16x32_bf16 v[12:15], v[138:141], v[206:209], 0
	v_mfma_f32_16x16x32_bf16 v[8:11], v[154:157], v[206:209], 0
	v_mfma_f32_16x16x32_bf16 v[60:63], v[150:153], v[182:185], v[60:63]
	v_mfma_f32_16x16x32_bf16 v[56:59], v[158:161], v[182:185], v[56:59]
	v_mfma_f32_16x16x32_bf16 v[44:47], v[150:153], v[194:197], v[44:47]
	v_mfma_f32_16x16x32_bf16 v[40:43], v[158:161], v[194:197], v[40:43]
	v_mfma_f32_16x16x32_bf16 v[28:31], v[150:153], v[202:205], v[28:31]
	v_mfma_f32_16x16x32_bf16 v[24:27], v[158:161], v[202:205], v[24:27]
	v_mfma_f32_16x16x32_bf16 v[12:15], v[150:153], v[210:213], v[12:15]
	v_mfma_f32_16x16x32_bf16 v[8:11], v[158:161], v[210:213], v[8:11]
	v_mfma_f32_16x16x32_bf16 v[52:55], v[162:165], v[178:181], 0
	v_mfma_f32_16x16x32_bf16 v[48:51], v[170:173], v[178:181], 0
	v_mfma_f32_16x16x32_bf16 v[36:39], v[162:165], v[190:193], 0
	v_mfma_f32_16x16x32_bf16 v[32:35], v[170:173], v[190:193], 0
	v_mfma_f32_16x16x32_bf16 v[20:23], v[162:165], v[198:201], 0
	v_mfma_f32_16x16x32_bf16 v[16:19], v[170:173], v[198:201], 0
	v_mfma_f32_16x16x32_bf16 v[4:7], v[162:165], v[206:209], 0
	v_mfma_f32_16x16x32_bf16 v[0:3], v[170:173], v[206:209], 0
	v_mfma_f32_16x16x32_bf16 v[52:55], v[166:169], v[182:185], v[52:55]
	v_mfma_f32_16x16x32_bf16 v[48:51], v[174:177], v[182:185], v[48:51]
	v_mfma_f32_16x16x32_bf16 v[36:39], v[166:169], v[194:197], v[36:39]
	v_mfma_f32_16x16x32_bf16 v[32:35], v[174:177], v[194:197], v[32:35]
	v_mfma_f32_16x16x32_bf16 v[20:23], v[166:169], v[202:205], v[20:23]
	v_mfma_f32_16x16x32_bf16 v[16:19], v[174:177], v[202:205], v[16:19]
	v_mfma_f32_16x16x32_bf16 v[4:7], v[166:169], v[210:213], v[4:7]
	v_mfma_f32_16x16x32_bf16 v[0:3], v[174:177], v[210:213], v[0:3]
	s_barrier
	s_add_i32 s59, 0, 0x18000
	v_add_u32_e32 v149, s59, v143
	s_add_i32 s60, 0, 0x1c000
	ds_read_b128 v[138:141], v149
	ds_read_b128 v[150:153], v149 offset:1024
	ds_read_b128 v[154:157], v149 offset:2048
	ds_read_b128 v[158:161], v149 offset:3072
	v_add_u32_e32 v149, s60, v143
	ds_read_b128 v[162:165], v149
	ds_read_b128 v[166:169], v149 offset:1024
	ds_read_b128 v[170:173], v149 offset:2048
	ds_read_b128 v[174:177], v149 offset:3072
	s_add_u32 s36, s36, 0x40000
	s_addc_u32 s37, s37, 0
	s_mov_b32 m0, s44
	v_lshl_add_u64 v[220:221], s[36:37], 0, v[128:129]
	ds_read_b128 v[178:181], v147 offset:32768
	ds_read_b128 v[182:185], v147 offset:33792
	ds_read_b128 v[190:193], v147 offset:34816
	ds_read_b128 v[194:197], v147 offset:35840
	ds_read_b128 v[198:201], v147 offset:36864
	ds_read_b128 v[202:205], v147 offset:37888
	ds_read_b128 v[206:209], v147 offset:38912
	ds_read_b128 v[210:213], v147 offset:39936
	global_load_lds_dwordx4 v[220:221], off
	v_lshl_add_u64 v[220:221], s[36:37], 0, v[130:131]
	s_mov_b32 m0, s45
	s_nop 0
	global_load_lds_dwordx4 v[220:221], off
	s_waitcnt vmcnt(8)
	s_waitcnt lgkmcnt(0)
	s_barrier
	s_waitcnt lgkmcnt(0)
	v_mfma_f32_16x16x32_bf16 v[120:123], v[138:141], v[178:181], v[120:123]
	v_mfma_f32_16x16x32_bf16 v[124:127], v[154:157], v[178:181], v[124:127]
	v_mfma_f32_16x16x32_bf16 v[108:111], v[138:141], v[190:193], v[108:111]
	v_mfma_f32_16x16x32_bf16 v[104:107], v[154:157], v[190:193], v[104:107]
	v_mfma_f32_16x16x32_bf16 v[92:95], v[138:141], v[198:201], v[92:95]
	v_mfma_f32_16x16x32_bf16 v[88:91], v[154:157], v[198:201], v[88:91]
	v_mfma_f32_16x16x32_bf16 v[76:79], v[138:141], v[206:209], v[76:79]
	v_mfma_f32_16x16x32_bf16 v[72:75], v[154:157], v[206:209], v[72:75]
	v_mfma_f32_16x16x32_bf16 v[120:123], v[150:153], v[182:185], v[120:123]
	v_mfma_f32_16x16x32_bf16 v[124:127], v[158:161], v[182:185], v[124:127]
	v_mfma_f32_16x16x32_bf16 v[108:111], v[150:153], v[194:197], v[108:111]
	v_mfma_f32_16x16x32_bf16 v[104:107], v[158:161], v[194:197], v[104:107]
	v_mfma_f32_16x16x32_bf16 v[92:95], v[150:153], v[202:205], v[92:95]
	v_mfma_f32_16x16x32_bf16 v[88:91], v[158:161], v[202:205], v[88:91]
	v_mfma_f32_16x16x32_bf16 v[76:79], v[150:153], v[210:213], v[76:79]
	v_mfma_f32_16x16x32_bf16 v[72:75], v[158:161], v[210:213], v[72:75]
	v_mfma_f32_16x16x32_bf16 v[116:119], v[162:165], v[178:181], v[116:119]
	v_mfma_f32_16x16x32_bf16 v[112:115], v[170:173], v[178:181], v[112:115]
	v_mfma_f32_16x16x32_bf16 v[100:103], v[162:165], v[190:193], v[100:103]
	v_mfma_f32_16x16x32_bf16 v[96:99], v[170:173], v[190:193], v[96:99]
	v_mfma_f32_16x16x32_bf16 v[84:87], v[162:165], v[198:201], v[84:87]
	v_mfma_f32_16x16x32_bf16 v[80:83], v[170:173], v[198:201], v[80:83]
	v_mfma_f32_16x16x32_bf16 v[68:71], v[162:165], v[206:209], v[68:71]
	v_mfma_f32_16x16x32_bf16 v[64:67], v[170:173], v[206:209], v[64:67]
	v_mfma_f32_16x16x32_bf16 v[116:119], v[166:169], v[182:185], v[116:119]
	v_mfma_f32_16x16x32_bf16 v[112:115], v[174:177], v[182:185], v[112:115]
	v_mfma_f32_16x16x32_bf16 v[100:103], v[166:169], v[194:197], v[100:103]
	v_mfma_f32_16x16x32_bf16 v[96:99], v[174:177], v[194:197], v[96:99]
	v_mfma_f32_16x16x32_bf16 v[84:87], v[166:169], v[202:205], v[84:87]
	v_mfma_f32_16x16x32_bf16 v[80:83], v[174:177], v[202:205], v[80:83]
	v_mfma_f32_16x16x32_bf16 v[68:71], v[166:169], v[210:213], v[68:71]
	v_mfma_f32_16x16x32_bf16 v[64:67], v[174:177], v[210:213], v[64:67]
	s_barrier
	s_add_i32 s36, s59, s41
	v_lshl_add_u64 v[186:187], v[186:187], 0, s[16:17]
	s_mov_b32 m0, s36
	ds_read_b128 v[178:181], v147 offset:49152
	ds_read_b128 v[182:185], v147 offset:50176
	ds_read_b128 v[190:193], v147 offset:51200
	ds_read_b128 v[194:197], v147 offset:52224
	ds_read_b128 v[198:201], v147 offset:53248
	ds_read_b128 v[202:205], v147 offset:54272
	ds_read_b128 v[206:209], v147 offset:55296
	ds_read_b128 v[210:213], v147 offset:56320
	global_load_lds_dwordx4 v[186:187], off
	s_add_i32 m0, s36, 0x2000
	s_add_u32 s4, s4, 0x40080
	v_lshl_add_u64 v[186:187], v[214:215], 0, s[16:17]
	s_addc_u32 s5, s5, 0
	s_add_i32 s36, s60, s41
	global_load_lds_dwordx4 v[186:187], off
	v_lshl_add_u64 v[186:187], s[4:5], 0, v[128:129]
	s_mov_b32 m0, s36
	s_nop 0
	global_load_lds_dwordx4 v[186:187], off
	v_lshl_add_u64 v[186:187], s[4:5], 0, v[130:131]
	s_add_i32 m0, s36, 0x2000
	s_nop 0
	global_load_lds_dwordx4 v[186:187], off
	v_lshl_add_u64 v[186:187], v[216:217], 0, s[16:17]
	s_mov_b32 m0, s48
	s_nop 0
	global_load_lds_dwordx4 v[186:187], off
	v_lshl_add_u64 v[186:187], v[218:219], 0, s[16:17]
	s_mov_b32 m0, s49
	s_nop 0
	global_load_lds_dwordx4 v[186:187], off
	s_waitcnt vmcnt(8)
	s_waitcnt lgkmcnt(0)
	s_barrier
	s_waitcnt lgkmcnt(0)
	v_mfma_f32_16x16x32_bf16 v[60:63], v[138:141], v[178:181], v[60:63]
	v_mfma_f32_16x16x32_bf16 v[56:59], v[154:157], v[178:181], v[56:59]
	v_mfma_f32_16x16x32_bf16 v[44:47], v[138:141], v[190:193], v[44:47]
	v_mfma_f32_16x16x32_bf16 v[40:43], v[154:157], v[190:193], v[40:43]
	v_mfma_f32_16x16x32_bf16 v[28:31], v[138:141], v[198:201], v[28:31]
	v_mfma_f32_16x16x32_bf16 v[24:27], v[154:157], v[198:201], v[24:27]
	v_mfma_f32_16x16x32_bf16 v[12:15], v[138:141], v[206:209], v[12:15]
	v_mfma_f32_16x16x32_bf16 v[8:11], v[154:157], v[206:209], v[8:11]
	v_mfma_f32_16x16x32_bf16 v[60:63], v[150:153], v[182:185], v[60:63]
	v_mfma_f32_16x16x32_bf16 v[56:59], v[158:161], v[182:185], v[56:59]
	v_mfma_f32_16x16x32_bf16 v[44:47], v[150:153], v[194:197], v[44:47]
	v_mfma_f32_16x16x32_bf16 v[40:43], v[158:161], v[194:197], v[40:43]
	v_mfma_f32_16x16x32_bf16 v[28:31], v[150:153], v[202:205], v[28:31]
	v_mfma_f32_16x16x32_bf16 v[24:27], v[158:161], v[202:205], v[24:27]
	v_mfma_f32_16x16x32_bf16 v[12:15], v[150:153], v[210:213], v[12:15]
	v_mfma_f32_16x16x32_bf16 v[8:11], v[158:161], v[210:213], v[8:11]
	v_mfma_f32_16x16x32_bf16 v[52:55], v[162:165], v[178:181], v[52:55]
	v_mfma_f32_16x16x32_bf16 v[48:51], v[170:173], v[178:181], v[48:51]
	v_mfma_f32_16x16x32_bf16 v[36:39], v[162:165], v[190:193], v[36:39]
	v_mfma_f32_16x16x32_bf16 v[32:35], v[170:173], v[190:193], v[32:35]
	v_mfma_f32_16x16x32_bf16 v[20:23], v[162:165], v[198:201], v[20:23]
	v_mfma_f32_16x16x32_bf16 v[16:19], v[170:173], v[198:201], v[16:19]
	v_mfma_f32_16x16x32_bf16 v[4:7], v[162:165], v[206:209], v[4:7]
	v_mfma_f32_16x16x32_bf16 v[0:3], v[170:173], v[206:209], v[0:3]
	v_mfma_f32_16x16x32_bf16 v[52:55], v[166:169], v[182:185], v[52:55]
	v_mfma_f32_16x16x32_bf16 v[48:51], v[174:177], v[182:185], v[48:51]
	v_mfma_f32_16x16x32_bf16 v[36:39], v[166:169], v[194:197], v[36:39]
	v_mfma_f32_16x16x32_bf16 v[32:35], v[174:177], v[194:197], v[32:35]
	v_mfma_f32_16x16x32_bf16 v[20:23], v[166:169], v[202:205], v[20:23]
	v_mfma_f32_16x16x32_bf16 v[16:19], v[174:177], v[202:205], v[16:19]
	v_mfma_f32_16x16x32_bf16 v[4:7], v[166:169], v[210:213], v[4:7]
	v_mfma_f32_16x16x32_bf16 v[0:3], v[174:177], v[210:213], v[0:3]
	s_barrier
	s_add_u32 s34, s34, 0x100
	s_addc_u32 s35, s35, 0
	s_add_u32 s23, s23, 0x100
	s_addc_u32 s25, s25, 0
	s_cmp_ge_i32 s31, s47
	s_mov_b32 s4, s31
	s_cbranch_scc0 .LBB0_1370
	s_branch .LBB0_1371

.LBB0_1370:
	ds_read_b128 v[138:141], v145
	ds_read_b128 v[150:153], v145 offset:1024
	ds_read_b128 v[154:157], v145 offset:2048
	ds_read_b128 v[158:161], v145 offset:3072
	ds_read_b128 v[162:165], v146
	ds_read_b128 v[166:169], v146 offset:1024
	ds_read_b128 v[170:173], v146 offset:2048
	ds_read_b128 v[174:177], v146 offset:3072
	s_add_i32 s31, s4, 2
	s_add_u32 s5, s34, 0xfffc0080
	s_addc_u32 s36, s35, -1
	s_cmp_eq_u32 s50, s4
	s_cselect_b32 s4, s28, s23
	s_cselect_b32 s37, s27, s36
	s_cselect_b32 s36, s26, s5
	s_cselect_b32 s5, s29, s25
	v_lshl_add_u64 v[186:187], s[34:35], 0, v[132:133]
	s_add_i32 m0, s42, 0xc000
	ds_read_b128 v[178:181], v147
	ds_read_b128 v[182:185], v147 offset:1024
	ds_read_b128 v[190:193], v147 offset:2048
	ds_read_b128 v[194:197], v147 offset:3072
	ds_read_b128 v[198:201], v147 offset:4096
	ds_read_b128 v[202:205], v147 offset:5120
	ds_read_b128 v[206:209], v147 offset:6144
	ds_read_b128 v[210:213], v147 offset:7168
	global_load_lds_dwordx4 v[186:187], off
	v_lshl_add_u64 v[186:187], s[34:35], 0, v[134:135]
	s_add_i32 m0, s42, 0xe000
	s_nop 0
	global_load_lds_dwordx4 v[186:187], off
	s_waitcnt vmcnt(8)
	s_waitcnt lgkmcnt(0)
	s_barrier
	s_waitcnt lgkmcnt(0)
	v_mfma_f32_16x16x32_bf16 v[120:123], v[138:141], v[178:181], v[120:123]
	v_mfma_f32_16x16x32_bf16 v[124:127], v[154:157], v[178:181], v[124:127]
	v_mfma_f32_16x16x32_bf16 v[108:111], v[138:141], v[190:193], v[108:111]
	v_mfma_f32_16x16x32_bf16 v[104:107], v[154:157], v[190:193], v[104:107]
	v_mfma_f32_16x16x32_bf16 v[92:95], v[138:141], v[198:201], v[92:95]
	v_mfma_f32_16x16x32_bf16 v[88:91], v[154:157], v[198:201], v[88:91]
	v_mfma_f32_16x16x32_bf16 v[76:79], v[138:141], v[206:209], v[76:79]
	v_mfma_f32_16x16x32_bf16 v[72:75], v[154:157], v[206:209], v[72:75]
	v_mfma_f32_16x16x32_bf16 v[120:123], v[150:153], v[182:185], v[120:123]
	v_mfma_f32_16x16x32_bf16 v[124:127], v[158:161], v[182:185], v[124:127]
	v_mfma_f32_16x16x32_bf16 v[108:111], v[150:153], v[194:197], v[108:111]
	v_mfma_f32_16x16x32_bf16 v[104:107], v[158:161], v[194:197], v[104:107]
	v_mfma_f32_16x16x32_bf16 v[92:95], v[150:153], v[202:205], v[92:95]
	v_mfma_f32_16x16x32_bf16 v[88:91], v[158:161], v[202:205], v[88:91]
	v_mfma_f32_16x16x32_bf16 v[76:79], v[150:153], v[210:213], v[76:79]
	v_mfma_f32_16x16x32_bf16 v[72:75], v[158:161], v[210:213], v[72:75]
	v_mfma_f32_16x16x32_bf16 v[116:119], v[162:165], v[178:181], v[116:119]
	v_mfma_f32_16x16x32_bf16 v[112:115], v[170:173], v[178:181], v[112:115]
	v_mfma_f32_16x16x32_bf16 v[100:103], v[162:165], v[190:193], v[100:103]
	v_mfma_f32_16x16x32_bf16 v[96:99], v[170:173], v[190:193], v[96:99]
	v_mfma_f32_16x16x32_bf16 v[84:87], v[162:165], v[198:201], v[84:87]
	v_mfma_f32_16x16x32_bf16 v[80:83], v[170:173], v[198:201], v[80:83]
	v_mfma_f32_16x16x32_bf16 v[68:71], v[162:165], v[206:209], v[68:71]
	v_mfma_f32_16x16x32_bf16 v[64:67], v[170:173], v[206:209], v[64:67]
	v_mfma_f32_16x16x32_bf16 v[116:119], v[166:169], v[182:185], v[116:119]
	v_mfma_f32_16x16x32_bf16 v[112:115], v[174:177], v[182:185], v[112:115]
	v_mfma_f32_16x16x32_bf16 v[100:103], v[166:169], v[194:197], v[100:103]
	v_mfma_f32_16x16x32_bf16 v[96:99], v[174:177], v[194:197], v[96:99]
	v_mfma_f32_16x16x32_bf16 v[84:87], v[166:169], v[202:205], v[84:87]
	v_mfma_f32_16x16x32_bf16 v[80:83], v[174:177], v[202:205], v[80:83]
	v_mfma_f32_16x16x32_bf16 v[68:71], v[166:169], v[210:213], v[68:71]
	v_mfma_f32_16x16x32_bf16 v[64:67], v[174:177], v[210:213], v[64:67]
	s_barrier
	s_add_i32 s59, s55, s41
	v_lshl_add_u64 v[186:187], s[4:5], 0, v[128:129]
	s_mov_b32 m0, s59
	ds_read_b128 v[178:181], v147 offset:16384
	ds_read_b128 v[182:185], v147 offset:17408
	ds_read_b128 v[190:193], v147 offset:18432
	ds_read_b128 v[194:197], v147 offset:19456
	ds_read_b128 v[198:201], v147 offset:20480
	ds_read_b128 v[202:205], v147 offset:21504
	ds_read_b128 v[206:209], v147 offset:22528
	ds_read_b128 v[210:213], v147 offset:23552
	global_load_lds_dwordx4 v[186:187], off
	s_add_i32 m0, s59, 0x2000
	s_add_u32 s60, s4, 0x40000
	v_lshl_add_u64 v[214:215], s[4:5], 0, v[130:131]
	s_addc_u32 s61, s5, 0
	s_add_i32 s59, s56, s41
	global_load_lds_dwordx4 v[214:215], off
	v_lshl_add_u64 v[216:217], s[60:61], 0, v[128:129]
	s_mov_b32 m0, s59
	v_lshl_add_u64 v[218:219], s[36:37], 0, v[130:131]
	global_load_lds_dwordx4 v[216:217], off
	v_lshl_add_u64 v[216:217], s[60:61], 0, v[130:131]
	s_add_i32 m0, s59, 0x2000
	s_nop 0
	global_load_lds_dwordx4 v[216:217], off
	v_lshl_add_u64 v[216:217], s[36:37], 0, v[128:129]
	s_mov_b32 m0, s42
	s_nop 0
	global_load_lds_dwordx4 v[216:217], off
	s_mov_b32 m0, s43
	s_nop 0
	global_load_lds_dwordx4 v[218:219], off
	s_waitcnt vmcnt(8)
	s_waitcnt lgkmcnt(0)
	s_barrier
	s_waitcnt lgkmcnt(0)
	v_mfma_f32_16x16x32_bf16 v[60:63], v[138:141], v[178:181], v[60:63]
	v_mfma_f32_16x16x32_bf16 v[56:59], v[154:157], v[178:181], v[56:59]
	v_mfma_f32_16x16x32_bf16 v[44:47], v[138:141], v[190:193], v[44:47]
	v_mfma_f32_16x16x32_bf16 v[40:43], v[154:157], v[190:193], v[40:43]
	v_mfma_f32_16x16x32_bf16 v[28:31], v[138:141], v[198:201], v[28:31]
	v_mfma_f32_16x16x32_bf16 v[24:27], v[154:157], v[198:201], v[24:27]
	v_mfma_f32_16x16x32_bf16 v[12:15], v[138:141], v[206:209], v[12:15]
	v_mfma_f32_16x16x32_bf16 v[8:11], v[154:157], v[206:209], v[8:11]
	v_mfma_f32_16x16x32_bf16 v[60:63], v[150:153], v[182:185], v[60:63]
	v_mfma_f32_16x16x32_bf16 v[56:59], v[158:161], v[182:185], v[56:59]
	v_mfma_f32_16x16x32_bf16 v[44:47], v[150:153], v[194:197], v[44:47]
	v_mfma_f32_16x16x32_bf16 v[40:43], v[158:161], v[194:197], v[40:43]
	v_mfma_f32_16x16x32_bf16 v[28:31], v[150:153], v[202:205], v[28:31]
	v_mfma_f32_16x16x32_bf16 v[24:27], v[158:161], v[202:205], v[24:27]
	v_mfma_f32_16x16x32_bf16 v[12:15], v[150:153], v[210:213], v[12:15]
	v_mfma_f32_16x16x32_bf16 v[8:11], v[158:161], v[210:213], v[8:11]
	v_mfma_f32_16x16x32_bf16 v[52:55], v[162:165], v[178:181], v[52:55]
	v_mfma_f32_16x16x32_bf16 v[48:51], v[170:173], v[178:181], v[48:51]
	v_mfma_f32_16x16x32_bf16 v[36:39], v[162:165], v[190:193], v[36:39]
	v_mfma_f32_16x16x32_bf16 v[32:35], v[170:173], v[190:193], v[32:35]
	v_mfma_f32_16x16x32_bf16 v[20:23], v[162:165], v[198:201], v[20:23]
	v_mfma_f32_16x16x32_bf16 v[16:19], v[170:173], v[198:201], v[16:19]
	v_mfma_f32_16x16x32_bf16 v[4:7], v[162:165], v[206:209], v[4:7]
	v_mfma_f32_16x16x32_bf16 v[0:3], v[170:173], v[206:209], v[0:3]
	v_mfma_f32_16x16x32_bf16 v[52:55], v[166:169], v[182:185], v[52:55]
	v_mfma_f32_16x16x32_bf16 v[48:51], v[174:177], v[182:185], v[48:51]
	v_mfma_f32_16x16x32_bf16 v[36:39], v[166:169], v[194:197], v[36:39]
	v_mfma_f32_16x16x32_bf16 v[32:35], v[174:177], v[194:197], v[32:35]
	v_mfma_f32_16x16x32_bf16 v[20:23], v[166:169], v[202:205], v[20:23]
	v_mfma_f32_16x16x32_bf16 v[16:19], v[174:177], v[202:205], v[16:19]
	v_mfma_f32_16x16x32_bf16 v[4:7], v[166:169], v[210:213], v[4:7]
	v_mfma_f32_16x16x32_bf16 v[0:3], v[174:177], v[210:213], v[0:3]
	s_barrier
	s_add_i32 s59, 0, 0x18000
	v_add_u32_e32 v149, s59, v143
	s_add_i32 s60, 0, 0x1c000
	ds_read_b128 v[138:141], v149
	ds_read_b128 v[150:153], v149 offset:1024
	ds_read_b128 v[154:157], v149 offset:2048
	ds_read_b128 v[158:161], v149 offset:3072
	v_add_u32_e32 v149, s60, v143
	ds_read_b128 v[162:165], v149
	ds_read_b128 v[166:169], v149 offset:1024
	ds_read_b128 v[170:173], v149 offset:2048
	ds_read_b128 v[174:177], v149 offset:3072
	s_add_u32 s36, s36, 0x40000
	s_addc_u32 s37, s37, 0
	s_mov_b32 m0, s44
	v_lshl_add_u64 v[220:221], s[36:37], 0, v[128:129]
	ds_read_b128 v[178:181], v147 offset:32768
	ds_read_b128 v[182:185], v147 offset:33792
	ds_read_b128 v[190:193], v147 offset:34816
	ds_read_b128 v[194:197], v147 offset:35840
	ds_read_b128 v[198:201], v147 offset:36864
	ds_read_b128 v[202:205], v147 offset:37888
	ds_read_b128 v[206:209], v147 offset:38912
	ds_read_b128 v[210:213], v147 offset:39936
	global_load_lds_dwordx4 v[220:221], off
	v_lshl_add_u64 v[220:221], s[36:37], 0, v[130:131]
	s_mov_b32 m0, s45
	s_nop 0
	global_load_lds_dwordx4 v[220:221], off
	s_waitcnt vmcnt(8)
	s_waitcnt lgkmcnt(0)
	s_barrier
	s_waitcnt lgkmcnt(0)
	v_mfma_f32_16x16x32_bf16 v[120:123], v[138:141], v[178:181], v[120:123]
	v_mfma_f32_16x16x32_bf16 v[124:127], v[154:157], v[178:181], v[124:127]
	v_mfma_f32_16x16x32_bf16 v[108:111], v[138:141], v[190:193], v[108:111]
	v_mfma_f32_16x16x32_bf16 v[104:107], v[154:157], v[190:193], v[104:107]
	v_mfma_f32_16x16x32_bf16 v[92:95], v[138:141], v[198:201], v[92:95]
	v_mfma_f32_16x16x32_bf16 v[88:91], v[154:157], v[198:201], v[88:91]
	v_mfma_f32_16x16x32_bf16 v[76:79], v[138:141], v[206:209], v[76:79]
	v_mfma_f32_16x16x32_bf16 v[72:75], v[154:157], v[206:209], v[72:75]
	v_mfma_f32_16x16x32_bf16 v[120:123], v[150:153], v[182:185], v[120:123]
	v_mfma_f32_16x16x32_bf16 v[124:127], v[158:161], v[182:185], v[124:127]
	v_mfma_f32_16x16x32_bf16 v[108:111], v[150:153], v[194:197], v[108:111]
	v_mfma_f32_16x16x32_bf16 v[104:107], v[158:161], v[194:197], v[104:107]
	v_mfma_f32_16x16x32_bf16 v[92:95], v[150:153], v[202:205], v[92:95]
	v_mfma_f32_16x16x32_bf16 v[88:91], v[158:161], v[202:205], v[88:91]
	v_mfma_f32_16x16x32_bf16 v[76:79], v[150:153], v[210:213], v[76:79]
	v_mfma_f32_16x16x32_bf16 v[72:75], v[158:161], v[210:213], v[72:75]
	v_mfma_f32_16x16x32_bf16 v[116:119], v[162:165], v[178:181], v[116:119]
	v_mfma_f32_16x16x32_bf16 v[112:115], v[170:173], v[178:181], v[112:115]
	v_mfma_f32_16x16x32_bf16 v[100:103], v[162:165], v[190:193], v[100:103]
	v_mfma_f32_16x16x32_bf16 v[96:99], v[170:173], v[190:193], v[96:99]
	v_mfma_f32_16x16x32_bf16 v[84:87], v[162:165], v[198:201], v[84:87]
	v_mfma_f32_16x16x32_bf16 v[80:83], v[170:173], v[198:201], v[80:83]
	v_mfma_f32_16x16x32_bf16 v[68:71], v[162:165], v[206:209], v[68:71]
	v_mfma_f32_16x16x32_bf16 v[64:67], v[170:173], v[206:209], v[64:67]
	v_mfma_f32_16x16x32_bf16 v[116:119], v[166:169], v[182:185], v[116:119]
	v_mfma_f32_16x16x32_bf16 v[112:115], v[174:177], v[182:185], v[112:115]
	v_mfma_f32_16x16x32_bf16 v[100:103], v[166:169], v[194:197], v[100:103]
	v_mfma_f32_16x16x32_bf16 v[96:99], v[174:177], v[194:197], v[96:99]
	v_mfma_f32_16x16x32_bf16 v[84:87], v[166:169], v[202:205], v[84:87]
	v_mfma_f32_16x16x32_bf16 v[80:83], v[174:177], v[202:205], v[80:83]
	v_mfma_f32_16x16x32_bf16 v[68:71], v[166:169], v[210:213], v[68:71]
	v_mfma_f32_16x16x32_bf16 v[64:67], v[174:177], v[210:213], v[64:67]
	s_barrier
	s_add_i32 s36, s59, s41
	v_lshl_add_u64 v[186:187], v[186:187], 0, s[16:17]
	s_mov_b32 m0, s36
	ds_read_b128 v[178:181], v147 offset:49152
	ds_read_b128 v[182:185], v147 offset:50176
	ds_read_b128 v[190:193], v147 offset:51200
	ds_read_b128 v[194:197], v147 offset:52224
	ds_read_b128 v[198:201], v147 offset:53248
	ds_read_b128 v[202:205], v147 offset:54272
	ds_read_b128 v[206:209], v147 offset:55296
	ds_read_b128 v[210:213], v147 offset:56320
	global_load_lds_dwordx4 v[186:187], off
	s_add_i32 m0, s36, 0x2000
	s_add_u32 s4, s4, 0x40080
	v_lshl_add_u64 v[186:187], v[214:215], 0, s[16:17]
	s_addc_u32 s5, s5, 0
	s_add_i32 s36, s60, s41
	global_load_lds_dwordx4 v[186:187], off
	v_lshl_add_u64 v[186:187], s[4:5], 0, v[128:129]
	s_mov_b32 m0, s36
	s_nop 0
	global_load_lds_dwordx4 v[186:187], off
	v_lshl_add_u64 v[186:187], s[4:5], 0, v[130:131]
	s_add_i32 m0, s36, 0x2000
	s_nop 0
	global_load_lds_dwordx4 v[186:187], off
	v_lshl_add_u64 v[186:187], v[216:217], 0, s[16:17]
	s_mov_b32 m0, s48
	s_nop 0
	global_load_lds_dwordx4 v[186:187], off
	v_lshl_add_u64 v[186:187], v[218:219], 0, s[16:17]
	s_mov_b32 m0, s49
	s_nop 0
	global_load_lds_dwordx4 v[186:187], off
	s_waitcnt vmcnt(8)
	s_waitcnt lgkmcnt(0)
	s_barrier
	s_waitcnt lgkmcnt(0)
	v_mfma_f32_16x16x32_bf16 v[60:63], v[138:141], v[178:181], v[60:63]
	v_mfma_f32_16x16x32_bf16 v[56:59], v[154:157], v[178:181], v[56:59]
	v_mfma_f32_16x16x32_bf16 v[44:47], v[138:141], v[190:193], v[44:47]
	v_mfma_f32_16x16x32_bf16 v[40:43], v[154:157], v[190:193], v[40:43]
	v_mfma_f32_16x16x32_bf16 v[28:31], v[138:141], v[198:201], v[28:31]
	v_mfma_f32_16x16x32_bf16 v[24:27], v[154:157], v[198:201], v[24:27]
	v_mfma_f32_16x16x32_bf16 v[12:15], v[138:141], v[206:209], v[12:15]
	v_mfma_f32_16x16x32_bf16 v[8:11], v[154:157], v[206:209], v[8:11]
	v_mfma_f32_16x16x32_bf16 v[60:63], v[150:153], v[182:185], v[60:63]
	v_mfma_f32_16x16x32_bf16 v[56:59], v[158:161], v[182:185], v[56:59]
	v_mfma_f32_16x16x32_bf16 v[44:47], v[150:153], v[194:197], v[44:47]
	v_mfma_f32_16x16x32_bf16 v[40:43], v[158:161], v[194:197], v[40:43]
	v_mfma_f32_16x16x32_bf16 v[28:31], v[150:153], v[202:205], v[28:31]
	v_mfma_f32_16x16x32_bf16 v[24:27], v[158:161], v[202:205], v[24:27]
	v_mfma_f32_16x16x32_bf16 v[12:15], v[150:153], v[210:213], v[12:15]
	v_mfma_f32_16x16x32_bf16 v[8:11], v[158:161], v[210:213], v[8:11]
	v_mfma_f32_16x16x32_bf16 v[52:55], v[162:165], v[178:181], v[52:55]
	v_mfma_f32_16x16x32_bf16 v[48:51], v[170:173], v[178:181], v[48:51]
	v_mfma_f32_16x16x32_bf16 v[36:39], v[162:165], v[190:193], v[36:39]
	v_mfma_f32_16x16x32_bf16 v[32:35], v[170:173], v[190:193], v[32:35]
	v_mfma_f32_16x16x32_bf16 v[20:23], v[162:165], v[198:201], v[20:23]
	v_mfma_f32_16x16x32_bf16 v[16:19], v[170:173], v[198:201], v[16:19]
	v_mfma_f32_16x16x32_bf16 v[4:7], v[162:165], v[206:209], v[4:7]
	v_mfma_f32_16x16x32_bf16 v[0:3], v[170:173], v[206:209], v[0:3]
	v_mfma_f32_16x16x32_bf16 v[52:55], v[166:169], v[182:185], v[52:55]
	v_mfma_f32_16x16x32_bf16 v[48:51], v[174:177], v[182:185], v[48:51]
	v_mfma_f32_16x16x32_bf16 v[36:39], v[166:169], v[194:197], v[36:39]
	v_mfma_f32_16x16x32_bf16 v[32:35], v[174:177], v[194:197], v[32:35]
	v_mfma_f32_16x16x32_bf16 v[20:23], v[166:169], v[202:205], v[20:23]
	v_mfma_f32_16x16x32_bf16 v[16:19], v[174:177], v[202:205], v[16:19]
	v_mfma_f32_16x16x32_bf16 v[4:7], v[166:169], v[210:213], v[4:7]
	v_mfma_f32_16x16x32_bf16 v[0:3], v[174:177], v[210:213], v[0:3]
	s_barrier
	s_add_u32 s34, s34, 0x100
	s_addc_u32 s35, s35, 0
	s_add_u32 s23, s23, 0x100
	s_addc_u32 s25, s25, 0
	s_cmp_ge_i32 s31, s47
	s_mov_b32 s4, s31
	s_cbranch_scc0 .LBB0_1370

.LBB0_1462:
	s_andn2_b64 vcc, exec, s[14:15]
	s_waitcnt vmcnt(0)
	s_cbranch_vccnz .Lpz_zero_4
	s_add_u32 s30, s4, 0x40080
	s_addc_u32 s31, s5, 0
	s_add_u32 s19, s34, 0x100
	s_addc_u32 s21, s35, 0
	s_mov_b32 s4, 0
	ds_read_b128 v[148:151], v143
	ds_read_b128 v[152:155], v143 offset:1024
	ds_read_b128 v[156:159], v143 offset:2048
	ds_read_b128 v[160:163], v143 offset:3072
	ds_read_b128 v[164:167], v144
	ds_read_b128 v[168:171], v144 offset:1024
	ds_read_b128 v[172:175], v144 offset:2048
	ds_read_b128 v[176:179], v144 offset:3072
	s_add_i32 s57, s4, 2
	s_add_u32 s5, s30, 0xfffc0080
	s_addc_u32 s34, s31, -1
	s_cmp_eq_u32 s46, s4
	s_cselect_b32 s4, s24, s19
	s_cselect_b32 s35, s23, s34
	s_cselect_b32 s34, s22, s5
	s_cselect_b32 s5, s25, s21
	v_lshl_add_u64 v[138:139], s[30:31], 0, v[132:133]
	s_add_i32 m0, s27, 0xc000
	ds_read_b128 v[180:183], v145
	ds_read_b128 v[184:187], v145 offset:1024
	ds_read_b128 v[190:193], v145 offset:2048
	ds_read_b128 v[194:197], v145 offset:3072
	ds_read_b128 v[198:201], v145 offset:4096
	ds_read_b128 v[202:205], v145 offset:5120
	ds_read_b128 v[206:209], v145 offset:6144
	ds_read_b128 v[210:213], v145 offset:7168
	global_load_lds_dwordx4 v[138:139], off
	v_lshl_add_u64 v[138:139], s[30:31], 0, v[134:135]
	s_add_i32 m0, s27, 0xe000
	s_nop 0
	global_load_lds_dwordx4 v[138:139], off
	s_waitcnt vmcnt(8)
	s_waitcnt lgkmcnt(0)
	s_barrier
	s_waitcnt lgkmcnt(0)
	v_mfma_f32_16x16x32_bf16 v[116:119], v[148:151], v[180:183], 0
	v_mfma_f32_16x16x32_bf16 v[112:115], v[156:159], v[180:183], 0
	v_mfma_f32_16x16x32_bf16 v[100:103], v[148:151], v[190:193], 0
	v_mfma_f32_16x16x32_bf16 v[96:99], v[156:159], v[190:193], 0
	v_mfma_f32_16x16x32_bf16 v[84:87], v[148:151], v[198:201], 0
	v_mfma_f32_16x16x32_bf16 v[80:83], v[156:159], v[198:201], 0
	v_mfma_f32_16x16x32_bf16 v[68:71], v[148:151], v[206:209], 0
	v_mfma_f32_16x16x32_bf16 v[64:67], v[156:159], v[206:209], 0
	v_mfma_f32_16x16x32_bf16 v[116:119], v[152:155], v[184:187], v[116:119]
	v_mfma_f32_16x16x32_bf16 v[112:115], v[160:163], v[184:187], v[112:115]
	v_mfma_f32_16x16x32_bf16 v[100:103], v[152:155], v[194:197], v[100:103]
	v_mfma_f32_16x16x32_bf16 v[96:99], v[160:163], v[194:197], v[96:99]
	v_mfma_f32_16x16x32_bf16 v[84:87], v[152:155], v[202:205], v[84:87]
	v_mfma_f32_16x16x32_bf16 v[80:83], v[160:163], v[202:205], v[80:83]
	v_mfma_f32_16x16x32_bf16 v[68:71], v[152:155], v[210:213], v[68:71]
	v_mfma_f32_16x16x32_bf16 v[64:67], v[160:163], v[210:213], v[64:67]
	v_mfma_f32_16x16x32_bf16 v[124:127], v[164:167], v[180:183], 0
	v_mfma_f32_16x16x32_bf16 v[120:123], v[172:175], v[180:183], 0
	v_mfma_f32_16x16x32_bf16 v[108:111], v[164:167], v[190:193], 0
	v_mfma_f32_16x16x32_bf16 v[104:107], v[172:175], v[190:193], 0
	v_mfma_f32_16x16x32_bf16 v[92:95], v[164:167], v[198:201], 0
	v_mfma_f32_16x16x32_bf16 v[88:91], v[172:175], v[198:201], 0
	v_mfma_f32_16x16x32_bf16 v[76:79], v[164:167], v[206:209], 0
	v_mfma_f32_16x16x32_bf16 v[72:75], v[172:175], v[206:209], 0
	v_mfma_f32_16x16x32_bf16 v[124:127], v[168:171], v[184:187], v[124:127]
	v_mfma_f32_16x16x32_bf16 v[120:123], v[176:179], v[184:187], v[120:123]
	v_mfma_f32_16x16x32_bf16 v[108:111], v[168:171], v[194:197], v[108:111]
	v_mfma_f32_16x16x32_bf16 v[104:107], v[176:179], v[194:197], v[104:107]
	v_mfma_f32_16x16x32_bf16 v[92:95], v[168:171], v[202:205], v[92:95]
	v_mfma_f32_16x16x32_bf16 v[88:91], v[176:179], v[202:205], v[88:91]
	v_mfma_f32_16x16x32_bf16 v[76:79], v[168:171], v[210:213], v[76:79]
	v_mfma_f32_16x16x32_bf16 v[72:75], v[176:179], v[210:213], v[72:75]
	s_barrier
	s_add_i32 s58, s52, s33
	v_lshl_add_u64 v[138:139], s[4:5], 0, v[128:129]
	s_mov_b32 m0, s58
	ds_read_b128 v[180:183], v145 offset:16384
	ds_read_b128 v[184:187], v145 offset:17408
	ds_read_b128 v[190:193], v145 offset:18432
	ds_read_b128 v[194:197], v145 offset:19456
	ds_read_b128 v[198:201], v145 offset:20480
	ds_read_b128 v[202:205], v145 offset:21504
	ds_read_b128 v[206:209], v145 offset:22528
	ds_read_b128 v[210:213], v145 offset:23552
	global_load_lds_dwordx4 v[138:139], off
	s_add_i32 m0, s58, 0x2000
	s_add_u32 s58, s4, 0x40000
	v_lshl_add_u64 v[214:215], s[4:5], 0, v[130:131]
	s_addc_u32 s59, s5, 0
	s_add_i32 s60, s53, s33
	global_load_lds_dwordx4 v[214:215], off
	v_lshl_add_u64 v[216:217], s[58:59], 0, v[128:129]
	s_mov_b32 m0, s60
	v_lshl_add_u64 v[218:219], s[34:35], 0, v[130:131]
	global_load_lds_dwordx4 v[216:217], off
	v_lshl_add_u64 v[216:217], s[58:59], 0, v[130:131]
	s_add_i32 m0, s60, 0x2000
	s_nop 0
	global_load_lds_dwordx4 v[216:217], off
	v_lshl_add_u64 v[216:217], s[34:35], 0, v[128:129]
	s_mov_b32 m0, s27
	s_nop 0
	global_load_lds_dwordx4 v[216:217], off
	s_mov_b32 m0, s29
	s_nop 0
	global_load_lds_dwordx4 v[218:219], off
	s_waitcnt vmcnt(8)
	s_waitcnt lgkmcnt(0)
	s_barrier
	s_waitcnt lgkmcnt(0)
	v_mfma_f32_16x16x32_bf16 v[52:55], v[148:151], v[180:183], 0
	v_mfma_f32_16x16x32_bf16 v[48:51], v[156:159], v[180:183], 0
	v_mfma_f32_16x16x32_bf16 v[36:39], v[148:151], v[190:193], 0
	v_mfma_f32_16x16x32_bf16 v[32:35], v[156:159], v[190:193], 0
	v_mfma_f32_16x16x32_bf16 v[20:23], v[148:151], v[198:201], 0
	v_mfma_f32_16x16x32_bf16 v[16:19], v[156:159], v[198:201], 0
	v_mfma_f32_16x16x32_bf16 v[4:7], v[148:151], v[206:209], 0
	v_mfma_f32_16x16x32_bf16 v[0:3], v[156:159], v[206:209], 0
	v_mfma_f32_16x16x32_bf16 v[52:55], v[152:155], v[184:187], v[52:55]
	v_mfma_f32_16x16x32_bf16 v[48:51], v[160:163], v[184:187], v[48:51]
	v_mfma_f32_16x16x32_bf16 v[36:39], v[152:155], v[194:197], v[36:39]
	v_mfma_f32_16x16x32_bf16 v[32:35], v[160:163], v[194:197], v[32:35]
	v_mfma_f32_16x16x32_bf16 v[20:23], v[152:155], v[202:205], v[20:23]
	v_mfma_f32_16x16x32_bf16 v[16:19], v[160:163], v[202:205], v[16:19]
	v_mfma_f32_16x16x32_bf16 v[4:7], v[152:155], v[210:213], v[4:7]
	v_mfma_f32_16x16x32_bf16 v[0:3], v[160:163], v[210:213], v[0:3]
	v_mfma_f32_16x16x32_bf16 v[60:63], v[164:167], v[180:183], 0
	v_mfma_f32_16x16x32_bf16 v[56:59], v[172:175], v[180:183], 0
	v_mfma_f32_16x16x32_bf16 v[44:47], v[164:167], v[190:193], 0
	v_mfma_f32_16x16x32_bf16 v[40:43], v[172:175], v[190:193], 0
	v_mfma_f32_16x16x32_bf16 v[28:31], v[164:167], v[198:201], 0
	v_mfma_f32_16x16x32_bf16 v[24:27], v[172:175], v[198:201], 0
	v_mfma_f32_16x16x32_bf16 v[12:15], v[164:167], v[206:209], 0
	v_mfma_f32_16x16x32_bf16 v[8:11], v[172:175], v[206:209], 0
	v_mfma_f32_16x16x32_bf16 v[60:63], v[168:171], v[184:187], v[60:63]
	v_mfma_f32_16x16x32_bf16 v[56:59], v[176:179], v[184:187], v[56:59]
	v_mfma_f32_16x16x32_bf16 v[44:47], v[168:171], v[194:197], v[44:47]
	v_mfma_f32_16x16x32_bf16 v[40:43], v[176:179], v[194:197], v[40:43]
	v_mfma_f32_16x16x32_bf16 v[28:31], v[168:171], v[202:205], v[28:31]
	v_mfma_f32_16x16x32_bf16 v[24:27], v[176:179], v[202:205], v[24:27]
	v_mfma_f32_16x16x32_bf16 v[12:15], v[168:171], v[210:213], v[12:15]
	v_mfma_f32_16x16x32_bf16 v[8:11], v[176:179], v[210:213], v[8:11]
	s_barrier
	s_add_i32 s58, 0, 0x18000
	v_add_u32_e32 v147, s58, v141
	s_add_i32 s59, 0, 0x1c000
	ds_read_b128 v[148:151], v147
	ds_read_b128 v[152:155], v147 offset:1024
	ds_read_b128 v[156:159], v147 offset:2048
	ds_read_b128 v[160:163], v147 offset:3072
	v_add_u32_e32 v147, s59, v141
	ds_read_b128 v[164:167], v147
	ds_read_b128 v[168:171], v147 offset:1024
	ds_read_b128 v[172:175], v147 offset:2048
	ds_read_b128 v[176:179], v147 offset:3072
	s_add_u32 s34, s34, 0x40000
	s_addc_u32 s35, s35, 0
	s_mov_b32 m0, s40
	v_lshl_add_u64 v[220:221], s[34:35], 0, v[128:129]
	ds_read_b128 v[180:183], v145 offset:32768
	ds_read_b128 v[184:187], v145 offset:33792
	ds_read_b128 v[190:193], v145 offset:34816
	ds_read_b128 v[194:197], v145 offset:35840
	ds_read_b128 v[198:201], v145 offset:36864
	ds_read_b128 v[202:205], v145 offset:37888
	ds_read_b128 v[206:209], v145 offset:38912
	ds_read_b128 v[210:213], v145 offset:39936
	global_load_lds_dwordx4 v[220:221], off
	v_lshl_add_u64 v[220:221], s[34:35], 0, v[130:131]
	s_mov_b32 m0, s41
	s_nop 0
	global_load_lds_dwordx4 v[220:221], off
	s_waitcnt vmcnt(8)
	s_waitcnt lgkmcnt(0)
	s_barrier
	s_waitcnt lgkmcnt(0)
	v_mfma_f32_16x16x32_bf16 v[116:119], v[148:151], v[180:183], v[116:119]
	v_mfma_f32_16x16x32_bf16 v[112:115], v[156:159], v[180:183], v[112:115]
	v_mfma_f32_16x16x32_bf16 v[100:103], v[148:151], v[190:193], v[100:103]
	v_mfma_f32_16x16x32_bf16 v[96:99], v[156:159], v[190:193], v[96:99]
	v_mfma_f32_16x16x32_bf16 v[84:87], v[148:151], v[198:201], v[84:87]
	v_mfma_f32_16x16x32_bf16 v[80:83], v[156:159], v[198:201], v[80:83]
	v_mfma_f32_16x16x32_bf16 v[68:71], v[148:151], v[206:209], v[68:71]
	v_mfma_f32_16x16x32_bf16 v[64:67], v[156:159], v[206:209], v[64:67]
	v_mfma_f32_16x16x32_bf16 v[116:119], v[152:155], v[184:187], v[116:119]
	v_mfma_f32_16x16x32_bf16 v[112:115], v[160:163], v[184:187], v[112:115]
	v_mfma_f32_16x16x32_bf16 v[100:103], v[152:155], v[194:197], v[100:103]
	v_mfma_f32_16x16x32_bf16 v[96:99], v[160:163], v[194:197], v[96:99]
	v_mfma_f32_16x16x32_bf16 v[84:87], v[152:155], v[202:205], v[84:87]
	v_mfma_f32_16x16x32_bf16 v[80:83], v[160:163], v[202:205], v[80:83]
	v_mfma_f32_16x16x32_bf16 v[68:71], v[152:155], v[210:213], v[68:71]
	v_mfma_f32_16x16x32_bf16 v[64:67], v[160:163], v[210:213], v[64:67]
	v_mfma_f32_16x16x32_bf16 v[124:127], v[164:167], v[180:183], v[124:127]
	v_mfma_f32_16x16x32_bf16 v[120:123], v[172:175], v[180:183], v[120:123]
	v_mfma_f32_16x16x32_bf16 v[108:111], v[164:167], v[190:193], v[108:111]
	v_mfma_f32_16x16x32_bf16 v[104:107], v[172:175], v[190:193], v[104:107]
	v_mfma_f32_16x16x32_bf16 v[92:95], v[164:167], v[198:201], v[92:95]
	v_mfma_f32_16x16x32_bf16 v[88:91], v[172:175], v[198:201], v[88:91]
	v_mfma_f32_16x16x32_bf16 v[76:79], v[164:167], v[206:209], v[76:79]
	v_mfma_f32_16x16x32_bf16 v[72:75], v[172:175], v[206:209], v[72:75]
	v_mfma_f32_16x16x32_bf16 v[124:127], v[168:171], v[184:187], v[124:127]
	v_mfma_f32_16x16x32_bf16 v[120:123], v[176:179], v[184:187], v[120:123]
	v_mfma_f32_16x16x32_bf16 v[108:111], v[168:171], v[194:197], v[108:111]
	v_mfma_f32_16x16x32_bf16 v[104:107], v[176:179], v[194:197], v[104:107]
	v_mfma_f32_16x16x32_bf16 v[92:95], v[168:171], v[202:205], v[92:95]
	v_mfma_f32_16x16x32_bf16 v[88:91], v[176:179], v[202:205], v[88:91]
	v_mfma_f32_16x16x32_bf16 v[76:79], v[168:171], v[210:213], v[76:79]
	v_mfma_f32_16x16x32_bf16 v[72:75], v[176:179], v[210:213], v[72:75]
	s_barrier
	s_add_i32 s34, s58, s33
	v_lshl_add_u64 v[138:139], v[138:139], 0, s[12:13]
	s_mov_b32 m0, s34
	ds_read_b128 v[180:183], v145 offset:49152
	ds_read_b128 v[184:187], v145 offset:50176
	ds_read_b128 v[190:193], v145 offset:51200
	ds_read_b128 v[194:197], v145 offset:52224
	ds_read_b128 v[198:201], v145 offset:53248
	ds_read_b128 v[202:205], v145 offset:54272
	ds_read_b128 v[206:209], v145 offset:55296
	ds_read_b128 v[210:213], v145 offset:56320
	global_load_lds_dwordx4 v[138:139], off
	s_add_i32 m0, s34, 0x2000
	s_add_u32 s4, s4, 0x40080
	v_lshl_add_u64 v[138:139], v[214:215], 0, s[12:13]
	s_addc_u32 s5, s5, 0
	s_add_i32 s34, s59, s33
	global_load_lds_dwordx4 v[138:139], off
	v_lshl_add_u64 v[138:139], s[4:5], 0, v[128:129]
	s_mov_b32 m0, s34
	s_nop 0
	global_load_lds_dwordx4 v[138:139], off
	v_lshl_add_u64 v[138:139], s[4:5], 0, v[130:131]
	s_add_i32 m0, s34, 0x2000
	s_nop 0
	global_load_lds_dwordx4 v[138:139], off
	v_lshl_add_u64 v[138:139], v[216:217], 0, s[12:13]
	s_mov_b32 m0, s43
	s_nop 0
	global_load_lds_dwordx4 v[138:139], off
	v_lshl_add_u64 v[138:139], v[218:219], 0, s[12:13]
	s_mov_b32 m0, s44
	s_nop 0
	global_load_lds_dwordx4 v[138:139], off
	s_waitcnt vmcnt(8)
	s_waitcnt lgkmcnt(0)
	s_barrier
	s_waitcnt lgkmcnt(0)
	v_mfma_f32_16x16x32_bf16 v[52:55], v[148:151], v[180:183], v[52:55]
	v_mfma_f32_16x16x32_bf16 v[48:51], v[156:159], v[180:183], v[48:51]
	v_mfma_f32_16x16x32_bf16 v[36:39], v[148:151], v[190:193], v[36:39]
	v_mfma_f32_16x16x32_bf16 v[32:35], v[156:159], v[190:193], v[32:35]
	v_mfma_f32_16x16x32_bf16 v[20:23], v[148:151], v[198:201], v[20:23]
	v_mfma_f32_16x16x32_bf16 v[16:19], v[156:159], v[198:201], v[16:19]
	v_mfma_f32_16x16x32_bf16 v[4:7], v[148:151], v[206:209], v[4:7]
	v_mfma_f32_16x16x32_bf16 v[0:3], v[156:159], v[206:209], v[0:3]
	v_mfma_f32_16x16x32_bf16 v[52:55], v[152:155], v[184:187], v[52:55]
	v_mfma_f32_16x16x32_bf16 v[48:51], v[160:163], v[184:187], v[48:51]
	v_mfma_f32_16x16x32_bf16 v[36:39], v[152:155], v[194:197], v[36:39]
	v_mfma_f32_16x16x32_bf16 v[32:35], v[160:163], v[194:197], v[32:35]
	v_mfma_f32_16x16x32_bf16 v[20:23], v[152:155], v[202:205], v[20:23]
	v_mfma_f32_16x16x32_bf16 v[16:19], v[160:163], v[202:205], v[16:19]
	v_mfma_f32_16x16x32_bf16 v[4:7], v[152:155], v[210:213], v[4:7]
	v_mfma_f32_16x16x32_bf16 v[0:3], v[160:163], v[210:213], v[0:3]
	v_mfma_f32_16x16x32_bf16 v[60:63], v[164:167], v[180:183], v[60:63]
	v_mfma_f32_16x16x32_bf16 v[56:59], v[172:175], v[180:183], v[56:59]
	v_mfma_f32_16x16x32_bf16 v[44:47], v[164:167], v[190:193], v[44:47]
	v_mfma_f32_16x16x32_bf16 v[40:43], v[172:175], v[190:193], v[40:43]
	v_mfma_f32_16x16x32_bf16 v[28:31], v[164:167], v[198:201], v[28:31]
	v_mfma_f32_16x16x32_bf16 v[24:27], v[172:175], v[198:201], v[24:27]
	v_mfma_f32_16x16x32_bf16 v[12:15], v[164:167], v[206:209], v[12:15]
	v_mfma_f32_16x16x32_bf16 v[8:11], v[172:175], v[206:209], v[8:11]
	v_mfma_f32_16x16x32_bf16 v[60:63], v[168:171], v[184:187], v[60:63]
	v_mfma_f32_16x16x32_bf16 v[56:59], v[176:179], v[184:187], v[56:59]
	v_mfma_f32_16x16x32_bf16 v[44:47], v[168:171], v[194:197], v[44:47]
	v_mfma_f32_16x16x32_bf16 v[40:43], v[176:179], v[194:197], v[40:43]
	v_mfma_f32_16x16x32_bf16 v[28:31], v[168:171], v[202:205], v[28:31]
	v_mfma_f32_16x16x32_bf16 v[24:27], v[176:179], v[202:205], v[24:27]
	v_mfma_f32_16x16x32_bf16 v[12:15], v[168:171], v[210:213], v[12:15]
	v_mfma_f32_16x16x32_bf16 v[8:11], v[176:179], v[210:213], v[8:11]
	s_barrier
	s_add_u32 s30, s30, 0x100
	s_addc_u32 s31, s31, 0
	s_add_u32 s19, s19, 0x100
	s_addc_u32 s21, s21, 0
	s_cmp_ge_i32 s57, s42
	s_mov_b32 s4, s57
	s_cbranch_scc0 .LBB0_1464
	s_branch .LBB0_1465

.LBB0_1464:
	ds_read_b128 v[148:151], v143
	ds_read_b128 v[152:155], v143 offset:1024
	ds_read_b128 v[156:159], v143 offset:2048
	ds_read_b128 v[160:163], v143 offset:3072
	ds_read_b128 v[164:167], v144
	ds_read_b128 v[168:171], v144 offset:1024
	ds_read_b128 v[172:175], v144 offset:2048
	ds_read_b128 v[176:179], v144 offset:3072
	s_add_i32 s57, s4, 2
	s_add_u32 s5, s30, 0xfffc0080
	s_addc_u32 s34, s31, -1
	s_cmp_eq_u32 s46, s4
	s_cselect_b32 s4, s24, s19
	s_cselect_b32 s35, s23, s34
	s_cselect_b32 s34, s22, s5
	s_cselect_b32 s5, s25, s21
	v_lshl_add_u64 v[138:139], s[30:31], 0, v[132:133]
	s_add_i32 m0, s27, 0xc000
	ds_read_b128 v[180:183], v145
	ds_read_b128 v[184:187], v145 offset:1024
	ds_read_b128 v[190:193], v145 offset:2048
	ds_read_b128 v[194:197], v145 offset:3072
	ds_read_b128 v[198:201], v145 offset:4096
	ds_read_b128 v[202:205], v145 offset:5120
	ds_read_b128 v[206:209], v145 offset:6144
	ds_read_b128 v[210:213], v145 offset:7168
	global_load_lds_dwordx4 v[138:139], off
	v_lshl_add_u64 v[138:139], s[30:31], 0, v[134:135]
	s_add_i32 m0, s27, 0xe000
	s_nop 0
	global_load_lds_dwordx4 v[138:139], off
	s_waitcnt vmcnt(8)
	s_waitcnt lgkmcnt(0)
	s_barrier
	s_waitcnt lgkmcnt(0)
	v_mfma_f32_16x16x32_bf16 v[116:119], v[148:151], v[180:183], v[116:119]
	v_mfma_f32_16x16x32_bf16 v[112:115], v[156:159], v[180:183], v[112:115]
	v_mfma_f32_16x16x32_bf16 v[100:103], v[148:151], v[190:193], v[100:103]
	v_mfma_f32_16x16x32_bf16 v[96:99], v[156:159], v[190:193], v[96:99]
	v_mfma_f32_16x16x32_bf16 v[84:87], v[148:151], v[198:201], v[84:87]
	v_mfma_f32_16x16x32_bf16 v[80:83], v[156:159], v[198:201], v[80:83]
	v_mfma_f32_16x16x32_bf16 v[68:71], v[148:151], v[206:209], v[68:71]
	v_mfma_f32_16x16x32_bf16 v[64:67], v[156:159], v[206:209], v[64:67]
	v_mfma_f32_16x16x32_bf16 v[116:119], v[152:155], v[184:187], v[116:119]
	v_mfma_f32_16x16x32_bf16 v[112:115], v[160:163], v[184:187], v[112:115]
	v_mfma_f32_16x16x32_bf16 v[100:103], v[152:155], v[194:197], v[100:103]
	v_mfma_f32_16x16x32_bf16 v[96:99], v[160:163], v[194:197], v[96:99]
	v_mfma_f32_16x16x32_bf16 v[84:87], v[152:155], v[202:205], v[84:87]
	v_mfma_f32_16x16x32_bf16 v[80:83], v[160:163], v[202:205], v[80:83]
	v_mfma_f32_16x16x32_bf16 v[68:71], v[152:155], v[210:213], v[68:71]
	v_mfma_f32_16x16x32_bf16 v[64:67], v[160:163], v[210:213], v[64:67]
	v_mfma_f32_16x16x32_bf16 v[124:127], v[164:167], v[180:183], v[124:127]
	v_mfma_f32_16x16x32_bf16 v[120:123], v[172:175], v[180:183], v[120:123]
	v_mfma_f32_16x16x32_bf16 v[108:111], v[164:167], v[190:193], v[108:111]
	v_mfma_f32_16x16x32_bf16 v[104:107], v[172:175], v[190:193], v[104:107]
	v_mfma_f32_16x16x32_bf16 v[92:95], v[164:167], v[198:201], v[92:95]
	v_mfma_f32_16x16x32_bf16 v[88:91], v[172:175], v[198:201], v[88:91]
	v_mfma_f32_16x16x32_bf16 v[76:79], v[164:167], v[206:209], v[76:79]
	v_mfma_f32_16x16x32_bf16 v[72:75], v[172:175], v[206:209], v[72:75]
	v_mfma_f32_16x16x32_bf16 v[124:127], v[168:171], v[184:187], v[124:127]
	v_mfma_f32_16x16x32_bf16 v[120:123], v[176:179], v[184:187], v[120:123]
	v_mfma_f32_16x16x32_bf16 v[108:111], v[168:171], v[194:197], v[108:111]
	v_mfma_f32_16x16x32_bf16 v[104:107], v[176:179], v[194:197], v[104:107]
	v_mfma_f32_16x16x32_bf16 v[92:95], v[168:171], v[202:205], v[92:95]
	v_mfma_f32_16x16x32_bf16 v[88:91], v[176:179], v[202:205], v[88:91]
	v_mfma_f32_16x16x32_bf16 v[76:79], v[168:171], v[210:213], v[76:79]
	v_mfma_f32_16x16x32_bf16 v[72:75], v[176:179], v[210:213], v[72:75]
	s_barrier
	s_add_i32 s58, s52, s33
	v_lshl_add_u64 v[138:139], s[4:5], 0, v[128:129]
	s_mov_b32 m0, s58
	ds_read_b128 v[180:183], v145 offset:16384
	ds_read_b128 v[184:187], v145 offset:17408
	ds_read_b128 v[190:193], v145 offset:18432
	ds_read_b128 v[194:197], v145 offset:19456
	ds_read_b128 v[198:201], v145 offset:20480
	ds_read_b128 v[202:205], v145 offset:21504
	ds_read_b128 v[206:209], v145 offset:22528
	ds_read_b128 v[210:213], v145 offset:23552
	global_load_lds_dwordx4 v[138:139], off
	s_add_i32 m0, s58, 0x2000
	s_add_u32 s58, s4, 0x40000
	v_lshl_add_u64 v[214:215], s[4:5], 0, v[130:131]
	s_addc_u32 s59, s5, 0
	s_add_i32 s60, s53, s33
	global_load_lds_dwordx4 v[214:215], off
	v_lshl_add_u64 v[216:217], s[58:59], 0, v[128:129]
	s_mov_b32 m0, s60
	v_lshl_add_u64 v[218:219], s[34:35], 0, v[130:131]
	global_load_lds_dwordx4 v[216:217], off
	v_lshl_add_u64 v[216:217], s[58:59], 0, v[130:131]
	s_add_i32 m0, s60, 0x2000
	s_nop 0
	global_load_lds_dwordx4 v[216:217], off
	v_lshl_add_u64 v[216:217], s[34:35], 0, v[128:129]
	s_mov_b32 m0, s27
	s_nop 0
	global_load_lds_dwordx4 v[216:217], off
	s_mov_b32 m0, s29
	s_nop 0
	global_load_lds_dwordx4 v[218:219], off
	s_waitcnt vmcnt(8)
	s_waitcnt lgkmcnt(0)
	s_barrier
	s_waitcnt lgkmcnt(0)
	v_mfma_f32_16x16x32_bf16 v[52:55], v[148:151], v[180:183], v[52:55]
	v_mfma_f32_16x16x32_bf16 v[48:51], v[156:159], v[180:183], v[48:51]
	v_mfma_f32_16x16x32_bf16 v[36:39], v[148:151], v[190:193], v[36:39]
	v_mfma_f32_16x16x32_bf16 v[32:35], v[156:159], v[190:193], v[32:35]
	v_mfma_f32_16x16x32_bf16 v[20:23], v[148:151], v[198:201], v[20:23]
	v_mfma_f32_16x16x32_bf16 v[16:19], v[156:159], v[198:201], v[16:19]
	v_mfma_f32_16x16x32_bf16 v[4:7], v[148:151], v[206:209], v[4:7]
	v_mfma_f32_16x16x32_bf16 v[0:3], v[156:159], v[206:209], v[0:3]
	v_mfma_f32_16x16x32_bf16 v[52:55], v[152:155], v[184:187], v[52:55]
	v_mfma_f32_16x16x32_bf16 v[48:51], v[160:163], v[184:187], v[48:51]
	v_mfma_f32_16x16x32_bf16 v[36:39], v[152:155], v[194:197], v[36:39]
	v_mfma_f32_16x16x32_bf16 v[32:35], v[160:163], v[194:197], v[32:35]
	v_mfma_f32_16x16x32_bf16 v[20:23], v[152:155], v[202:205], v[20:23]
	v_mfma_f32_16x16x32_bf16 v[16:19], v[160:163], v[202:205], v[16:19]
	v_mfma_f32_16x16x32_bf16 v[4:7], v[152:155], v[210:213], v[4:7]
	v_mfma_f32_16x16x32_bf16 v[0:3], v[160:163], v[210:213], v[0:3]
	v_mfma_f32_16x16x32_bf16 v[60:63], v[164:167], v[180:183], v[60:63]
	v_mfma_f32_16x16x32_bf16 v[56:59], v[172:175], v[180:183], v[56:59]
	v_mfma_f32_16x16x32_bf16 v[44:47], v[164:167], v[190:193], v[44:47]
	v_mfma_f32_16x16x32_bf16 v[40:43], v[172:175], v[190:193], v[40:43]
	v_mfma_f32_16x16x32_bf16 v[28:31], v[164:167], v[198:201], v[28:31]
	v_mfma_f32_16x16x32_bf16 v[24:27], v[172:175], v[198:201], v[24:27]
	v_mfma_f32_16x16x32_bf16 v[12:15], v[164:167], v[206:209], v[12:15]
	v_mfma_f32_16x16x32_bf16 v[8:11], v[172:175], v[206:209], v[8:11]
	v_mfma_f32_16x16x32_bf16 v[60:63], v[168:171], v[184:187], v[60:63]
	v_mfma_f32_16x16x32_bf16 v[56:59], v[176:179], v[184:187], v[56:59]
	v_mfma_f32_16x16x32_bf16 v[44:47], v[168:171], v[194:197], v[44:47]
	v_mfma_f32_16x16x32_bf16 v[40:43], v[176:179], v[194:197], v[40:43]
	v_mfma_f32_16x16x32_bf16 v[28:31], v[168:171], v[202:205], v[28:31]
	v_mfma_f32_16x16x32_bf16 v[24:27], v[176:179], v[202:205], v[24:27]
	v_mfma_f32_16x16x32_bf16 v[12:15], v[168:171], v[210:213], v[12:15]
	v_mfma_f32_16x16x32_bf16 v[8:11], v[176:179], v[210:213], v[8:11]
	s_barrier
	s_add_i32 s58, 0, 0x18000
	v_add_u32_e32 v147, s58, v141
	s_add_i32 s59, 0, 0x1c000
	ds_read_b128 v[148:151], v147
	ds_read_b128 v[152:155], v147 offset:1024
	ds_read_b128 v[156:159], v147 offset:2048
	ds_read_b128 v[160:163], v147 offset:3072
	v_add_u32_e32 v147, s59, v141
	ds_read_b128 v[164:167], v147
	ds_read_b128 v[168:171], v147 offset:1024
	ds_read_b128 v[172:175], v147 offset:2048
	ds_read_b128 v[176:179], v147 offset:3072
	s_add_u32 s34, s34, 0x40000
	s_addc_u32 s35, s35, 0
	s_mov_b32 m0, s40
	v_lshl_add_u64 v[220:221], s[34:35], 0, v[128:129]
	ds_read_b128 v[180:183], v145 offset:32768
	ds_read_b128 v[184:187], v145 offset:33792
	ds_read_b128 v[190:193], v145 offset:34816
	ds_read_b128 v[194:197], v145 offset:35840
	ds_read_b128 v[198:201], v145 offset:36864
	ds_read_b128 v[202:205], v145 offset:37888
	ds_read_b128 v[206:209], v145 offset:38912
	ds_read_b128 v[210:213], v145 offset:39936
	global_load_lds_dwordx4 v[220:221], off
	v_lshl_add_u64 v[220:221], s[34:35], 0, v[130:131]
	s_mov_b32 m0, s41
	s_nop 0
	global_load_lds_dwordx4 v[220:221], off
	s_waitcnt vmcnt(8)
	s_waitcnt lgkmcnt(0)
	s_barrier
	s_waitcnt lgkmcnt(0)
	v_mfma_f32_16x16x32_bf16 v[116:119], v[148:151], v[180:183], v[116:119]
	v_mfma_f32_16x16x32_bf16 v[112:115], v[156:159], v[180:183], v[112:115]
	v_mfma_f32_16x16x32_bf16 v[100:103], v[148:151], v[190:193], v[100:103]
	v_mfma_f32_16x16x32_bf16 v[96:99], v[156:159], v[190:193], v[96:99]
	v_mfma_f32_16x16x32_bf16 v[84:87], v[148:151], v[198:201], v[84:87]
	v_mfma_f32_16x16x32_bf16 v[80:83], v[156:159], v[198:201], v[80:83]
	v_mfma_f32_16x16x32_bf16 v[68:71], v[148:151], v[206:209], v[68:71]
	v_mfma_f32_16x16x32_bf16 v[64:67], v[156:159], v[206:209], v[64:67]
	v_mfma_f32_16x16x32_bf16 v[116:119], v[152:155], v[184:187], v[116:119]
	v_mfma_f32_16x16x32_bf16 v[112:115], v[160:163], v[184:187], v[112:115]
	v_mfma_f32_16x16x32_bf16 v[100:103], v[152:155], v[194:197], v[100:103]
	v_mfma_f32_16x16x32_bf16 v[96:99], v[160:163], v[194:197], v[96:99]
	v_mfma_f32_16x16x32_bf16 v[84:87], v[152:155], v[202:205], v[84:87]
	v_mfma_f32_16x16x32_bf16 v[80:83], v[160:163], v[202:205], v[80:83]
	v_mfma_f32_16x16x32_bf16 v[68:71], v[152:155], v[210:213], v[68:71]
	v_mfma_f32_16x16x32_bf16 v[64:67], v[160:163], v[210:213], v[64:67]
	v_mfma_f32_16x16x32_bf16 v[124:127], v[164:167], v[180:183], v[124:127]
	v_mfma_f32_16x16x32_bf16 v[120:123], v[172:175], v[180:183], v[120:123]
	v_mfma_f32_16x16x32_bf16 v[108:111], v[164:167], v[190:193], v[108:111]
	v_mfma_f32_16x16x32_bf16 v[104:107], v[172:175], v[190:193], v[104:107]
	v_mfma_f32_16x16x32_bf16 v[92:95], v[164:167], v[198:201], v[92:95]
	v_mfma_f32_16x16x32_bf16 v[88:91], v[172:175], v[198:201], v[88:91]
	v_mfma_f32_16x16x32_bf16 v[76:79], v[164:167], v[206:209], v[76:79]
	v_mfma_f32_16x16x32_bf16 v[72:75], v[172:175], v[206:209], v[72:75]
	v_mfma_f32_16x16x32_bf16 v[124:127], v[168:171], v[184:187], v[124:127]
	v_mfma_f32_16x16x32_bf16 v[120:123], v[176:179], v[184:187], v[120:123]
	v_mfma_f32_16x16x32_bf16 v[108:111], v[168:171], v[194:197], v[108:111]
	v_mfma_f32_16x16x32_bf16 v[104:107], v[176:179], v[194:197], v[104:107]
	v_mfma_f32_16x16x32_bf16 v[92:95], v[168:171], v[202:205], v[92:95]
	v_mfma_f32_16x16x32_bf16 v[88:91], v[176:179], v[202:205], v[88:91]
	v_mfma_f32_16x16x32_bf16 v[76:79], v[168:171], v[210:213], v[76:79]
	v_mfma_f32_16x16x32_bf16 v[72:75], v[176:179], v[210:213], v[72:75]
	s_barrier
	s_add_i32 s34, s58, s33
	v_lshl_add_u64 v[138:139], v[138:139], 0, s[12:13]
	s_mov_b32 m0, s34
	ds_read_b128 v[180:183], v145 offset:49152
	ds_read_b128 v[184:187], v145 offset:50176
	ds_read_b128 v[190:193], v145 offset:51200
	ds_read_b128 v[194:197], v145 offset:52224
	ds_read_b128 v[198:201], v145 offset:53248
	ds_read_b128 v[202:205], v145 offset:54272
	ds_read_b128 v[206:209], v145 offset:55296
	ds_read_b128 v[210:213], v145 offset:56320
	global_load_lds_dwordx4 v[138:139], off
	s_add_i32 m0, s34, 0x2000
	s_add_u32 s4, s4, 0x40080
	v_lshl_add_u64 v[138:139], v[214:215], 0, s[12:13]
	s_addc_u32 s5, s5, 0
	s_add_i32 s34, s59, s33
	global_load_lds_dwordx4 v[138:139], off
	v_lshl_add_u64 v[138:139], s[4:5], 0, v[128:129]
	s_mov_b32 m0, s34
	s_nop 0
	global_load_lds_dwordx4 v[138:139], off
	v_lshl_add_u64 v[138:139], s[4:5], 0, v[130:131]
	s_add_i32 m0, s34, 0x2000
	s_nop 0
	global_load_lds_dwordx4 v[138:139], off
	v_lshl_add_u64 v[138:139], v[216:217], 0, s[12:13]
	s_mov_b32 m0, s43
	s_nop 0
	global_load_lds_dwordx4 v[138:139], off
	v_lshl_add_u64 v[138:139], v[218:219], 0, s[12:13]
	s_mov_b32 m0, s44
	s_nop 0
	global_load_lds_dwordx4 v[138:139], off
	s_waitcnt vmcnt(8)
	s_waitcnt lgkmcnt(0)
	s_barrier
	s_waitcnt lgkmcnt(0)
	v_mfma_f32_16x16x32_bf16 v[52:55], v[148:151], v[180:183], v[52:55]
	v_mfma_f32_16x16x32_bf16 v[48:51], v[156:159], v[180:183], v[48:51]
	v_mfma_f32_16x16x32_bf16 v[36:39], v[148:151], v[190:193], v[36:39]
	v_mfma_f32_16x16x32_bf16 v[32:35], v[156:159], v[190:193], v[32:35]
	v_mfma_f32_16x16x32_bf16 v[20:23], v[148:151], v[198:201], v[20:23]
	v_mfma_f32_16x16x32_bf16 v[16:19], v[156:159], v[198:201], v[16:19]
	v_mfma_f32_16x16x32_bf16 v[4:7], v[148:151], v[206:209], v[4:7]
	v_mfma_f32_16x16x32_bf16 v[0:3], v[156:159], v[206:209], v[0:3]
	v_mfma_f32_16x16x32_bf16 v[52:55], v[152:155], v[184:187], v[52:55]
	v_mfma_f32_16x16x32_bf16 v[48:51], v[160:163], v[184:187], v[48:51]
	v_mfma_f32_16x16x32_bf16 v[36:39], v[152:155], v[194:197], v[36:39]
	v_mfma_f32_16x16x32_bf16 v[32:35], v[160:163], v[194:197], v[32:35]
	v_mfma_f32_16x16x32_bf16 v[20:23], v[152:155], v[202:205], v[20:23]
	v_mfma_f32_16x16x32_bf16 v[16:19], v[160:163], v[202:205], v[16:19]
	v_mfma_f32_16x16x32_bf16 v[4:7], v[152:155], v[210:213], v[4:7]
	v_mfma_f32_16x16x32_bf16 v[0:3], v[160:163], v[210:213], v[0:3]
	v_mfma_f32_16x16x32_bf16 v[60:63], v[164:167], v[180:183], v[60:63]
	v_mfma_f32_16x16x32_bf16 v[56:59], v[172:175], v[180:183], v[56:59]
	v_mfma_f32_16x16x32_bf16 v[44:47], v[164:167], v[190:193], v[44:47]
	v_mfma_f32_16x16x32_bf16 v[40:43], v[172:175], v[190:193], v[40:43]
	v_mfma_f32_16x16x32_bf16 v[28:31], v[164:167], v[198:201], v[28:31]
	v_mfma_f32_16x16x32_bf16 v[24:27], v[172:175], v[198:201], v[24:27]
	v_mfma_f32_16x16x32_bf16 v[12:15], v[164:167], v[206:209], v[12:15]
	v_mfma_f32_16x16x32_bf16 v[8:11], v[172:175], v[206:209], v[8:11]
	v_mfma_f32_16x16x32_bf16 v[60:63], v[168:171], v[184:187], v[60:63]
	v_mfma_f32_16x16x32_bf16 v[56:59], v[176:179], v[184:187], v[56:59]
	v_mfma_f32_16x16x32_bf16 v[44:47], v[168:171], v[194:197], v[44:47]
	v_mfma_f32_16x16x32_bf16 v[40:43], v[176:179], v[194:197], v[40:43]
	v_mfma_f32_16x16x32_bf16 v[28:31], v[168:171], v[202:205], v[28:31]
	v_mfma_f32_16x16x32_bf16 v[24:27], v[176:179], v[202:205], v[24:27]
	v_mfma_f32_16x16x32_bf16 v[12:15], v[168:171], v[210:213], v[12:15]
	v_mfma_f32_16x16x32_bf16 v[8:11], v[176:179], v[210:213], v[8:11]
	s_barrier
	s_add_u32 s30, s30, 0x100
	s_addc_u32 s31, s31, 0
	s_add_u32 s19, s19, 0x100
	s_addc_u32 s21, s21, 0
	s_cmp_ge_i32 s57, s42
	s_mov_b32 s4, s57
	s_cbranch_scc0 .LBB0_1464

.LBB0_1550:
	s_andn2_b64 vcc, exec, s[18:19]
	s_waitcnt lgkmcnt(0)
	s_waitcnt vmcnt(0)
	s_cbranch_vccnz .Lpz_zero_5
	s_add_u32 s26, s26, 0xb0080
	s_addc_u32 s27, s27, 0
	s_add_u32 s56, s4, 0x100
	s_addc_u32 s57, s5, 0
	s_mov_b32 s4, 0
	ds_read_b128 v[138:141], v145
	ds_read_b128 v[150:153], v145 offset:1024
	ds_read_b128 v[154:157], v145 offset:2048
	ds_read_b128 v[158:161], v145 offset:3072
	ds_read_b128 v[162:165], v146
	ds_read_b128 v[166:169], v146 offset:1024
	ds_read_b128 v[170:173], v146 offset:2048
	ds_read_b128 v[174:177], v146 offset:3072
	s_add_i32 s58, s4, 2
	s_add_u32 s5, s26, 0xfff50080
	s_addc_u32 s28, s27, -1
	s_cmp_eq_u32 s44, s4
	s_cselect_b32 s4, s24, s56
	s_cselect_b32 s29, s23, s28
	s_cselect_b32 s28, s22, s5
	s_cselect_b32 s5, s25, s57
	v_lshl_add_u64 v[186:187], s[26:27], 0, v[132:133]
	s_add_i32 m0, s36, 0xc000
	ds_read_b128 v[178:181], v147
	ds_read_b128 v[182:185], v147 offset:1024
	ds_read_b128 v[190:193], v147 offset:2048
	ds_read_b128 v[194:197], v147 offset:3072
	ds_read_b128 v[198:201], v147 offset:4096
	ds_read_b128 v[202:205], v147 offset:5120
	ds_read_b128 v[206:209], v147 offset:6144
	ds_read_b128 v[210:213], v147 offset:7168
	global_load_lds_dwordx4 v[186:187], off
	v_lshl_add_u64 v[186:187], s[26:27], 0, v[134:135]
	s_add_i32 m0, s36, 0xe000
	s_nop 0
	global_load_lds_dwordx4 v[186:187], off
	s_waitcnt vmcnt(8)
	s_waitcnt lgkmcnt(0)
	s_barrier
	s_waitcnt lgkmcnt(0)
	v_mfma_f32_16x16x32_bf16 v[120:123], v[138:141], v[178:181], 0
	v_mfma_f32_16x16x32_bf16 v[124:127], v[154:157], v[178:181], 0
	v_mfma_f32_16x16x32_bf16 v[108:111], v[138:141], v[190:193], 0
	v_mfma_f32_16x16x32_bf16 v[104:107], v[154:157], v[190:193], 0
	v_mfma_f32_16x16x32_bf16 v[92:95], v[138:141], v[198:201], 0
	v_mfma_f32_16x16x32_bf16 v[88:91], v[154:157], v[198:201], 0
	v_mfma_f32_16x16x32_bf16 v[76:79], v[138:141], v[206:209], 0
	v_mfma_f32_16x16x32_bf16 v[72:75], v[154:157], v[206:209], 0
	v_mfma_f32_16x16x32_bf16 v[120:123], v[150:153], v[182:185], v[120:123]
	v_mfma_f32_16x16x32_bf16 v[124:127], v[158:161], v[182:185], v[124:127]
	v_mfma_f32_16x16x32_bf16 v[108:111], v[150:153], v[194:197], v[108:111]
	v_mfma_f32_16x16x32_bf16 v[104:107], v[158:161], v[194:197], v[104:107]
	v_mfma_f32_16x16x32_bf16 v[92:95], v[150:153], v[202:205], v[92:95]
	v_mfma_f32_16x16x32_bf16 v[88:91], v[158:161], v[202:205], v[88:91]
	v_mfma_f32_16x16x32_bf16 v[76:79], v[150:153], v[210:213], v[76:79]
	v_mfma_f32_16x16x32_bf16 v[72:75], v[158:161], v[210:213], v[72:75]
	v_mfma_f32_16x16x32_bf16 v[116:119], v[162:165], v[178:181], 0
	v_mfma_f32_16x16x32_bf16 v[112:115], v[170:173], v[178:181], 0
	v_mfma_f32_16x16x32_bf16 v[100:103], v[162:165], v[190:193], 0
	v_mfma_f32_16x16x32_bf16 v[96:99], v[170:173], v[190:193], 0
	v_mfma_f32_16x16x32_bf16 v[84:87], v[162:165], v[198:201], 0
	v_mfma_f32_16x16x32_bf16 v[80:83], v[170:173], v[198:201], 0
	v_mfma_f32_16x16x32_bf16 v[68:71], v[162:165], v[206:209], 0
	v_mfma_f32_16x16x32_bf16 v[64:67], v[170:173], v[206:209], 0
	v_mfma_f32_16x16x32_bf16 v[116:119], v[166:169], v[182:185], v[116:119]
	v_mfma_f32_16x16x32_bf16 v[112:115], v[174:177], v[182:185], v[112:115]
	v_mfma_f32_16x16x32_bf16 v[100:103], v[166:169], v[194:197], v[100:103]
	v_mfma_f32_16x16x32_bf16 v[96:99], v[174:177], v[194:197], v[96:99]
	v_mfma_f32_16x16x32_bf16 v[84:87], v[166:169], v[202:205], v[84:87]
	v_mfma_f32_16x16x32_bf16 v[80:83], v[174:177], v[202:205], v[80:83]
	v_mfma_f32_16x16x32_bf16 v[68:71], v[166:169], v[210:213], v[68:71]
	v_mfma_f32_16x16x32_bf16 v[64:67], v[174:177], v[210:213], v[64:67]
	s_barrier
	s_add_i32 s59, s49, s35
	v_lshl_add_u64 v[186:187], s[4:5], 0, v[128:129]
	s_mov_b32 m0, s59
	ds_read_b128 v[178:181], v147 offset:16384
	ds_read_b128 v[182:185], v147 offset:17408
	ds_read_b128 v[190:193], v147 offset:18432
	ds_read_b128 v[194:197], v147 offset:19456
	ds_read_b128 v[198:201], v147 offset:20480
	ds_read_b128 v[202:205], v147 offset:21504
	ds_read_b128 v[206:209], v147 offset:22528
	ds_read_b128 v[210:213], v147 offset:23552
	global_load_lds_dwordx4 v[186:187], off
	s_add_i32 m0, s59, 0x2000
	s_add_u32 s60, s4, 0xb0000
	v_lshl_add_u64 v[214:215], s[4:5], 0, v[130:131]
	s_addc_u32 s61, s5, 0
	s_add_i32 s59, s50, s35
	global_load_lds_dwordx4 v[214:215], off
	v_lshl_add_u64 v[216:217], s[60:61], 0, v[128:129]
	s_mov_b32 m0, s59
	v_lshl_add_u64 v[218:219], s[28:29], 0, v[130:131]
	global_load_lds_dwordx4 v[216:217], off
	v_lshl_add_u64 v[216:217], s[60:61], 0, v[130:131]
	s_add_i32 m0, s59, 0x2000
	s_nop 0
	global_load_lds_dwordx4 v[216:217], off
	v_lshl_add_u64 v[216:217], s[28:29], 0, v[128:129]
	s_mov_b32 m0, s36
	s_nop 0
	global_load_lds_dwordx4 v[216:217], off
	s_mov_b32 m0, s37
	s_nop 0
	global_load_lds_dwordx4 v[218:219], off
	s_waitcnt vmcnt(8)
	s_waitcnt lgkmcnt(0)
	s_barrier
	s_waitcnt lgkmcnt(0)
	v_mfma_f32_16x16x32_bf16 v[60:63], v[138:141], v[178:181], 0
	v_mfma_f32_16x16x32_bf16 v[56:59], v[154:157], v[178:181], 0
	v_mfma_f32_16x16x32_bf16 v[44:47], v[138:141], v[190:193], 0
	v_mfma_f32_16x16x32_bf16 v[40:43], v[154:157], v[190:193], 0
	v_mfma_f32_16x16x32_bf16 v[28:31], v[138:141], v[198:201], 0
	v_mfma_f32_16x16x32_bf16 v[24:27], v[154:157], v[198:201], 0
	v_mfma_f32_16x16x32_bf16 v[12:15], v[138:141], v[206:209], 0
	v_mfma_f32_16x16x32_bf16 v[8:11], v[154:157], v[206:209], 0
	v_mfma_f32_16x16x32_bf16 v[60:63], v[150:153], v[182:185], v[60:63]
	v_mfma_f32_16x16x32_bf16 v[56:59], v[158:161], v[182:185], v[56:59]
	v_mfma_f32_16x16x32_bf16 v[44:47], v[150:153], v[194:197], v[44:47]
	v_mfma_f32_16x16x32_bf16 v[40:43], v[158:161], v[194:197], v[40:43]
	v_mfma_f32_16x16x32_bf16 v[28:31], v[150:153], v[202:205], v[28:31]
	v_mfma_f32_16x16x32_bf16 v[24:27], v[158:161], v[202:205], v[24:27]
	v_mfma_f32_16x16x32_bf16 v[12:15], v[150:153], v[210:213], v[12:15]
	v_mfma_f32_16x16x32_bf16 v[8:11], v[158:161], v[210:213], v[8:11]
	v_mfma_f32_16x16x32_bf16 v[52:55], v[162:165], v[178:181], 0
	v_mfma_f32_16x16x32_bf16 v[48:51], v[170:173], v[178:181], 0
	v_mfma_f32_16x16x32_bf16 v[36:39], v[162:165], v[190:193], 0
	v_mfma_f32_16x16x32_bf16 v[32:35], v[170:173], v[190:193], 0
	v_mfma_f32_16x16x32_bf16 v[20:23], v[162:165], v[198:201], 0
	v_mfma_f32_16x16x32_bf16 v[16:19], v[170:173], v[198:201], 0
	v_mfma_f32_16x16x32_bf16 v[4:7], v[162:165], v[206:209], 0
	v_mfma_f32_16x16x32_bf16 v[0:3], v[170:173], v[206:209], 0
	v_mfma_f32_16x16x32_bf16 v[52:55], v[166:169], v[182:185], v[52:55]
	v_mfma_f32_16x16x32_bf16 v[48:51], v[174:177], v[182:185], v[48:51]
	v_mfma_f32_16x16x32_bf16 v[36:39], v[166:169], v[194:197], v[36:39]
	v_mfma_f32_16x16x32_bf16 v[32:35], v[174:177], v[194:197], v[32:35]
	v_mfma_f32_16x16x32_bf16 v[20:23], v[166:169], v[202:205], v[20:23]
	v_mfma_f32_16x16x32_bf16 v[16:19], v[174:177], v[202:205], v[16:19]
	v_mfma_f32_16x16x32_bf16 v[4:7], v[166:169], v[210:213], v[4:7]
	v_mfma_f32_16x16x32_bf16 v[0:3], v[174:177], v[210:213], v[0:3]
	s_barrier
	s_add_i32 s59, 0, 0x18000
	v_add_u32_e32 v149, s59, v143
	s_add_i32 s60, 0, 0x1c000
	ds_read_b128 v[138:141], v149
	ds_read_b128 v[150:153], v149 offset:1024
	ds_read_b128 v[154:157], v149 offset:2048
	ds_read_b128 v[158:161], v149 offset:3072
	v_add_u32_e32 v149, s60, v143
	ds_read_b128 v[162:165], v149
	ds_read_b128 v[166:169], v149 offset:1024
	ds_read_b128 v[170:173], v149 offset:2048
	ds_read_b128 v[174:177], v149 offset:3072
	s_add_u32 s28, s28, 0xb0000
	s_addc_u32 s29, s29, 0
	s_mov_b32 m0, s38
	v_lshl_add_u64 v[220:221], s[28:29], 0, v[128:129]
	ds_read_b128 v[178:181], v147 offset:32768
	ds_read_b128 v[182:185], v147 offset:33792
	ds_read_b128 v[190:193], v147 offset:34816
	ds_read_b128 v[194:197], v147 offset:35840
	ds_read_b128 v[198:201], v147 offset:36864
	ds_read_b128 v[202:205], v147 offset:37888
	ds_read_b128 v[206:209], v147 offset:38912
	ds_read_b128 v[210:213], v147 offset:39936
	global_load_lds_dwordx4 v[220:221], off
	v_lshl_add_u64 v[220:221], s[28:29], 0, v[130:131]
	s_mov_b32 m0, s39
	s_nop 0
	global_load_lds_dwordx4 v[220:221], off
	s_waitcnt vmcnt(8)
	s_waitcnt lgkmcnt(0)
	s_barrier
	s_waitcnt lgkmcnt(0)
	v_mfma_f32_16x16x32_bf16 v[120:123], v[138:141], v[178:181], v[120:123]
	v_mfma_f32_16x16x32_bf16 v[124:127], v[154:157], v[178:181], v[124:127]
	v_mfma_f32_16x16x32_bf16 v[108:111], v[138:141], v[190:193], v[108:111]
	v_mfma_f32_16x16x32_bf16 v[104:107], v[154:157], v[190:193], v[104:107]
	v_mfma_f32_16x16x32_bf16 v[92:95], v[138:141], v[198:201], v[92:95]
	v_mfma_f32_16x16x32_bf16 v[88:91], v[154:157], v[198:201], v[88:91]
	v_mfma_f32_16x16x32_bf16 v[76:79], v[138:141], v[206:209], v[76:79]
	v_mfma_f32_16x16x32_bf16 v[72:75], v[154:157], v[206:209], v[72:75]
	v_mfma_f32_16x16x32_bf16 v[120:123], v[150:153], v[182:185], v[120:123]
	v_mfma_f32_16x16x32_bf16 v[124:127], v[158:161], v[182:185], v[124:127]
	v_mfma_f32_16x16x32_bf16 v[108:111], v[150:153], v[194:197], v[108:111]
	v_mfma_f32_16x16x32_bf16 v[104:107], v[158:161], v[194:197], v[104:107]
	v_mfma_f32_16x16x32_bf16 v[92:95], v[150:153], v[202:205], v[92:95]
	v_mfma_f32_16x16x32_bf16 v[88:91], v[158:161], v[202:205], v[88:91]
	v_mfma_f32_16x16x32_bf16 v[76:79], v[150:153], v[210:213], v[76:79]
	v_mfma_f32_16x16x32_bf16 v[72:75], v[158:161], v[210:213], v[72:75]
	v_mfma_f32_16x16x32_bf16 v[116:119], v[162:165], v[178:181], v[116:119]
	v_mfma_f32_16x16x32_bf16 v[112:115], v[170:173], v[178:181], v[112:115]
	v_mfma_f32_16x16x32_bf16 v[100:103], v[162:165], v[190:193], v[100:103]
	v_mfma_f32_16x16x32_bf16 v[96:99], v[170:173], v[190:193], v[96:99]
	v_mfma_f32_16x16x32_bf16 v[84:87], v[162:165], v[198:201], v[84:87]
	v_mfma_f32_16x16x32_bf16 v[80:83], v[170:173], v[198:201], v[80:83]
	v_mfma_f32_16x16x32_bf16 v[68:71], v[162:165], v[206:209], v[68:71]
	v_mfma_f32_16x16x32_bf16 v[64:67], v[170:173], v[206:209], v[64:67]
	v_mfma_f32_16x16x32_bf16 v[116:119], v[166:169], v[182:185], v[116:119]
	v_mfma_f32_16x16x32_bf16 v[112:115], v[174:177], v[182:185], v[112:115]
	v_mfma_f32_16x16x32_bf16 v[100:103], v[166:169], v[194:197], v[100:103]
	v_mfma_f32_16x16x32_bf16 v[96:99], v[174:177], v[194:197], v[96:99]
	v_mfma_f32_16x16x32_bf16 v[84:87], v[166:169], v[202:205], v[84:87]
	v_mfma_f32_16x16x32_bf16 v[80:83], v[174:177], v[202:205], v[80:83]
	v_mfma_f32_16x16x32_bf16 v[68:71], v[166:169], v[210:213], v[68:71]
	v_mfma_f32_16x16x32_bf16 v[64:67], v[174:177], v[210:213], v[64:67]
	s_barrier
	s_add_i32 s28, s59, s35
	v_lshl_add_u64 v[186:187], v[186:187], 0, s[16:17]
	s_mov_b32 m0, s28
	ds_read_b128 v[178:181], v147 offset:49152
	ds_read_b128 v[182:185], v147 offset:50176
	ds_read_b128 v[190:193], v147 offset:51200
	ds_read_b128 v[194:197], v147 offset:52224
	ds_read_b128 v[198:201], v147 offset:53248
	ds_read_b128 v[202:205], v147 offset:54272
	ds_read_b128 v[206:209], v147 offset:55296
	ds_read_b128 v[210:213], v147 offset:56320
	global_load_lds_dwordx4 v[186:187], off
	s_add_i32 m0, s28, 0x2000
	s_add_u32 s4, s4, 0xb0080
	v_lshl_add_u64 v[186:187], v[214:215], 0, s[16:17]
	s_addc_u32 s5, s5, 0
	s_add_i32 s28, s60, s35
	global_load_lds_dwordx4 v[186:187], off
	v_lshl_add_u64 v[186:187], s[4:5], 0, v[128:129]
	s_mov_b32 m0, s28
	s_nop 0
	global_load_lds_dwordx4 v[186:187], off
	v_lshl_add_u64 v[186:187], s[4:5], 0, v[130:131]
	s_add_i32 m0, s28, 0x2000
	s_nop 0
	global_load_lds_dwordx4 v[186:187], off
	v_lshl_add_u64 v[186:187], v[216:217], 0, s[16:17]
	s_mov_b32 m0, s42
	s_nop 0
	global_load_lds_dwordx4 v[186:187], off
	v_lshl_add_u64 v[186:187], v[218:219], 0, s[16:17]
	s_mov_b32 m0, s43
	s_nop 0
	global_load_lds_dwordx4 v[186:187], off
	s_waitcnt vmcnt(8)
	s_waitcnt lgkmcnt(0)
	s_barrier
	s_waitcnt lgkmcnt(0)
	v_mfma_f32_16x16x32_bf16 v[60:63], v[138:141], v[178:181], v[60:63]
	v_mfma_f32_16x16x32_bf16 v[56:59], v[154:157], v[178:181], v[56:59]
	v_mfma_f32_16x16x32_bf16 v[44:47], v[138:141], v[190:193], v[44:47]
	v_mfma_f32_16x16x32_bf16 v[40:43], v[154:157], v[190:193], v[40:43]
	v_mfma_f32_16x16x32_bf16 v[28:31], v[138:141], v[198:201], v[28:31]
	v_mfma_f32_16x16x32_bf16 v[24:27], v[154:157], v[198:201], v[24:27]
	v_mfma_f32_16x16x32_bf16 v[12:15], v[138:141], v[206:209], v[12:15]
	v_mfma_f32_16x16x32_bf16 v[8:11], v[154:157], v[206:209], v[8:11]
	v_mfma_f32_16x16x32_bf16 v[60:63], v[150:153], v[182:185], v[60:63]
	v_mfma_f32_16x16x32_bf16 v[56:59], v[158:161], v[182:185], v[56:59]
	v_mfma_f32_16x16x32_bf16 v[44:47], v[150:153], v[194:197], v[44:47]
	v_mfma_f32_16x16x32_bf16 v[40:43], v[158:161], v[194:197], v[40:43]
	v_mfma_f32_16x16x32_bf16 v[28:31], v[150:153], v[202:205], v[28:31]
	v_mfma_f32_16x16x32_bf16 v[24:27], v[158:161], v[202:205], v[24:27]
	v_mfma_f32_16x16x32_bf16 v[12:15], v[150:153], v[210:213], v[12:15]
	v_mfma_f32_16x16x32_bf16 v[8:11], v[158:161], v[210:213], v[8:11]
	v_mfma_f32_16x16x32_bf16 v[52:55], v[162:165], v[178:181], v[52:55]
	v_mfma_f32_16x16x32_bf16 v[48:51], v[170:173], v[178:181], v[48:51]
	v_mfma_f32_16x16x32_bf16 v[36:39], v[162:165], v[190:193], v[36:39]
	v_mfma_f32_16x16x32_bf16 v[32:35], v[170:173], v[190:193], v[32:35]
	v_mfma_f32_16x16x32_bf16 v[20:23], v[162:165], v[198:201], v[20:23]
	v_mfma_f32_16x16x32_bf16 v[16:19], v[170:173], v[198:201], v[16:19]
	v_mfma_f32_16x16x32_bf16 v[4:7], v[162:165], v[206:209], v[4:7]
	v_mfma_f32_16x16x32_bf16 v[0:3], v[170:173], v[206:209], v[0:3]
	v_mfma_f32_16x16x32_bf16 v[52:55], v[166:169], v[182:185], v[52:55]
	v_mfma_f32_16x16x32_bf16 v[48:51], v[174:177], v[182:185], v[48:51]
	v_mfma_f32_16x16x32_bf16 v[36:39], v[166:169], v[194:197], v[36:39]
	v_mfma_f32_16x16x32_bf16 v[32:35], v[174:177], v[194:197], v[32:35]
	v_mfma_f32_16x16x32_bf16 v[20:23], v[166:169], v[202:205], v[20:23]
	v_mfma_f32_16x16x32_bf16 v[16:19], v[174:177], v[202:205], v[16:19]
	v_mfma_f32_16x16x32_bf16 v[4:7], v[166:169], v[210:213], v[4:7]
	v_mfma_f32_16x16x32_bf16 v[0:3], v[174:177], v[210:213], v[0:3]
	s_barrier
	s_add_u32 s26, s26, 0x100
	s_addc_u32 s27, s27, 0
	s_add_u32 s56, s56, 0x100
	s_addc_u32 s57, s57, 0
	s_cmp_ge_i32 s58, s41
	s_mov_b32 s4, s58
	s_cbranch_scc0 .LBB0_1552
	s_branch .LBB0_1553

.LBB0_1552:
	ds_read_b128 v[138:141], v145
	ds_read_b128 v[150:153], v145 offset:1024
	ds_read_b128 v[154:157], v145 offset:2048
	ds_read_b128 v[158:161], v145 offset:3072
	ds_read_b128 v[162:165], v146
	ds_read_b128 v[166:169], v146 offset:1024
	ds_read_b128 v[170:173], v146 offset:2048
	ds_read_b128 v[174:177], v146 offset:3072
	s_add_i32 s58, s4, 2
	s_add_u32 s5, s26, 0xfff50080
	s_addc_u32 s28, s27, -1
	s_cmp_eq_u32 s44, s4
	s_cselect_b32 s4, s24, s56
	s_cselect_b32 s29, s23, s28
	s_cselect_b32 s28, s22, s5
	s_cselect_b32 s5, s25, s57
	v_lshl_add_u64 v[186:187], s[26:27], 0, v[132:133]
	s_add_i32 m0, s36, 0xc000
	ds_read_b128 v[178:181], v147
	ds_read_b128 v[182:185], v147 offset:1024
	ds_read_b128 v[190:193], v147 offset:2048
	ds_read_b128 v[194:197], v147 offset:3072
	ds_read_b128 v[198:201], v147 offset:4096
	ds_read_b128 v[202:205], v147 offset:5120
	ds_read_b128 v[206:209], v147 offset:6144
	ds_read_b128 v[210:213], v147 offset:7168
	global_load_lds_dwordx4 v[186:187], off
	v_lshl_add_u64 v[186:187], s[26:27], 0, v[134:135]
	s_add_i32 m0, s36, 0xe000
	s_nop 0
	global_load_lds_dwordx4 v[186:187], off
	s_waitcnt vmcnt(8)
	s_waitcnt lgkmcnt(0)
	s_barrier
	s_waitcnt lgkmcnt(0)
	v_mfma_f32_16x16x32_bf16 v[120:123], v[138:141], v[178:181], v[120:123]
	v_mfma_f32_16x16x32_bf16 v[124:127], v[154:157], v[178:181], v[124:127]
	v_mfma_f32_16x16x32_bf16 v[108:111], v[138:141], v[190:193], v[108:111]
	v_mfma_f32_16x16x32_bf16 v[104:107], v[154:157], v[190:193], v[104:107]
	v_mfma_f32_16x16x32_bf16 v[92:95], v[138:141], v[198:201], v[92:95]
	v_mfma_f32_16x16x32_bf16 v[88:91], v[154:157], v[198:201], v[88:91]
	v_mfma_f32_16x16x32_bf16 v[76:79], v[138:141], v[206:209], v[76:79]
	v_mfma_f32_16x16x32_bf16 v[72:75], v[154:157], v[206:209], v[72:75]
	v_mfma_f32_16x16x32_bf16 v[120:123], v[150:153], v[182:185], v[120:123]
	v_mfma_f32_16x16x32_bf16 v[124:127], v[158:161], v[182:185], v[124:127]
	v_mfma_f32_16x16x32_bf16 v[108:111], v[150:153], v[194:197], v[108:111]
	v_mfma_f32_16x16x32_bf16 v[104:107], v[158:161], v[194:197], v[104:107]
	v_mfma_f32_16x16x32_bf16 v[92:95], v[150:153], v[202:205], v[92:95]
	v_mfma_f32_16x16x32_bf16 v[88:91], v[158:161], v[202:205], v[88:91]
	v_mfma_f32_16x16x32_bf16 v[76:79], v[150:153], v[210:213], v[76:79]
	v_mfma_f32_16x16x32_bf16 v[72:75], v[158:161], v[210:213], v[72:75]
	v_mfma_f32_16x16x32_bf16 v[116:119], v[162:165], v[178:181], v[116:119]
	v_mfma_f32_16x16x32_bf16 v[112:115], v[170:173], v[178:181], v[112:115]
	v_mfma_f32_16x16x32_bf16 v[100:103], v[162:165], v[190:193], v[100:103]
	v_mfma_f32_16x16x32_bf16 v[96:99], v[170:173], v[190:193], v[96:99]
	v_mfma_f32_16x16x32_bf16 v[84:87], v[162:165], v[198:201], v[84:87]
	v_mfma_f32_16x16x32_bf16 v[80:83], v[170:173], v[198:201], v[80:83]
	v_mfma_f32_16x16x32_bf16 v[68:71], v[162:165], v[206:209], v[68:71]
	v_mfma_f32_16x16x32_bf16 v[64:67], v[170:173], v[206:209], v[64:67]
	v_mfma_f32_16x16x32_bf16 v[116:119], v[166:169], v[182:185], v[116:119]
	v_mfma_f32_16x16x32_bf16 v[112:115], v[174:177], v[182:185], v[112:115]
	v_mfma_f32_16x16x32_bf16 v[100:103], v[166:169], v[194:197], v[100:103]
	v_mfma_f32_16x16x32_bf16 v[96:99], v[174:177], v[194:197], v[96:99]
	v_mfma_f32_16x16x32_bf16 v[84:87], v[166:169], v[202:205], v[84:87]
	v_mfma_f32_16x16x32_bf16 v[80:83], v[174:177], v[202:205], v[80:83]
	v_mfma_f32_16x16x32_bf16 v[68:71], v[166:169], v[210:213], v[68:71]
	v_mfma_f32_16x16x32_bf16 v[64:67], v[174:177], v[210:213], v[64:67]
	s_barrier
	s_add_i32 s59, s49, s35
	v_lshl_add_u64 v[186:187], s[4:5], 0, v[128:129]
	s_mov_b32 m0, s59
	ds_read_b128 v[178:181], v147 offset:16384
	ds_read_b128 v[182:185], v147 offset:17408
	ds_read_b128 v[190:193], v147 offset:18432
	ds_read_b128 v[194:197], v147 offset:19456
	ds_read_b128 v[198:201], v147 offset:20480
	ds_read_b128 v[202:205], v147 offset:21504
	ds_read_b128 v[206:209], v147 offset:22528
	ds_read_b128 v[210:213], v147 offset:23552
	global_load_lds_dwordx4 v[186:187], off
	s_add_i32 m0, s59, 0x2000
	s_add_u32 s60, s4, 0xb0000
	v_lshl_add_u64 v[214:215], s[4:5], 0, v[130:131]
	s_addc_u32 s61, s5, 0
	s_add_i32 s59, s50, s35
	global_load_lds_dwordx4 v[214:215], off
	v_lshl_add_u64 v[216:217], s[60:61], 0, v[128:129]
	s_mov_b32 m0, s59
	v_lshl_add_u64 v[218:219], s[28:29], 0, v[130:131]
	global_load_lds_dwordx4 v[216:217], off
	v_lshl_add_u64 v[216:217], s[60:61], 0, v[130:131]
	s_add_i32 m0, s59, 0x2000
	s_nop 0
	global_load_lds_dwordx4 v[216:217], off
	v_lshl_add_u64 v[216:217], s[28:29], 0, v[128:129]
	s_mov_b32 m0, s36
	s_nop 0
	global_load_lds_dwordx4 v[216:217], off
	s_mov_b32 m0, s37
	s_nop 0
	global_load_lds_dwordx4 v[218:219], off
	s_waitcnt vmcnt(8)
	s_waitcnt lgkmcnt(0)
	s_barrier
	s_waitcnt lgkmcnt(0)
	v_mfma_f32_16x16x32_bf16 v[60:63], v[138:141], v[178:181], v[60:63]
	v_mfma_f32_16x16x32_bf16 v[56:59], v[154:157], v[178:181], v[56:59]
	v_mfma_f32_16x16x32_bf16 v[44:47], v[138:141], v[190:193], v[44:47]
	v_mfma_f32_16x16x32_bf16 v[40:43], v[154:157], v[190:193], v[40:43]
	v_mfma_f32_16x16x32_bf16 v[28:31], v[138:141], v[198:201], v[28:31]
	v_mfma_f32_16x16x32_bf16 v[24:27], v[154:157], v[198:201], v[24:27]
	v_mfma_f32_16x16x32_bf16 v[12:15], v[138:141], v[206:209], v[12:15]
	v_mfma_f32_16x16x32_bf16 v[8:11], v[154:157], v[206:209], v[8:11]
	v_mfma_f32_16x16x32_bf16 v[60:63], v[150:153], v[182:185], v[60:63]
	v_mfma_f32_16x16x32_bf16 v[56:59], v[158:161], v[182:185], v[56:59]
	v_mfma_f32_16x16x32_bf16 v[44:47], v[150:153], v[194:197], v[44:47]
	v_mfma_f32_16x16x32_bf16 v[40:43], v[158:161], v[194:197], v[40:43]
	v_mfma_f32_16x16x32_bf16 v[28:31], v[150:153], v[202:205], v[28:31]
	v_mfma_f32_16x16x32_bf16 v[24:27], v[158:161], v[202:205], v[24:27]
	v_mfma_f32_16x16x32_bf16 v[12:15], v[150:153], v[210:213], v[12:15]
	v_mfma_f32_16x16x32_bf16 v[8:11], v[158:161], v[210:213], v[8:11]
	v_mfma_f32_16x16x32_bf16 v[52:55], v[162:165], v[178:181], v[52:55]
	v_mfma_f32_16x16x32_bf16 v[48:51], v[170:173], v[178:181], v[48:51]
	v_mfma_f32_16x16x32_bf16 v[36:39], v[162:165], v[190:193], v[36:39]
	v_mfma_f32_16x16x32_bf16 v[32:35], v[170:173], v[190:193], v[32:35]
	v_mfma_f32_16x16x32_bf16 v[20:23], v[162:165], v[198:201], v[20:23]
	v_mfma_f32_16x16x32_bf16 v[16:19], v[170:173], v[198:201], v[16:19]
	v_mfma_f32_16x16x32_bf16 v[4:7], v[162:165], v[206:209], v[4:7]
	v_mfma_f32_16x16x32_bf16 v[0:3], v[170:173], v[206:209], v[0:3]
	v_mfma_f32_16x16x32_bf16 v[52:55], v[166:169], v[182:185], v[52:55]
	v_mfma_f32_16x16x32_bf16 v[48:51], v[174:177], v[182:185], v[48:51]
	v_mfma_f32_16x16x32_bf16 v[36:39], v[166:169], v[194:197], v[36:39]
	v_mfma_f32_16x16x32_bf16 v[32:35], v[174:177], v[194:197], v[32:35]
	v_mfma_f32_16x16x32_bf16 v[20:23], v[166:169], v[202:205], v[20:23]
	v_mfma_f32_16x16x32_bf16 v[16:19], v[174:177], v[202:205], v[16:19]
	v_mfma_f32_16x16x32_bf16 v[4:7], v[166:169], v[210:213], v[4:7]
	v_mfma_f32_16x16x32_bf16 v[0:3], v[174:177], v[210:213], v[0:3]
	s_barrier
	s_add_i32 s59, 0, 0x18000
	v_add_u32_e32 v149, s59, v143
	s_add_i32 s60, 0, 0x1c000
	ds_read_b128 v[138:141], v149
	ds_read_b128 v[150:153], v149 offset:1024
	ds_read_b128 v[154:157], v149 offset:2048
	ds_read_b128 v[158:161], v149 offset:3072
	v_add_u32_e32 v149, s60, v143
	ds_read_b128 v[162:165], v149
	ds_read_b128 v[166:169], v149 offset:1024
	ds_read_b128 v[170:173], v149 offset:2048
	ds_read_b128 v[174:177], v149 offset:3072
	s_add_u32 s28, s28, 0xb0000
	s_addc_u32 s29, s29, 0
	s_mov_b32 m0, s38
	v_lshl_add_u64 v[220:221], s[28:29], 0, v[128:129]
	ds_read_b128 v[178:181], v147 offset:32768
	ds_read_b128 v[182:185], v147 offset:33792
	ds_read_b128 v[190:193], v147 offset:34816
	ds_read_b128 v[194:197], v147 offset:35840
	ds_read_b128 v[198:201], v147 offset:36864
	ds_read_b128 v[202:205], v147 offset:37888
	ds_read_b128 v[206:209], v147 offset:38912
	ds_read_b128 v[210:213], v147 offset:39936
	global_load_lds_dwordx4 v[220:221], off
	v_lshl_add_u64 v[220:221], s[28:29], 0, v[130:131]
	s_mov_b32 m0, s39
	s_nop 0
	global_load_lds_dwordx4 v[220:221], off
	s_waitcnt vmcnt(8)
	s_waitcnt lgkmcnt(0)
	s_barrier
	s_waitcnt lgkmcnt(0)
	v_mfma_f32_16x16x32_bf16 v[120:123], v[138:141], v[178:181], v[120:123]
	v_mfma_f32_16x16x32_bf16 v[124:127], v[154:157], v[178:181], v[124:127]
	v_mfma_f32_16x16x32_bf16 v[108:111], v[138:141], v[190:193], v[108:111]
	v_mfma_f32_16x16x32_bf16 v[104:107], v[154:157], v[190:193], v[104:107]
	v_mfma_f32_16x16x32_bf16 v[92:95], v[138:141], v[198:201], v[92:95]
	v_mfma_f32_16x16x32_bf16 v[88:91], v[154:157], v[198:201], v[88:91]
	v_mfma_f32_16x16x32_bf16 v[76:79], v[138:141], v[206:209], v[76:79]
	v_mfma_f32_16x16x32_bf16 v[72:75], v[154:157], v[206:209], v[72:75]
	v_mfma_f32_16x16x32_bf16 v[120:123], v[150:153], v[182:185], v[120:123]
	v_mfma_f32_16x16x32_bf16 v[124:127], v[158:161], v[182:185], v[124:127]
	v_mfma_f32_16x16x32_bf16 v[108:111], v[150:153], v[194:197], v[108:111]
	v_mfma_f32_16x16x32_bf16 v[104:107], v[158:161], v[194:197], v[104:107]
	v_mfma_f32_16x16x32_bf16 v[92:95], v[150:153], v[202:205], v[92:95]
	v_mfma_f32_16x16x32_bf16 v[88:91], v[158:161], v[202:205], v[88:91]
	v_mfma_f32_16x16x32_bf16 v[76:79], v[150:153], v[210:213], v[76:79]
	v_mfma_f32_16x16x32_bf16 v[72:75], v[158:161], v[210:213], v[72:75]
	v_mfma_f32_16x16x32_bf16 v[116:119], v[162:165], v[178:181], v[116:119]
	v_mfma_f32_16x16x32_bf16 v[112:115], v[170:173], v[178:181], v[112:115]
	v_mfma_f32_16x16x32_bf16 v[100:103], v[162:165], v[190:193], v[100:103]
	v_mfma_f32_16x16x32_bf16 v[96:99], v[170:173], v[190:193], v[96:99]
	v_mfma_f32_16x16x32_bf16 v[84:87], v[162:165], v[198:201], v[84:87]
	v_mfma_f32_16x16x32_bf16 v[80:83], v[170:173], v[198:201], v[80:83]
	v_mfma_f32_16x16x32_bf16 v[68:71], v[162:165], v[206:209], v[68:71]
	v_mfma_f32_16x16x32_bf16 v[64:67], v[170:173], v[206:209], v[64:67]
	v_mfma_f32_16x16x32_bf16 v[116:119], v[166:169], v[182:185], v[116:119]
	v_mfma_f32_16x16x32_bf16 v[112:115], v[174:177], v[182:185], v[112:115]
	v_mfma_f32_16x16x32_bf16 v[100:103], v[166:169], v[194:197], v[100:103]
	v_mfma_f32_16x16x32_bf16 v[96:99], v[174:177], v[194:197], v[96:99]
	v_mfma_f32_16x16x32_bf16 v[84:87], v[166:169], v[202:205], v[84:87]
	v_mfma_f32_16x16x32_bf16 v[80:83], v[174:177], v[202:205], v[80:83]
	v_mfma_f32_16x16x32_bf16 v[68:71], v[166:169], v[210:213], v[68:71]
	v_mfma_f32_16x16x32_bf16 v[64:67], v[174:177], v[210:213], v[64:67]
	s_barrier
	s_add_i32 s28, s59, s35
	v_lshl_add_u64 v[186:187], v[186:187], 0, s[16:17]
	s_mov_b32 m0, s28
	ds_read_b128 v[178:181], v147 offset:49152
	ds_read_b128 v[182:185], v147 offset:50176
	ds_read_b128 v[190:193], v147 offset:51200
	ds_read_b128 v[194:197], v147 offset:52224
	ds_read_b128 v[198:201], v147 offset:53248
	ds_read_b128 v[202:205], v147 offset:54272
	ds_read_b128 v[206:209], v147 offset:55296
	ds_read_b128 v[210:213], v147 offset:56320
	global_load_lds_dwordx4 v[186:187], off
	s_add_i32 m0, s28, 0x2000
	s_add_u32 s4, s4, 0xb0080
	v_lshl_add_u64 v[186:187], v[214:215], 0, s[16:17]
	s_addc_u32 s5, s5, 0
	s_add_i32 s28, s60, s35
	global_load_lds_dwordx4 v[186:187], off
	v_lshl_add_u64 v[186:187], s[4:5], 0, v[128:129]
	s_mov_b32 m0, s28
	s_nop 0
	global_load_lds_dwordx4 v[186:187], off
	v_lshl_add_u64 v[186:187], s[4:5], 0, v[130:131]
	s_add_i32 m0, s28, 0x2000
	s_nop 0
	global_load_lds_dwordx4 v[186:187], off
	v_lshl_add_u64 v[186:187], v[216:217], 0, s[16:17]
	s_mov_b32 m0, s42
	s_nop 0
	global_load_lds_dwordx4 v[186:187], off
	v_lshl_add_u64 v[186:187], v[218:219], 0, s[16:17]
	s_mov_b32 m0, s43
	s_nop 0
	global_load_lds_dwordx4 v[186:187], off
	s_waitcnt vmcnt(8)
	s_waitcnt lgkmcnt(0)
	s_barrier
	s_waitcnt lgkmcnt(0)
	v_mfma_f32_16x16x32_bf16 v[60:63], v[138:141], v[178:181], v[60:63]
	v_mfma_f32_16x16x32_bf16 v[56:59], v[154:157], v[178:181], v[56:59]
	v_mfma_f32_16x16x32_bf16 v[44:47], v[138:141], v[190:193], v[44:47]
	v_mfma_f32_16x16x32_bf16 v[40:43], v[154:157], v[190:193], v[40:43]
	v_mfma_f32_16x16x32_bf16 v[28:31], v[138:141], v[198:201], v[28:31]
	v_mfma_f32_16x16x32_bf16 v[24:27], v[154:157], v[198:201], v[24:27]
	v_mfma_f32_16x16x32_bf16 v[12:15], v[138:141], v[206:209], v[12:15]
	v_mfma_f32_16x16x32_bf16 v[8:11], v[154:157], v[206:209], v[8:11]
	v_mfma_f32_16x16x32_bf16 v[60:63], v[150:153], v[182:185], v[60:63]
	v_mfma_f32_16x16x32_bf16 v[56:59], v[158:161], v[182:185], v[56:59]
	v_mfma_f32_16x16x32_bf16 v[44:47], v[150:153], v[194:197], v[44:47]
	v_mfma_f32_16x16x32_bf16 v[40:43], v[158:161], v[194:197], v[40:43]
	v_mfma_f32_16x16x32_bf16 v[28:31], v[150:153], v[202:205], v[28:31]
	v_mfma_f32_16x16x32_bf16 v[24:27], v[158:161], v[202:205], v[24:27]
	v_mfma_f32_16x16x32_bf16 v[12:15], v[150:153], v[210:213], v[12:15]
	v_mfma_f32_16x16x32_bf16 v[8:11], v[158:161], v[210:213], v[8:11]
	v_mfma_f32_16x16x32_bf16 v[52:55], v[162:165], v[178:181], v[52:55]
	v_mfma_f32_16x16x32_bf16 v[48:51], v[170:173], v[178:181], v[48:51]
	v_mfma_f32_16x16x32_bf16 v[36:39], v[162:165], v[190:193], v[36:39]
	v_mfma_f32_16x16x32_bf16 v[32:35], v[170:173], v[190:193], v[32:35]
	v_mfma_f32_16x16x32_bf16 v[20:23], v[162:165], v[198:201], v[20:23]
	v_mfma_f32_16x16x32_bf16 v[16:19], v[170:173], v[198:201], v[16:19]
	v_mfma_f32_16x16x32_bf16 v[4:7], v[162:165], v[206:209], v[4:7]
	v_mfma_f32_16x16x32_bf16 v[0:3], v[170:173], v[206:209], v[0:3]
	v_mfma_f32_16x16x32_bf16 v[52:55], v[166:169], v[182:185], v[52:55]
	v_mfma_f32_16x16x32_bf16 v[48:51], v[174:177], v[182:185], v[48:51]
	v_mfma_f32_16x16x32_bf16 v[36:39], v[166:169], v[194:197], v[36:39]
	v_mfma_f32_16x16x32_bf16 v[32:35], v[174:177], v[194:197], v[32:35]
	v_mfma_f32_16x16x32_bf16 v[20:23], v[166:169], v[202:205], v[20:23]
	v_mfma_f32_16x16x32_bf16 v[16:19], v[174:177], v[202:205], v[16:19]
	v_mfma_f32_16x16x32_bf16 v[4:7], v[166:169], v[210:213], v[4:7]
	v_mfma_f32_16x16x32_bf16 v[0:3], v[174:177], v[210:213], v[0:3]
	s_barrier
	s_add_u32 s26, s26, 0x100
	s_addc_u32 s27, s27, 0
	s_add_u32 s56, s56, 0x100
	s_addc_u32 s57, s57, 0
	s_cmp_ge_i32 s58, s41
	s_mov_b32 s4, s58
	s_cbranch_scc0 .LBB0_1552

.LBB0_1652:
	s_andn2_b64 vcc, exec, s[12:13]
	s_cbranch_vccnz .Lpz_zero_6
	s_add_u32 s28, s28, 0x40080
	s_addc_u32 s29, s29, 0
	s_add_u32 s17, s30, 0x100
	s_addc_u32 s19, s31, 0
	s_mov_b32 s30, 0
	ds_read_b128 v[138:141], v147
	ds_read_b128 v[152:155], v147 offset:1024
	ds_read_b128 v[156:159], v147 offset:2048
	ds_read_b128 v[160:163], v147 offset:3072
	ds_read_b128 v[164:167], v148
	ds_read_b128 v[168:171], v148 offset:1024
	ds_read_b128 v[172:175], v148 offset:2048
	ds_read_b128 v[176:179], v148 offset:3072
	s_add_i32 s53, s30, 2
	s_add_u32 s31, s28, 0xfffc0080
	s_addc_u32 s34, s29, -1
	s_cmp_eq_u32 s44, s30
	s_cselect_b32 s30, s22, s17
	s_cselect_b32 s35, s21, s34
	s_cselect_b32 s34, s20, s31
	s_cselect_b32 s31, s23, s19
	v_lshl_add_u64 v[142:143], s[28:29], 0, v[132:133]
	s_add_i32 m0, s27, 0xc000
	ds_read_b128 v[180:183], v149
	ds_read_b128 v[184:187], v149 offset:1024
	ds_read_b128 v[188:191], v149 offset:2048
	ds_read_b128 v[192:195], v149 offset:3072
	ds_read_b128 v[196:199], v149 offset:4096
	ds_read_b128 v[200:203], v149 offset:5120
	ds_read_b128 v[204:207], v149 offset:6144
	ds_read_b128 v[208:211], v149 offset:7168
	global_load_lds_dwordx4 v[142:143], off
	v_lshl_add_u64 v[142:143], s[28:29], 0, v[134:135]
	s_add_i32 m0, s27, 0xe000
	s_nop 0
	global_load_lds_dwordx4 v[142:143], off
	s_waitcnt vmcnt(8)
	s_waitcnt lgkmcnt(0)
	s_barrier
	s_waitcnt lgkmcnt(0)
	v_mfma_f32_16x16x32_bf16 v[124:127], v[138:141], v[180:183], 0
	v_mfma_f32_16x16x32_bf16 v[120:123], v[156:159], v[180:183], 0
	v_mfma_f32_16x16x32_bf16 v[108:111], v[138:141], v[188:191], 0
	v_mfma_f32_16x16x32_bf16 v[104:107], v[156:159], v[188:191], 0
	v_mfma_f32_16x16x32_bf16 v[92:95], v[138:141], v[196:199], 0
	v_mfma_f32_16x16x32_bf16 v[88:91], v[156:159], v[196:199], 0
	v_mfma_f32_16x16x32_bf16 v[76:79], v[138:141], v[204:207], 0
	v_mfma_f32_16x16x32_bf16 v[72:75], v[156:159], v[204:207], 0
	v_mfma_f32_16x16x32_bf16 v[124:127], v[152:155], v[184:187], v[124:127]
	v_mfma_f32_16x16x32_bf16 v[120:123], v[160:163], v[184:187], v[120:123]
	v_mfma_f32_16x16x32_bf16 v[108:111], v[152:155], v[192:195], v[108:111]
	v_mfma_f32_16x16x32_bf16 v[104:107], v[160:163], v[192:195], v[104:107]
	v_mfma_f32_16x16x32_bf16 v[92:95], v[152:155], v[200:203], v[92:95]
	v_mfma_f32_16x16x32_bf16 v[88:91], v[160:163], v[200:203], v[88:91]
	v_mfma_f32_16x16x32_bf16 v[76:79], v[152:155], v[208:211], v[76:79]
	v_mfma_f32_16x16x32_bf16 v[72:75], v[160:163], v[208:211], v[72:75]
	v_mfma_f32_16x16x32_bf16 v[116:119], v[164:167], v[180:183], 0
	v_mfma_f32_16x16x32_bf16 v[112:115], v[172:175], v[180:183], 0
	v_mfma_f32_16x16x32_bf16 v[100:103], v[164:167], v[188:191], 0
	v_mfma_f32_16x16x32_bf16 v[96:99], v[172:175], v[188:191], 0
	v_mfma_f32_16x16x32_bf16 v[84:87], v[164:167], v[196:199], 0
	v_mfma_f32_16x16x32_bf16 v[80:83], v[172:175], v[196:199], 0
	v_mfma_f32_16x16x32_bf16 v[68:71], v[164:167], v[204:207], 0
	v_mfma_f32_16x16x32_bf16 v[64:67], v[172:175], v[204:207], 0
	v_mfma_f32_16x16x32_bf16 v[116:119], v[168:171], v[184:187], v[116:119]
	v_mfma_f32_16x16x32_bf16 v[112:115], v[176:179], v[184:187], v[112:115]
	v_mfma_f32_16x16x32_bf16 v[100:103], v[168:171], v[192:195], v[100:103]
	v_mfma_f32_16x16x32_bf16 v[96:99], v[176:179], v[192:195], v[96:99]
	v_mfma_f32_16x16x32_bf16 v[84:87], v[168:171], v[200:203], v[84:87]
	v_mfma_f32_16x16x32_bf16 v[80:83], v[176:179], v[200:203], v[80:83]
	v_mfma_f32_16x16x32_bf16 v[68:71], v[168:171], v[208:211], v[68:71]
	v_mfma_f32_16x16x32_bf16 v[64:67], v[176:179], v[208:211], v[64:67]
	s_barrier
	s_add_i32 s54, s49, s33
	v_lshl_add_u64 v[142:143], s[30:31], 0, v[128:129]
	s_mov_b32 m0, s54
	ds_read_b128 v[180:183], v149 offset:16384
	ds_read_b128 v[184:187], v149 offset:17408
	ds_read_b128 v[188:191], v149 offset:18432
	ds_read_b128 v[192:195], v149 offset:19456
	ds_read_b128 v[196:199], v149 offset:20480
	ds_read_b128 v[200:203], v149 offset:21504
	ds_read_b128 v[204:207], v149 offset:22528
	ds_read_b128 v[208:211], v149 offset:23552
	global_load_lds_dwordx4 v[142:143], off
	s_add_i32 m0, s54, 0x2000
	s_add_u32 s54, s30, 0x40000
	v_lshl_add_u64 v[212:213], s[30:31], 0, v[130:131]
	s_addc_u32 s55, s31, 0
	s_add_i32 s56, s50, s33
	global_load_lds_dwordx4 v[212:213], off
	v_lshl_add_u64 v[214:215], s[54:55], 0, v[128:129]
	s_mov_b32 m0, s56
	v_lshl_add_u64 v[216:217], s[34:35], 0, v[130:131]
	global_load_lds_dwordx4 v[214:215], off
	v_lshl_add_u64 v[214:215], s[54:55], 0, v[130:131]
	s_add_i32 m0, s56, 0x2000
	s_nop 0
	global_load_lds_dwordx4 v[214:215], off
	v_lshl_add_u64 v[214:215], s[34:35], 0, v[128:129]
	s_mov_b32 m0, s27
	s_nop 0
	global_load_lds_dwordx4 v[214:215], off
	s_mov_b32 m0, s38
	s_nop 0
	global_load_lds_dwordx4 v[216:217], off
	s_waitcnt vmcnt(8)
	s_waitcnt lgkmcnt(0)
	s_barrier
	s_waitcnt lgkmcnt(0)
	v_mfma_f32_16x16x32_bf16 v[60:63], v[138:141], v[180:183], 0
	v_mfma_f32_16x16x32_bf16 v[56:59], v[156:159], v[180:183], 0
	v_mfma_f32_16x16x32_bf16 v[44:47], v[138:141], v[188:191], 0
	v_mfma_f32_16x16x32_bf16 v[40:43], v[156:159], v[188:191], 0
	v_mfma_f32_16x16x32_bf16 v[28:31], v[138:141], v[196:199], 0
	v_mfma_f32_16x16x32_bf16 v[24:27], v[156:159], v[196:199], 0
	v_mfma_f32_16x16x32_bf16 v[12:15], v[138:141], v[204:207], 0
	v_mfma_f32_16x16x32_bf16 v[8:11], v[156:159], v[204:207], 0
	v_mfma_f32_16x16x32_bf16 v[60:63], v[152:155], v[184:187], v[60:63]
	v_mfma_f32_16x16x32_bf16 v[56:59], v[160:163], v[184:187], v[56:59]
	v_mfma_f32_16x16x32_bf16 v[44:47], v[152:155], v[192:195], v[44:47]
	v_mfma_f32_16x16x32_bf16 v[40:43], v[160:163], v[192:195], v[40:43]
	v_mfma_f32_16x16x32_bf16 v[28:31], v[152:155], v[200:203], v[28:31]
	v_mfma_f32_16x16x32_bf16 v[24:27], v[160:163], v[200:203], v[24:27]
	v_mfma_f32_16x16x32_bf16 v[12:15], v[152:155], v[208:211], v[12:15]
	v_mfma_f32_16x16x32_bf16 v[8:11], v[160:163], v[208:211], v[8:11]
	v_mfma_f32_16x16x32_bf16 v[52:55], v[164:167], v[180:183], 0
	v_mfma_f32_16x16x32_bf16 v[48:51], v[172:175], v[180:183], 0
	v_mfma_f32_16x16x32_bf16 v[36:39], v[164:167], v[188:191], 0
	v_mfma_f32_16x16x32_bf16 v[32:35], v[172:175], v[188:191], 0
	v_mfma_f32_16x16x32_bf16 v[20:23], v[164:167], v[196:199], 0
	v_mfma_f32_16x16x32_bf16 v[16:19], v[172:175], v[196:199], 0
	v_mfma_f32_16x16x32_bf16 v[4:7], v[164:167], v[204:207], 0
	v_mfma_f32_16x16x32_bf16 v[0:3], v[172:175], v[204:207], 0
	v_mfma_f32_16x16x32_bf16 v[52:55], v[168:171], v[184:187], v[52:55]
	v_mfma_f32_16x16x32_bf16 v[48:51], v[176:179], v[184:187], v[48:51]
	v_mfma_f32_16x16x32_bf16 v[36:39], v[168:171], v[192:195], v[36:39]
	v_mfma_f32_16x16x32_bf16 v[32:35], v[176:179], v[192:195], v[32:35]
	v_mfma_f32_16x16x32_bf16 v[20:23], v[168:171], v[200:203], v[20:23]
	v_mfma_f32_16x16x32_bf16 v[16:19], v[176:179], v[200:203], v[16:19]
	v_mfma_f32_16x16x32_bf16 v[4:7], v[168:171], v[208:211], v[4:7]
	v_mfma_f32_16x16x32_bf16 v[0:3], v[176:179], v[208:211], v[0:3]
	s_barrier
	s_add_i32 s54, 0, 0x18000
	v_add_u32_e32 v151, s54, v145
	s_add_i32 s55, 0, 0x1c000
	ds_read_b128 v[138:141], v151
	ds_read_b128 v[152:155], v151 offset:1024
	ds_read_b128 v[156:159], v151 offset:2048
	ds_read_b128 v[160:163], v151 offset:3072
	v_add_u32_e32 v151, s55, v145
	ds_read_b128 v[164:167], v151
	ds_read_b128 v[168:171], v151 offset:1024
	ds_read_b128 v[172:175], v151 offset:2048
	ds_read_b128 v[176:179], v151 offset:3072
	s_add_u32 s34, s34, 0x40000
	s_addc_u32 s35, s35, 0
	s_mov_b32 m0, s39
	v_lshl_add_u64 v[218:219], s[34:35], 0, v[128:129]
	ds_read_b128 v[180:183], v149 offset:32768
	ds_read_b128 v[184:187], v149 offset:33792
	ds_read_b128 v[188:191], v149 offset:34816
	ds_read_b128 v[192:195], v149 offset:35840
	ds_read_b128 v[196:199], v149 offset:36864
	ds_read_b128 v[200:203], v149 offset:37888
	ds_read_b128 v[204:207], v149 offset:38912
	ds_read_b128 v[208:211], v149 offset:39936
	global_load_lds_dwordx4 v[218:219], off
	v_lshl_add_u64 v[218:219], s[34:35], 0, v[130:131]
	s_mov_b32 m0, s40
	s_nop 0
	global_load_lds_dwordx4 v[218:219], off
	s_waitcnt vmcnt(8)
	s_waitcnt lgkmcnt(0)
	s_barrier
	s_waitcnt lgkmcnt(0)
	v_mfma_f32_16x16x32_bf16 v[124:127], v[138:141], v[180:183], v[124:127]
	v_mfma_f32_16x16x32_bf16 v[120:123], v[156:159], v[180:183], v[120:123]
	v_mfma_f32_16x16x32_bf16 v[108:111], v[138:141], v[188:191], v[108:111]
	v_mfma_f32_16x16x32_bf16 v[104:107], v[156:159], v[188:191], v[104:107]
	v_mfma_f32_16x16x32_bf16 v[92:95], v[138:141], v[196:199], v[92:95]
	v_mfma_f32_16x16x32_bf16 v[88:91], v[156:159], v[196:199], v[88:91]
	v_mfma_f32_16x16x32_bf16 v[76:79], v[138:141], v[204:207], v[76:79]
	v_mfma_f32_16x16x32_bf16 v[72:75], v[156:159], v[204:207], v[72:75]
	v_mfma_f32_16x16x32_bf16 v[124:127], v[152:155], v[184:187], v[124:127]
	v_mfma_f32_16x16x32_bf16 v[120:123], v[160:163], v[184:187], v[120:123]
	v_mfma_f32_16x16x32_bf16 v[108:111], v[152:155], v[192:195], v[108:111]
	v_mfma_f32_16x16x32_bf16 v[104:107], v[160:163], v[192:195], v[104:107]
	v_mfma_f32_16x16x32_bf16 v[92:95], v[152:155], v[200:203], v[92:95]
	v_mfma_f32_16x16x32_bf16 v[88:91], v[160:163], v[200:203], v[88:91]
	v_mfma_f32_16x16x32_bf16 v[76:79], v[152:155], v[208:211], v[76:79]
	v_mfma_f32_16x16x32_bf16 v[72:75], v[160:163], v[208:211], v[72:75]
	v_mfma_f32_16x16x32_bf16 v[116:119], v[164:167], v[180:183], v[116:119]
	v_mfma_f32_16x16x32_bf16 v[112:115], v[172:175], v[180:183], v[112:115]
	v_mfma_f32_16x16x32_bf16 v[100:103], v[164:167], v[188:191], v[100:103]
	v_mfma_f32_16x16x32_bf16 v[96:99], v[172:175], v[188:191], v[96:99]
	v_mfma_f32_16x16x32_bf16 v[84:87], v[164:167], v[196:199], v[84:87]
	v_mfma_f32_16x16x32_bf16 v[80:83], v[172:175], v[196:199], v[80:83]
	v_mfma_f32_16x16x32_bf16 v[68:71], v[164:167], v[204:207], v[68:71]
	v_mfma_f32_16x16x32_bf16 v[64:67], v[172:175], v[204:207], v[64:67]
	v_mfma_f32_16x16x32_bf16 v[116:119], v[168:171], v[184:187], v[116:119]
	v_mfma_f32_16x16x32_bf16 v[112:115], v[176:179], v[184:187], v[112:115]
	v_mfma_f32_16x16x32_bf16 v[100:103], v[168:171], v[192:195], v[100:103]
	v_mfma_f32_16x16x32_bf16 v[96:99], v[176:179], v[192:195], v[96:99]
	v_mfma_f32_16x16x32_bf16 v[84:87], v[168:171], v[200:203], v[84:87]
	v_mfma_f32_16x16x32_bf16 v[80:83], v[176:179], v[200:203], v[80:83]
	v_mfma_f32_16x16x32_bf16 v[68:71], v[168:171], v[208:211], v[68:71]
	v_mfma_f32_16x16x32_bf16 v[64:67], v[176:179], v[208:211], v[64:67]
	s_barrier
	s_add_i32 s34, s54, s33
	v_lshl_add_u64 v[142:143], v[142:143], 0, s[10:11]
	s_mov_b32 m0, s34
	ds_read_b128 v[180:183], v149 offset:49152
	ds_read_b128 v[184:187], v149 offset:50176
	ds_read_b128 v[188:191], v149 offset:51200
	ds_read_b128 v[192:195], v149 offset:52224
	ds_read_b128 v[196:199], v149 offset:53248
	ds_read_b128 v[200:203], v149 offset:54272
	ds_read_b128 v[204:207], v149 offset:55296
	ds_read_b128 v[208:211], v149 offset:56320
	global_load_lds_dwordx4 v[142:143], off
	s_add_i32 m0, s34, 0x2000
	s_add_u32 s30, s30, 0x40080
	v_lshl_add_u64 v[142:143], v[212:213], 0, s[10:11]
	s_addc_u32 s31, s31, 0
	s_add_i32 s34, s55, s33
	global_load_lds_dwordx4 v[142:143], off
	v_lshl_add_u64 v[142:143], s[30:31], 0, v[128:129]
	s_mov_b32 m0, s34
	s_nop 0
	global_load_lds_dwordx4 v[142:143], off
	v_lshl_add_u64 v[142:143], s[30:31], 0, v[130:131]
	s_add_i32 m0, s34, 0x2000
	s_nop 0
	global_load_lds_dwordx4 v[142:143], off
	v_lshl_add_u64 v[142:143], v[214:215], 0, s[10:11]
	s_mov_b32 m0, s42
	s_nop 0
	global_load_lds_dwordx4 v[142:143], off
	v_lshl_add_u64 v[142:143], v[216:217], 0, s[10:11]
	s_mov_b32 m0, s43
	s_nop 0
	global_load_lds_dwordx4 v[142:143], off
	s_waitcnt vmcnt(8)
	s_waitcnt lgkmcnt(0)
	s_barrier
	s_waitcnt lgkmcnt(0)
	v_mfma_f32_16x16x32_bf16 v[60:63], v[138:141], v[180:183], v[60:63]
	v_mfma_f32_16x16x32_bf16 v[56:59], v[156:159], v[180:183], v[56:59]
	v_mfma_f32_16x16x32_bf16 v[44:47], v[138:141], v[188:191], v[44:47]
	v_mfma_f32_16x16x32_bf16 v[40:43], v[156:159], v[188:191], v[40:43]
	v_mfma_f32_16x16x32_bf16 v[28:31], v[138:141], v[196:199], v[28:31]
	v_mfma_f32_16x16x32_bf16 v[24:27], v[156:159], v[196:199], v[24:27]
	v_mfma_f32_16x16x32_bf16 v[12:15], v[138:141], v[204:207], v[12:15]
	v_mfma_f32_16x16x32_bf16 v[8:11], v[156:159], v[204:207], v[8:11]
	v_mfma_f32_16x16x32_bf16 v[60:63], v[152:155], v[184:187], v[60:63]
	v_mfma_f32_16x16x32_bf16 v[56:59], v[160:163], v[184:187], v[56:59]
	v_mfma_f32_16x16x32_bf16 v[44:47], v[152:155], v[192:195], v[44:47]
	v_mfma_f32_16x16x32_bf16 v[40:43], v[160:163], v[192:195], v[40:43]
	v_mfma_f32_16x16x32_bf16 v[28:31], v[152:155], v[200:203], v[28:31]
	v_mfma_f32_16x16x32_bf16 v[24:27], v[160:163], v[200:203], v[24:27]
	v_mfma_f32_16x16x32_bf16 v[12:15], v[152:155], v[208:211], v[12:15]
	v_mfma_f32_16x16x32_bf16 v[8:11], v[160:163], v[208:211], v[8:11]
	v_mfma_f32_16x16x32_bf16 v[52:55], v[164:167], v[180:183], v[52:55]
	v_mfma_f32_16x16x32_bf16 v[48:51], v[172:175], v[180:183], v[48:51]
	v_mfma_f32_16x16x32_bf16 v[36:39], v[164:167], v[188:191], v[36:39]
	v_mfma_f32_16x16x32_bf16 v[32:35], v[172:175], v[188:191], v[32:35]
	v_mfma_f32_16x16x32_bf16 v[20:23], v[164:167], v[196:199], v[20:23]
	v_mfma_f32_16x16x32_bf16 v[16:19], v[172:175], v[196:199], v[16:19]
	v_mfma_f32_16x16x32_bf16 v[4:7], v[164:167], v[204:207], v[4:7]
	v_mfma_f32_16x16x32_bf16 v[0:3], v[172:175], v[204:207], v[0:3]
	v_mfma_f32_16x16x32_bf16 v[52:55], v[168:171], v[184:187], v[52:55]
	v_mfma_f32_16x16x32_bf16 v[48:51], v[176:179], v[184:187], v[48:51]
	v_mfma_f32_16x16x32_bf16 v[36:39], v[168:171], v[192:195], v[36:39]
	v_mfma_f32_16x16x32_bf16 v[32:35], v[176:179], v[192:195], v[32:35]
	v_mfma_f32_16x16x32_bf16 v[20:23], v[168:171], v[200:203], v[20:23]
	v_mfma_f32_16x16x32_bf16 v[16:19], v[176:179], v[200:203], v[16:19]
	v_mfma_f32_16x16x32_bf16 v[4:7], v[168:171], v[208:211], v[4:7]
	v_mfma_f32_16x16x32_bf16 v[0:3], v[176:179], v[208:211], v[0:3]
	s_barrier
	s_add_u32 s28, s28, 0x100
	s_addc_u32 s29, s29, 0
	s_add_u32 s17, s17, 0x100
	s_addc_u32 s19, s19, 0
	s_cmp_ge_i32 s53, s41
	s_mov_b32 s30, s53
	s_cbranch_scc0 .LBB0_1654
	s_branch .LBB0_1655

.LBB0_1654:
	ds_read_b128 v[138:141], v147
	ds_read_b128 v[152:155], v147 offset:1024
	ds_read_b128 v[156:159], v147 offset:2048
	ds_read_b128 v[160:163], v147 offset:3072
	ds_read_b128 v[164:167], v148
	ds_read_b128 v[168:171], v148 offset:1024
	ds_read_b128 v[172:175], v148 offset:2048
	ds_read_b128 v[176:179], v148 offset:3072
	s_add_i32 s53, s30, 2
	s_add_u32 s31, s28, 0xfffc0080
	s_addc_u32 s34, s29, -1
	s_cmp_eq_u32 s44, s30
	s_cselect_b32 s30, s22, s17
	s_cselect_b32 s35, s21, s34
	s_cselect_b32 s34, s20, s31
	s_cselect_b32 s31, s23, s19
	v_lshl_add_u64 v[142:143], s[28:29], 0, v[132:133]
	s_add_i32 m0, s27, 0xc000
	ds_read_b128 v[180:183], v149
	ds_read_b128 v[184:187], v149 offset:1024
	ds_read_b128 v[188:191], v149 offset:2048
	ds_read_b128 v[192:195], v149 offset:3072
	ds_read_b128 v[196:199], v149 offset:4096
	ds_read_b128 v[200:203], v149 offset:5120
	ds_read_b128 v[204:207], v149 offset:6144
	ds_read_b128 v[208:211], v149 offset:7168
	global_load_lds_dwordx4 v[142:143], off
	v_lshl_add_u64 v[142:143], s[28:29], 0, v[134:135]
	s_add_i32 m0, s27, 0xe000
	s_nop 0
	global_load_lds_dwordx4 v[142:143], off
	s_waitcnt vmcnt(8)
	s_waitcnt lgkmcnt(0)
	s_barrier
	s_waitcnt lgkmcnt(0)
	v_mfma_f32_16x16x32_bf16 v[124:127], v[138:141], v[180:183], v[124:127]
	v_mfma_f32_16x16x32_bf16 v[120:123], v[156:159], v[180:183], v[120:123]
	v_mfma_f32_16x16x32_bf16 v[108:111], v[138:141], v[188:191], v[108:111]
	v_mfma_f32_16x16x32_bf16 v[104:107], v[156:159], v[188:191], v[104:107]
	v_mfma_f32_16x16x32_bf16 v[92:95], v[138:141], v[196:199], v[92:95]
	v_mfma_f32_16x16x32_bf16 v[88:91], v[156:159], v[196:199], v[88:91]
	v_mfma_f32_16x16x32_bf16 v[76:79], v[138:141], v[204:207], v[76:79]
	v_mfma_f32_16x16x32_bf16 v[72:75], v[156:159], v[204:207], v[72:75]
	v_mfma_f32_16x16x32_bf16 v[124:127], v[152:155], v[184:187], v[124:127]
	v_mfma_f32_16x16x32_bf16 v[120:123], v[160:163], v[184:187], v[120:123]
	v_mfma_f32_16x16x32_bf16 v[108:111], v[152:155], v[192:195], v[108:111]
	v_mfma_f32_16x16x32_bf16 v[104:107], v[160:163], v[192:195], v[104:107]
	v_mfma_f32_16x16x32_bf16 v[92:95], v[152:155], v[200:203], v[92:95]
	v_mfma_f32_16x16x32_bf16 v[88:91], v[160:163], v[200:203], v[88:91]
	v_mfma_f32_16x16x32_bf16 v[76:79], v[152:155], v[208:211], v[76:79]
	v_mfma_f32_16x16x32_bf16 v[72:75], v[160:163], v[208:211], v[72:75]
	v_mfma_f32_16x16x32_bf16 v[116:119], v[164:167], v[180:183], v[116:119]
	v_mfma_f32_16x16x32_bf16 v[112:115], v[172:175], v[180:183], v[112:115]
	v_mfma_f32_16x16x32_bf16 v[100:103], v[164:167], v[188:191], v[100:103]
	v_mfma_f32_16x16x32_bf16 v[96:99], v[172:175], v[188:191], v[96:99]
	v_mfma_f32_16x16x32_bf16 v[84:87], v[164:167], v[196:199], v[84:87]
	v_mfma_f32_16x16x32_bf16 v[80:83], v[172:175], v[196:199], v[80:83]
	v_mfma_f32_16x16x32_bf16 v[68:71], v[164:167], v[204:207], v[68:71]
	v_mfma_f32_16x16x32_bf16 v[64:67], v[172:175], v[204:207], v[64:67]
	v_mfma_f32_16x16x32_bf16 v[116:119], v[168:171], v[184:187], v[116:119]
	v_mfma_f32_16x16x32_bf16 v[112:115], v[176:179], v[184:187], v[112:115]
	v_mfma_f32_16x16x32_bf16 v[100:103], v[168:171], v[192:195], v[100:103]
	v_mfma_f32_16x16x32_bf16 v[96:99], v[176:179], v[192:195], v[96:99]
	v_mfma_f32_16x16x32_bf16 v[84:87], v[168:171], v[200:203], v[84:87]
	v_mfma_f32_16x16x32_bf16 v[80:83], v[176:179], v[200:203], v[80:83]
	v_mfma_f32_16x16x32_bf16 v[68:71], v[168:171], v[208:211], v[68:71]
	v_mfma_f32_16x16x32_bf16 v[64:67], v[176:179], v[208:211], v[64:67]
	s_barrier
	s_add_i32 s54, s49, s33
	v_lshl_add_u64 v[142:143], s[30:31], 0, v[128:129]
	s_mov_b32 m0, s54
	ds_read_b128 v[180:183], v149 offset:16384
	ds_read_b128 v[184:187], v149 offset:17408
	ds_read_b128 v[188:191], v149 offset:18432
	ds_read_b128 v[192:195], v149 offset:19456
	ds_read_b128 v[196:199], v149 offset:20480
	ds_read_b128 v[200:203], v149 offset:21504
	ds_read_b128 v[204:207], v149 offset:22528
	ds_read_b128 v[208:211], v149 offset:23552
	global_load_lds_dwordx4 v[142:143], off
	s_add_i32 m0, s54, 0x2000
	s_add_u32 s54, s30, 0x40000
	v_lshl_add_u64 v[212:213], s[30:31], 0, v[130:131]
	s_addc_u32 s55, s31, 0
	s_add_i32 s56, s50, s33
	global_load_lds_dwordx4 v[212:213], off
	v_lshl_add_u64 v[214:215], s[54:55], 0, v[128:129]
	s_mov_b32 m0, s56
	v_lshl_add_u64 v[216:217], s[34:35], 0, v[130:131]
	global_load_lds_dwordx4 v[214:215], off
	v_lshl_add_u64 v[214:215], s[54:55], 0, v[130:131]
	s_add_i32 m0, s56, 0x2000
	s_nop 0
	global_load_lds_dwordx4 v[214:215], off
	v_lshl_add_u64 v[214:215], s[34:35], 0, v[128:129]
	s_mov_b32 m0, s27
	s_nop 0
	global_load_lds_dwordx4 v[214:215], off
	s_mov_b32 m0, s38
	s_nop 0
	global_load_lds_dwordx4 v[216:217], off
	s_waitcnt vmcnt(8)
	s_waitcnt lgkmcnt(0)
	s_barrier
	s_waitcnt lgkmcnt(0)
	v_mfma_f32_16x16x32_bf16 v[60:63], v[138:141], v[180:183], v[60:63]
	v_mfma_f32_16x16x32_bf16 v[56:59], v[156:159], v[180:183], v[56:59]
	v_mfma_f32_16x16x32_bf16 v[44:47], v[138:141], v[188:191], v[44:47]
	v_mfma_f32_16x16x32_bf16 v[40:43], v[156:159], v[188:191], v[40:43]
	v_mfma_f32_16x16x32_bf16 v[28:31], v[138:141], v[196:199], v[28:31]
	v_mfma_f32_16x16x32_bf16 v[24:27], v[156:159], v[196:199], v[24:27]
	v_mfma_f32_16x16x32_bf16 v[12:15], v[138:141], v[204:207], v[12:15]
	v_mfma_f32_16x16x32_bf16 v[8:11], v[156:159], v[204:207], v[8:11]
	v_mfma_f32_16x16x32_bf16 v[60:63], v[152:155], v[184:187], v[60:63]
	v_mfma_f32_16x16x32_bf16 v[56:59], v[160:163], v[184:187], v[56:59]
	v_mfma_f32_16x16x32_bf16 v[44:47], v[152:155], v[192:195], v[44:47]
	v_mfma_f32_16x16x32_bf16 v[40:43], v[160:163], v[192:195], v[40:43]
	v_mfma_f32_16x16x32_bf16 v[28:31], v[152:155], v[200:203], v[28:31]
	v_mfma_f32_16x16x32_bf16 v[24:27], v[160:163], v[200:203], v[24:27]
	v_mfma_f32_16x16x32_bf16 v[12:15], v[152:155], v[208:211], v[12:15]
	v_mfma_f32_16x16x32_bf16 v[8:11], v[160:163], v[208:211], v[8:11]
	v_mfma_f32_16x16x32_bf16 v[52:55], v[164:167], v[180:183], v[52:55]
	v_mfma_f32_16x16x32_bf16 v[48:51], v[172:175], v[180:183], v[48:51]
	v_mfma_f32_16x16x32_bf16 v[36:39], v[164:167], v[188:191], v[36:39]
	v_mfma_f32_16x16x32_bf16 v[32:35], v[172:175], v[188:191], v[32:35]
	v_mfma_f32_16x16x32_bf16 v[20:23], v[164:167], v[196:199], v[20:23]
	v_mfma_f32_16x16x32_bf16 v[16:19], v[172:175], v[196:199], v[16:19]
	v_mfma_f32_16x16x32_bf16 v[4:7], v[164:167], v[204:207], v[4:7]
	v_mfma_f32_16x16x32_bf16 v[0:3], v[172:175], v[204:207], v[0:3]
	v_mfma_f32_16x16x32_bf16 v[52:55], v[168:171], v[184:187], v[52:55]
	v_mfma_f32_16x16x32_bf16 v[48:51], v[176:179], v[184:187], v[48:51]
	v_mfma_f32_16x16x32_bf16 v[36:39], v[168:171], v[192:195], v[36:39]
	v_mfma_f32_16x16x32_bf16 v[32:35], v[176:179], v[192:195], v[32:35]
	v_mfma_f32_16x16x32_bf16 v[20:23], v[168:171], v[200:203], v[20:23]
	v_mfma_f32_16x16x32_bf16 v[16:19], v[176:179], v[200:203], v[16:19]
	v_mfma_f32_16x16x32_bf16 v[4:7], v[168:171], v[208:211], v[4:7]
	v_mfma_f32_16x16x32_bf16 v[0:3], v[176:179], v[208:211], v[0:3]
	s_barrier
	s_add_i32 s54, 0, 0x18000
	v_add_u32_e32 v151, s54, v145
	s_add_i32 s55, 0, 0x1c000
	ds_read_b128 v[138:141], v151
	ds_read_b128 v[152:155], v151 offset:1024
	ds_read_b128 v[156:159], v151 offset:2048
	ds_read_b128 v[160:163], v151 offset:3072
	v_add_u32_e32 v151, s55, v145
	ds_read_b128 v[164:167], v151
	ds_read_b128 v[168:171], v151 offset:1024
	ds_read_b128 v[172:175], v151 offset:2048
	ds_read_b128 v[176:179], v151 offset:3072
	s_add_u32 s34, s34, 0x40000
	s_addc_u32 s35, s35, 0
	s_mov_b32 m0, s39
	v_lshl_add_u64 v[218:219], s[34:35], 0, v[128:129]
	ds_read_b128 v[180:183], v149 offset:32768
	ds_read_b128 v[184:187], v149 offset:33792
	ds_read_b128 v[188:191], v149 offset:34816
	ds_read_b128 v[192:195], v149 offset:35840
	ds_read_b128 v[196:199], v149 offset:36864
	ds_read_b128 v[200:203], v149 offset:37888
	ds_read_b128 v[204:207], v149 offset:38912
	ds_read_b128 v[208:211], v149 offset:39936
	global_load_lds_dwordx4 v[218:219], off
	v_lshl_add_u64 v[218:219], s[34:35], 0, v[130:131]
	s_mov_b32 m0, s40
	s_nop 0
	global_load_lds_dwordx4 v[218:219], off
	s_waitcnt vmcnt(8)
	s_waitcnt lgkmcnt(0)
	s_barrier
	s_waitcnt lgkmcnt(0)
	v_mfma_f32_16x16x32_bf16 v[124:127], v[138:141], v[180:183], v[124:127]
	v_mfma_f32_16x16x32_bf16 v[120:123], v[156:159], v[180:183], v[120:123]
	v_mfma_f32_16x16x32_bf16 v[108:111], v[138:141], v[188:191], v[108:111]
	v_mfma_f32_16x16x32_bf16 v[104:107], v[156:159], v[188:191], v[104:107]
	v_mfma_f32_16x16x32_bf16 v[92:95], v[138:141], v[196:199], v[92:95]
	v_mfma_f32_16x16x32_bf16 v[88:91], v[156:159], v[196:199], v[88:91]
	v_mfma_f32_16x16x32_bf16 v[76:79], v[138:141], v[204:207], v[76:79]
	v_mfma_f32_16x16x32_bf16 v[72:75], v[156:159], v[204:207], v[72:75]
	v_mfma_f32_16x16x32_bf16 v[124:127], v[152:155], v[184:187], v[124:127]
	v_mfma_f32_16x16x32_bf16 v[120:123], v[160:163], v[184:187], v[120:123]
	v_mfma_f32_16x16x32_bf16 v[108:111], v[152:155], v[192:195], v[108:111]
	v_mfma_f32_16x16x32_bf16 v[104:107], v[160:163], v[192:195], v[104:107]
	v_mfma_f32_16x16x32_bf16 v[92:95], v[152:155], v[200:203], v[92:95]
	v_mfma_f32_16x16x32_bf16 v[88:91], v[160:163], v[200:203], v[88:91]
	v_mfma_f32_16x16x32_bf16 v[76:79], v[152:155], v[208:211], v[76:79]
	v_mfma_f32_16x16x32_bf16 v[72:75], v[160:163], v[208:211], v[72:75]
	v_mfma_f32_16x16x32_bf16 v[116:119], v[164:167], v[180:183], v[116:119]
	v_mfma_f32_16x16x32_bf16 v[112:115], v[172:175], v[180:183], v[112:115]
	v_mfma_f32_16x16x32_bf16 v[100:103], v[164:167], v[188:191], v[100:103]
	v_mfma_f32_16x16x32_bf16 v[96:99], v[172:175], v[188:191], v[96:99]
	v_mfma_f32_16x16x32_bf16 v[84:87], v[164:167], v[196:199], v[84:87]
	v_mfma_f32_16x16x32_bf16 v[80:83], v[172:175], v[196:199], v[80:83]
	v_mfma_f32_16x16x32_bf16 v[68:71], v[164:167], v[204:207], v[68:71]
	v_mfma_f32_16x16x32_bf16 v[64:67], v[172:175], v[204:207], v[64:67]
	v_mfma_f32_16x16x32_bf16 v[116:119], v[168:171], v[184:187], v[116:119]
	v_mfma_f32_16x16x32_bf16 v[112:115], v[176:179], v[184:187], v[112:115]
	v_mfma_f32_16x16x32_bf16 v[100:103], v[168:171], v[192:195], v[100:103]
	v_mfma_f32_16x16x32_bf16 v[96:99], v[176:179], v[192:195], v[96:99]
	v_mfma_f32_16x16x32_bf16 v[84:87], v[168:171], v[200:203], v[84:87]
	v_mfma_f32_16x16x32_bf16 v[80:83], v[176:179], v[200:203], v[80:83]
	v_mfma_f32_16x16x32_bf16 v[68:71], v[168:171], v[208:211], v[68:71]
	v_mfma_f32_16x16x32_bf16 v[64:67], v[176:179], v[208:211], v[64:67]
	s_barrier
	s_add_i32 s34, s54, s33
	v_lshl_add_u64 v[142:143], v[142:143], 0, s[10:11]
	s_mov_b32 m0, s34
	ds_read_b128 v[180:183], v149 offset:49152
	ds_read_b128 v[184:187], v149 offset:50176
	ds_read_b128 v[188:191], v149 offset:51200
	ds_read_b128 v[192:195], v149 offset:52224
	ds_read_b128 v[196:199], v149 offset:53248
	ds_read_b128 v[200:203], v149 offset:54272
	ds_read_b128 v[204:207], v149 offset:55296
	ds_read_b128 v[208:211], v149 offset:56320
	global_load_lds_dwordx4 v[142:143], off
	s_add_i32 m0, s34, 0x2000
	s_add_u32 s30, s30, 0x40080
	v_lshl_add_u64 v[142:143], v[212:213], 0, s[10:11]
	s_addc_u32 s31, s31, 0
	s_add_i32 s34, s55, s33
	global_load_lds_dwordx4 v[142:143], off
	v_lshl_add_u64 v[142:143], s[30:31], 0, v[128:129]
	s_mov_b32 m0, s34
	s_nop 0
	global_load_lds_dwordx4 v[142:143], off
	v_lshl_add_u64 v[142:143], s[30:31], 0, v[130:131]
	s_add_i32 m0, s34, 0x2000
	s_nop 0
	global_load_lds_dwordx4 v[142:143], off
	v_lshl_add_u64 v[142:143], v[214:215], 0, s[10:11]
	s_mov_b32 m0, s42
	s_nop 0
	global_load_lds_dwordx4 v[142:143], off
	v_lshl_add_u64 v[142:143], v[216:217], 0, s[10:11]
	s_mov_b32 m0, s43
	s_nop 0
	global_load_lds_dwordx4 v[142:143], off
	s_waitcnt vmcnt(8)
	s_waitcnt lgkmcnt(0)
	s_barrier
	s_waitcnt lgkmcnt(0)
	v_mfma_f32_16x16x32_bf16 v[60:63], v[138:141], v[180:183], v[60:63]
	v_mfma_f32_16x16x32_bf16 v[56:59], v[156:159], v[180:183], v[56:59]
	v_mfma_f32_16x16x32_bf16 v[44:47], v[138:141], v[188:191], v[44:47]
	v_mfma_f32_16x16x32_bf16 v[40:43], v[156:159], v[188:191], v[40:43]
	v_mfma_f32_16x16x32_bf16 v[28:31], v[138:141], v[196:199], v[28:31]
	v_mfma_f32_16x16x32_bf16 v[24:27], v[156:159], v[196:199], v[24:27]
	v_mfma_f32_16x16x32_bf16 v[12:15], v[138:141], v[204:207], v[12:15]
	v_mfma_f32_16x16x32_bf16 v[8:11], v[156:159], v[204:207], v[8:11]
	v_mfma_f32_16x16x32_bf16 v[60:63], v[152:155], v[184:187], v[60:63]
	v_mfma_f32_16x16x32_bf16 v[56:59], v[160:163], v[184:187], v[56:59]
	v_mfma_f32_16x16x32_bf16 v[44:47], v[152:155], v[192:195], v[44:47]
	v_mfma_f32_16x16x32_bf16 v[40:43], v[160:163], v[192:195], v[40:43]
	v_mfma_f32_16x16x32_bf16 v[28:31], v[152:155], v[200:203], v[28:31]
	v_mfma_f32_16x16x32_bf16 v[24:27], v[160:163], v[200:203], v[24:27]
	v_mfma_f32_16x16x32_bf16 v[12:15], v[152:155], v[208:211], v[12:15]
	v_mfma_f32_16x16x32_bf16 v[8:11], v[160:163], v[208:211], v[8:11]
	v_mfma_f32_16x16x32_bf16 v[52:55], v[164:167], v[180:183], v[52:55]
	v_mfma_f32_16x16x32_bf16 v[48:51], v[172:175], v[180:183], v[48:51]
	v_mfma_f32_16x16x32_bf16 v[36:39], v[164:167], v[188:191], v[36:39]
	v_mfma_f32_16x16x32_bf16 v[32:35], v[172:175], v[188:191], v[32:35]
	v_mfma_f32_16x16x32_bf16 v[20:23], v[164:167], v[196:199], v[20:23]
	v_mfma_f32_16x16x32_bf16 v[16:19], v[172:175], v[196:199], v[16:19]
	v_mfma_f32_16x16x32_bf16 v[4:7], v[164:167], v[204:207], v[4:7]
	v_mfma_f32_16x16x32_bf16 v[0:3], v[172:175], v[204:207], v[0:3]
	v_mfma_f32_16x16x32_bf16 v[52:55], v[168:171], v[184:187], v[52:55]
	v_mfma_f32_16x16x32_bf16 v[48:51], v[176:179], v[184:187], v[48:51]
	v_mfma_f32_16x16x32_bf16 v[36:39], v[168:171], v[192:195], v[36:39]
	v_mfma_f32_16x16x32_bf16 v[32:35], v[176:179], v[192:195], v[32:35]
	v_mfma_f32_16x16x32_bf16 v[20:23], v[168:171], v[200:203], v[20:23]
	v_mfma_f32_16x16x32_bf16 v[16:19], v[176:179], v[200:203], v[16:19]
	v_mfma_f32_16x16x32_bf16 v[4:7], v[168:171], v[208:211], v[4:7]
	v_mfma_f32_16x16x32_bf16 v[0:3], v[176:179], v[208:211], v[0:3]
	s_barrier
	s_add_u32 s28, s28, 0x100
	s_addc_u32 s29, s29, 0
	s_add_u32 s17, s17, 0x100
	s_addc_u32 s19, s19, 0
	s_cmp_ge_i32 s53, s41
	s_mov_b32 s30, s53
	s_cbranch_scc0 .LBB0_1654
